# GEMM K-loops: hipcc's per-phase s_setprio 1/0 flips (224) deleted; timing-only change
# speedup vs baseline: 1.0036x; 1.0036x over previous
.LBB0_103:
	s_add_u32 s8, s4, 0xfffc0080
	s_addc_u32 s9, s5, -1
	s_add_i32 s20, 0, 0x10000
	s_cmp_eq_u32 s88, 12
	s_cselect_b32 s55, s51, s9
	s_cselect_b32 s54, s50, s8
	v_add_u32_e32 v150, s20, v154
	s_cselect_b32 s9, s7, s87
	s_cselect_b32 s8, s49, s57
	s_add_i32 s37, 0, 0x14000
	ds_read_b128 v[142:145], v150
	ds_read_b128 v[146:149], v150 offset:1024
	ds_read_b128 v[156:159], v150 offset:2048
	ds_read_b128 v[160:163], v150 offset:3072
	v_add_u32_e32 v150, s37, v154
	ds_read_b128 v[164:167], v150
	ds_read_b128 v[168:171], v150 offset:1024
	ds_read_b128 v[172:175], v150 offset:2048
	ds_read_b128 v[202:205], v150 offset:3072
	v_lshl_add_u64 v[150:151], s[4:5], 0, v[136:137]
	s_add_i32 m0, s62, 0xc000
	ds_read_b128 v[206:209], v155
	ds_read_b128 v[222:225], v155 offset:1024
	ds_read_b128 v[226:229], v155 offset:2048
	ds_read_b128 v[230:233], v155 offset:3072
	ds_read_b128 v[234:237], v155 offset:4096
	ds_read_b128 v[238:241], v155 offset:5120
	ds_read_b128 v[242:245], v155 offset:6144
	ds_read_b128 v[246:249], v155 offset:7168
	global_load_lds_dwordx4 v[150:151], off
	v_lshl_add_u64 v[150:151], s[4:5], 0, v[138:139]
	s_add_i32 m0, s62, 0xe000
	s_nop 0
	global_load_lds_dwordx4 v[150:151], off
	s_waitcnt vmcnt(8)
	s_waitcnt lgkmcnt(0)
	s_barrier
	s_waitcnt lgkmcnt(0)
	v_mfma_f32_16x16x32_bf16 v[126:129], v[142:145], v[206:209], v[126:129]
	v_mfma_f32_16x16x32_bf16 v[122:125], v[156:159], v[206:209], v[122:125]
	v_mfma_f32_16x16x32_bf16 v[110:113], v[142:145], v[226:229], v[110:113]
	v_mfma_f32_16x16x32_bf16 v[106:109], v[156:159], v[226:229], v[106:109]
	v_mfma_f32_16x16x32_bf16 v[94:97], v[142:145], v[234:237], v[94:97]
	v_mfma_f32_16x16x32_bf16 v[90:93], v[156:159], v[234:237], v[90:93]
	v_mfma_f32_16x16x32_bf16 v[78:81], v[142:145], v[242:245], v[78:81]
	v_mfma_f32_16x16x32_bf16 v[74:77], v[156:159], v[242:245], v[74:77]
	v_mfma_f32_16x16x32_bf16 v[126:129], v[146:149], v[222:225], v[126:129]
	v_mfma_f32_16x16x32_bf16 v[122:125], v[160:163], v[222:225], v[122:125]
	v_mfma_f32_16x16x32_bf16 v[110:113], v[146:149], v[230:233], v[110:113]
	v_mfma_f32_16x16x32_bf16 v[106:109], v[160:163], v[230:233], v[106:109]
	v_mfma_f32_16x16x32_bf16 v[94:97], v[146:149], v[238:241], v[94:97]
	v_mfma_f32_16x16x32_bf16 v[90:93], v[160:163], v[238:241], v[90:93]
	v_mfma_f32_16x16x32_bf16 v[78:81], v[146:149], v[246:249], v[78:81]
	v_mfma_f32_16x16x32_bf16 v[74:77], v[160:163], v[246:249], v[74:77]
	v_mfma_f32_16x16x32_bf16 v[118:121], v[164:167], v[206:209], v[118:121]
	v_mfma_f32_16x16x32_bf16 v[114:117], v[172:175], v[206:209], v[114:117]
	v_mfma_f32_16x16x32_bf16 v[102:105], v[164:167], v[226:229], v[102:105]
	v_mfma_f32_16x16x32_bf16 v[98:101], v[172:175], v[226:229], v[98:101]
	v_mfma_f32_16x16x32_bf16 v[86:89], v[164:167], v[234:237], v[86:89]
	v_mfma_f32_16x16x32_bf16 v[82:85], v[172:175], v[234:237], v[82:85]
	v_mfma_f32_16x16x32_bf16 v[70:73], v[164:167], v[242:245], v[70:73]
	v_mfma_f32_16x16x32_bf16 v[66:69], v[172:175], v[242:245], v[66:69]
	v_mfma_f32_16x16x32_bf16 v[118:121], v[168:171], v[222:225], v[118:121]
	v_mfma_f32_16x16x32_bf16 v[114:117], v[202:205], v[222:225], v[114:117]
	v_mfma_f32_16x16x32_bf16 v[102:105], v[168:171], v[230:233], v[102:105]
	v_mfma_f32_16x16x32_bf16 v[98:101], v[202:205], v[230:233], v[98:101]
	v_mfma_f32_16x16x32_bf16 v[86:89], v[168:171], v[238:241], v[86:89]
	v_mfma_f32_16x16x32_bf16 v[82:85], v[202:205], v[238:241], v[82:85]
	v_mfma_f32_16x16x32_bf16 v[70:73], v[168:171], v[246:249], v[70:73]
	v_mfma_f32_16x16x32_bf16 v[66:69], v[202:205], v[246:249], v[66:69]
	s_barrier
	s_add_i32 s20, s20, s61
	v_lshl_add_u64 v[150:151], s[8:9], 0, v[0:1]
	s_mov_b32 m0, s20
	ds_read_b128 v[206:209], v155 offset:16384
	ds_read_b128 v[222:225], v155 offset:17408
	ds_read_b128 v[226:229], v155 offset:18432
	ds_read_b128 v[230:233], v155 offset:19456
	ds_read_b128 v[234:237], v155 offset:20480
	ds_read_b128 v[238:241], v155 offset:21504
	ds_read_b128 v[242:245], v155 offset:22528
	ds_read_b128 v[246:249], v155 offset:23552
	global_load_lds_dwordx4 v[150:151], off
	s_add_i32 m0, s20, 0x2000
	s_add_u32 s20, s8, 0x40000
	v_lshl_add_u64 v[176:177], s[8:9], 0, v[134:135]
	s_addc_u32 s21, s9, 0
	s_add_i32 s37, s37, s61
	global_load_lds_dwordx4 v[176:177], off
	v_lshl_add_u64 v[178:179], s[20:21], 0, v[0:1]
	s_mov_b32 m0, s37
	v_lshl_add_u64 v[180:181], s[54:55], 0, v[132:133]
	global_load_lds_dwordx4 v[178:179], off
	v_lshl_add_u64 v[178:179], s[20:21], 0, v[134:135]
	s_add_i32 m0, s37, 0x2000
	s_nop 0
	global_load_lds_dwordx4 v[178:179], off
	v_lshl_add_u64 v[178:179], s[54:55], 0, v[130:131]
	s_mov_b32 m0, s62
	s_nop 0
	global_load_lds_dwordx4 v[178:179], off
	s_mov_b32 m0, s63
	s_nop 0
	global_load_lds_dwordx4 v[180:181], off
	s_waitcnt vmcnt(8)
	s_waitcnt lgkmcnt(0)
	s_barrier
	s_waitcnt lgkmcnt(0)
	v_mfma_f32_16x16x32_bf16 v[62:65], v[142:145], v[206:209], v[62:65]
	v_mfma_f32_16x16x32_bf16 v[58:61], v[156:159], v[206:209], v[58:61]
	v_mfma_f32_16x16x32_bf16 v[46:49], v[142:145], v[226:229], v[46:49]
	v_mfma_f32_16x16x32_bf16 v[42:45], v[156:159], v[226:229], v[42:45]
	v_mfma_f32_16x16x32_bf16 v[30:33], v[142:145], v[234:237], v[30:33]
	v_mfma_f32_16x16x32_bf16 v[26:29], v[156:159], v[234:237], v[26:29]
	v_mfma_f32_16x16x32_bf16 v[14:17], v[142:145], v[242:245], v[14:17]
	v_mfma_f32_16x16x32_bf16 v[10:13], v[156:159], v[242:245], v[10:13]
	v_mfma_f32_16x16x32_bf16 v[62:65], v[146:149], v[222:225], v[62:65]
	v_mfma_f32_16x16x32_bf16 v[58:61], v[160:163], v[222:225], v[58:61]
	v_mfma_f32_16x16x32_bf16 v[46:49], v[146:149], v[230:233], v[46:49]
	v_mfma_f32_16x16x32_bf16 v[42:45], v[160:163], v[230:233], v[42:45]
	v_mfma_f32_16x16x32_bf16 v[30:33], v[146:149], v[238:241], v[30:33]
	v_mfma_f32_16x16x32_bf16 v[26:29], v[160:163], v[238:241], v[26:29]
	v_mfma_f32_16x16x32_bf16 v[14:17], v[146:149], v[246:249], v[14:17]
	v_mfma_f32_16x16x32_bf16 v[10:13], v[160:163], v[246:249], v[10:13]
	v_mfma_f32_16x16x32_bf16 v[54:57], v[164:167], v[206:209], v[54:57]
	v_mfma_f32_16x16x32_bf16 v[50:53], v[172:175], v[206:209], v[50:53]
	v_mfma_f32_16x16x32_bf16 v[38:41], v[164:167], v[226:229], v[38:41]
	v_mfma_f32_16x16x32_bf16 v[34:37], v[172:175], v[226:229], v[34:37]
	v_mfma_f32_16x16x32_bf16 v[22:25], v[164:167], v[234:237], v[22:25]
	v_mfma_f32_16x16x32_bf16 v[18:21], v[172:175], v[234:237], v[18:21]
	v_mfma_f32_16x16x32_bf16 v[6:9], v[164:167], v[242:245], v[6:9]
	v_mfma_f32_16x16x32_bf16 v[2:5], v[172:175], v[242:245], v[2:5]
	v_mfma_f32_16x16x32_bf16 v[54:57], v[168:171], v[222:225], v[54:57]
	v_mfma_f32_16x16x32_bf16 v[50:53], v[202:205], v[222:225], v[50:53]
	v_mfma_f32_16x16x32_bf16 v[38:41], v[168:171], v[230:233], v[38:41]
	v_mfma_f32_16x16x32_bf16 v[34:37], v[202:205], v[230:233], v[34:37]
	v_mfma_f32_16x16x32_bf16 v[22:25], v[168:171], v[238:241], v[22:25]
	v_mfma_f32_16x16x32_bf16 v[18:21], v[202:205], v[238:241], v[18:21]
	v_mfma_f32_16x16x32_bf16 v[6:9], v[168:171], v[246:249], v[6:9]
	v_mfma_f32_16x16x32_bf16 v[2:5], v[202:205], v[246:249], v[2:5]
	s_barrier
	s_add_i32 s37, 0, 0x18000
	s_add_i32 s77, 0, 0x1c000
	v_add_u32_e32 v160, s37, v154
	v_add_u32_e32 v182, s77, v154
	ds_read_b128 v[142:145], v160
	ds_read_b128 v[146:149], v160 offset:1024
	ds_read_b128 v[156:159], v160 offset:2048
	ds_read_b128 v[160:163], v160 offset:3072
	ds_read_b128 v[164:167], v182
	ds_read_b128 v[168:171], v182 offset:1024
	ds_read_b128 v[172:175], v182 offset:2048
	ds_read_b128 v[202:205], v182 offset:3072
	s_add_u32 s20, s54, 0x40000
	s_addc_u32 s21, s55, 0
	s_mov_b32 m0, s64
	v_lshl_add_u64 v[182:183], s[20:21], 0, v[130:131]
	ds_read_b128 v[206:209], v155 offset:32768
	ds_read_b128 v[222:225], v155 offset:33792
	ds_read_b128 v[226:229], v155 offset:34816
	ds_read_b128 v[230:233], v155 offset:35840
	ds_read_b128 v[234:237], v155 offset:36864
	ds_read_b128 v[238:241], v155 offset:37888
	ds_read_b128 v[242:245], v155 offset:38912
	ds_read_b128 v[246:249], v155 offset:39936
	global_load_lds_dwordx4 v[182:183], off
	v_lshl_add_u64 v[182:183], s[20:21], 0, v[132:133]
	s_mov_b32 m0, s65
	s_nop 0
	global_load_lds_dwordx4 v[182:183], off
	s_waitcnt vmcnt(8)
	s_waitcnt lgkmcnt(0)
	s_barrier
	s_waitcnt lgkmcnt(0)
	v_mfma_f32_16x16x32_bf16 v[126:129], v[142:145], v[206:209], v[126:129]
	v_mfma_f32_16x16x32_bf16 v[122:125], v[156:159], v[206:209], v[122:125]
	v_mfma_f32_16x16x32_bf16 v[110:113], v[142:145], v[226:229], v[110:113]
	v_mfma_f32_16x16x32_bf16 v[106:109], v[156:159], v[226:229], v[106:109]
	v_mfma_f32_16x16x32_bf16 v[94:97], v[142:145], v[234:237], v[94:97]
	v_mfma_f32_16x16x32_bf16 v[90:93], v[156:159], v[234:237], v[90:93]
	v_mfma_f32_16x16x32_bf16 v[78:81], v[142:145], v[242:245], v[78:81]
	v_mfma_f32_16x16x32_bf16 v[74:77], v[156:159], v[242:245], v[74:77]
	v_mfma_f32_16x16x32_bf16 v[126:129], v[146:149], v[222:225], v[126:129]
	v_mfma_f32_16x16x32_bf16 v[122:125], v[160:163], v[222:225], v[122:125]
	v_mfma_f32_16x16x32_bf16 v[110:113], v[146:149], v[230:233], v[110:113]
	v_mfma_f32_16x16x32_bf16 v[106:109], v[160:163], v[230:233], v[106:109]
	v_mfma_f32_16x16x32_bf16 v[94:97], v[146:149], v[238:241], v[94:97]
	v_mfma_f32_16x16x32_bf16 v[90:93], v[160:163], v[238:241], v[90:93]
	v_mfma_f32_16x16x32_bf16 v[78:81], v[146:149], v[246:249], v[78:81]
	v_mfma_f32_16x16x32_bf16 v[74:77], v[160:163], v[246:249], v[74:77]
	v_mfma_f32_16x16x32_bf16 v[118:121], v[164:167], v[206:209], v[118:121]
	v_mfma_f32_16x16x32_bf16 v[114:117], v[172:175], v[206:209], v[114:117]
	v_mfma_f32_16x16x32_bf16 v[102:105], v[164:167], v[226:229], v[102:105]
	v_mfma_f32_16x16x32_bf16 v[98:101], v[172:175], v[226:229], v[98:101]
	v_mfma_f32_16x16x32_bf16 v[86:89], v[164:167], v[234:237], v[86:89]
	v_mfma_f32_16x16x32_bf16 v[82:85], v[172:175], v[234:237], v[82:85]
	v_mfma_f32_16x16x32_bf16 v[70:73], v[164:167], v[242:245], v[70:73]
	v_mfma_f32_16x16x32_bf16 v[66:69], v[172:175], v[242:245], v[66:69]
	v_mfma_f32_16x16x32_bf16 v[118:121], v[168:171], v[222:225], v[118:121]
	v_mfma_f32_16x16x32_bf16 v[114:117], v[202:205], v[222:225], v[114:117]
	v_mfma_f32_16x16x32_bf16 v[102:105], v[168:171], v[230:233], v[102:105]
	v_mfma_f32_16x16x32_bf16 v[98:101], v[202:205], v[230:233], v[98:101]
	v_mfma_f32_16x16x32_bf16 v[86:89], v[168:171], v[238:241], v[86:89]
	v_mfma_f32_16x16x32_bf16 v[82:85], v[202:205], v[238:241], v[82:85]
	v_mfma_f32_16x16x32_bf16 v[70:73], v[168:171], v[246:249], v[70:73]
	v_mfma_f32_16x16x32_bf16 v[66:69], v[202:205], v[246:249], v[66:69]
	s_barrier
	s_add_i32 s20, s37, s61
	v_lshl_add_u64 v[150:151], v[150:151], 0, s[24:25]
	s_mov_b32 m0, s20
	ds_read_b128 v[206:209], v155 offset:49152
	ds_read_b128 v[222:225], v155 offset:50176
	ds_read_b128 v[226:229], v155 offset:51200
	ds_read_b128 v[230:233], v155 offset:52224
	ds_read_b128 v[234:237], v155 offset:53248
	ds_read_b128 v[238:241], v155 offset:54272
	ds_read_b128 v[242:245], v155 offset:55296
	ds_read_b128 v[246:249], v155 offset:56320
	global_load_lds_dwordx4 v[150:151], off
	s_add_i32 m0, s20, 0x2000
	s_add_u32 s8, s8, 0x40080
	v_lshl_add_u64 v[150:151], v[176:177], 0, s[24:25]
	s_addc_u32 s9, s9, 0
	s_add_i32 s20, s77, s61
	global_load_lds_dwordx4 v[150:151], off
	v_lshl_add_u64 v[150:151], s[8:9], 0, v[0:1]
	s_mov_b32 m0, s20
	s_nop 0
	global_load_lds_dwordx4 v[150:151], off
	v_lshl_add_u64 v[150:151], s[8:9], 0, v[134:135]
	s_add_i32 m0, s20, 0x2000
	s_nop 0
	global_load_lds_dwordx4 v[150:151], off
	v_lshl_add_u64 v[150:151], v[178:179], 0, s[24:25]
	s_mov_b32 m0, s67
	s_nop 0
	global_load_lds_dwordx4 v[150:151], off
	v_lshl_add_u64 v[150:151], v[180:181], 0, s[24:25]
	s_mov_b32 m0, s68
	s_nop 0
	global_load_lds_dwordx4 v[150:151], off
	s_waitcnt vmcnt(8)
	s_waitcnt lgkmcnt(0)
	s_barrier
	s_waitcnt lgkmcnt(0)
	v_mfma_f32_16x16x32_bf16 v[62:65], v[142:145], v[206:209], v[62:65]
	v_mfma_f32_16x16x32_bf16 v[58:61], v[156:159], v[206:209], v[58:61]
	v_mfma_f32_16x16x32_bf16 v[46:49], v[142:145], v[226:229], v[46:49]
	v_mfma_f32_16x16x32_bf16 v[42:45], v[156:159], v[226:229], v[42:45]
	v_mfma_f32_16x16x32_bf16 v[30:33], v[142:145], v[234:237], v[30:33]
	v_mfma_f32_16x16x32_bf16 v[26:29], v[156:159], v[234:237], v[26:29]
	v_mfma_f32_16x16x32_bf16 v[14:17], v[142:145], v[242:245], v[14:17]
	v_mfma_f32_16x16x32_bf16 v[10:13], v[156:159], v[242:245], v[10:13]
	v_mfma_f32_16x16x32_bf16 v[62:65], v[146:149], v[222:225], v[62:65]
	v_mfma_f32_16x16x32_bf16 v[58:61], v[160:163], v[222:225], v[58:61]
	v_mfma_f32_16x16x32_bf16 v[46:49], v[146:149], v[230:233], v[46:49]
	v_mfma_f32_16x16x32_bf16 v[42:45], v[160:163], v[230:233], v[42:45]
	v_mfma_f32_16x16x32_bf16 v[30:33], v[146:149], v[238:241], v[30:33]
	v_mfma_f32_16x16x32_bf16 v[26:29], v[160:163], v[238:241], v[26:29]
	v_mfma_f32_16x16x32_bf16 v[14:17], v[146:149], v[246:249], v[14:17]
	v_mfma_f32_16x16x32_bf16 v[10:13], v[160:163], v[246:249], v[10:13]
	v_mfma_f32_16x16x32_bf16 v[54:57], v[164:167], v[206:209], v[54:57]
	v_mfma_f32_16x16x32_bf16 v[50:53], v[172:175], v[206:209], v[50:53]
	v_mfma_f32_16x16x32_bf16 v[38:41], v[164:167], v[226:229], v[38:41]
	v_mfma_f32_16x16x32_bf16 v[34:37], v[172:175], v[226:229], v[34:37]
	v_mfma_f32_16x16x32_bf16 v[22:25], v[164:167], v[234:237], v[22:25]
	v_mfma_f32_16x16x32_bf16 v[18:21], v[172:175], v[234:237], v[18:21]
	v_mfma_f32_16x16x32_bf16 v[6:9], v[164:167], v[242:245], v[6:9]
	v_mfma_f32_16x16x32_bf16 v[2:5], v[172:175], v[242:245], v[2:5]
	v_mfma_f32_16x16x32_bf16 v[54:57], v[168:171], v[222:225], v[54:57]
	v_mfma_f32_16x16x32_bf16 v[50:53], v[202:205], v[222:225], v[50:53]
	v_mfma_f32_16x16x32_bf16 v[38:41], v[168:171], v[230:233], v[38:41]
	v_mfma_f32_16x16x32_bf16 v[34:37], v[202:205], v[230:233], v[34:37]
	v_mfma_f32_16x16x32_bf16 v[22:25], v[168:171], v[238:241], v[22:25]
	v_mfma_f32_16x16x32_bf16 v[18:21], v[202:205], v[238:241], v[18:21]
	v_mfma_f32_16x16x32_bf16 v[6:9], v[168:171], v[246:249], v[6:9]
	v_mfma_f32_16x16x32_bf16 v[2:5], v[202:205], v[246:249], v[2:5]
	s_barrier
	s_add_i32 s88, s88, 2
	s_add_u32 s4, s4, 0x100
	s_addc_u32 s5, s5, 0
	s_add_u32 s57, s57, 0x100
	s_addc_u32 s87, s87, 0
	s_cmp_gt_u32 s88, 13
	s_cbranch_scc0 .LBB0_103
	s_and_b64 vcc, exec, s[46:47]
	s_cbranch_vccz .LBB0_106
	s_barrier

.LBB0_436:
	s_add_u32 s37, s52, s56
	s_addc_u32 s57, s53, 0
	s_add_u32 s58, s37, 0x100
	s_addc_u32 s59, s57, 0
	s_and_b64 s[20:21], s[54:55], exec
	s_cselect_b32 s59, s45, s59
	s_cselect_b32 s58, s44, s58
	s_add_u32 s20, s50, s56
	s_addc_u32 s21, s51, 0
	s_add_u32 s56, s20, 0x100
	s_addc_u32 s60, s21, 0
	s_add_i32 s78, 0, 0x10000
	s_and_b64 s[20:21], s[54:55], exec
	s_cselect_b32 s61, s19, s60
	s_cselect_b32 s60, s49, s56
	s_add_i32 s20, 0, 0x14000
	s_add_u32 s64, s37, 0x10080
	s_addc_u32 s65, s57, 0
	s_add_i32 s37, s78, s70
	s_add_i32 m0, s71, 0xc000
	s_add_i32 s21, s71, 0xe000
	s_add_i32 s77, s37, 0x2000
	v_add_u32_e32 v0, s78, v142
	s_add_u32 s62, s60, 0x10000
	ds_read_b128 v[138:141], v0
	ds_read_b128 v[144:147], v0 offset:1024
	ds_read_b128 v[148:151], v0 offset:2048
	ds_read_b128 v[152:155], v0 offset:3072
	v_add_u32_e32 v0, s20, v142
	s_addc_u32 s63, s61, 0
	s_add_i32 s82, s20, s70
	ds_read_b128 v[156:159], v0
	ds_read_b128 v[160:163], v0 offset:1024
	ds_read_b128 v[164:167], v0 offset:2048
	ds_read_b128 v[168:171], v0 offset:3072
	s_add_i32 s83, s82, 0x2000
	s_add_i32 vcc_hi, 0, 0x18000
	s_add_i32 vcc_lo, 0, 0x1c000
	s_add_u32 s56, s58, 0x10000
	s_addc_u32 s57, s59, 0
	s_add_i32 s97, vcc_hi, s70
	s_add_i32 s96, s97, 0x2000
	s_add_u32 s54, s60, 0x10080
	s_addc_u32 s55, s61, 0
	s_add_i32 s78, vcc_lo, s70
	s_add_i32 s20, s78, 0x2000
	v_lshl_add_u64 v[176:177], s[64:65], 0, v[130:131]
	ds_read_b128 v[172:175], v143
	ds_read_b128 v[202:205], v143 offset:1024
	ds_read_b128 v[206:209], v143 offset:2048
	ds_read_b128 v[222:225], v143 offset:3072
	ds_read_b128 v[226:229], v143 offset:4096
	ds_read_b128 v[230:233], v143 offset:5120
	ds_read_b128 v[234:237], v143 offset:6144
	ds_read_b128 v[238:241], v143 offset:7168
	global_load_lds_dwordx4 v[176:177], off
	v_lshl_add_u64 v[176:177], s[64:65], 0, v[132:133]
	s_mov_b32 m0, s21
	s_nop 0
	global_load_lds_dwordx4 v[176:177], off
	s_waitcnt vmcnt(8)
	s_waitcnt lgkmcnt(0)
	s_barrier
	s_waitcnt lgkmcnt(0)
	v_mfma_f32_16x16x32_bf16 v[126:129], v[138:141], v[172:175], v[126:129]
	v_mfma_f32_16x16x32_bf16 v[122:125], v[148:151], v[172:175], v[122:125]
	v_mfma_f32_16x16x32_bf16 v[118:121], v[138:141], v[206:209], v[118:121]
	v_mfma_f32_16x16x32_bf16 v[114:117], v[148:151], v[206:209], v[114:117]
	v_mfma_f32_16x16x32_bf16 v[110:113], v[138:141], v[226:229], v[110:113]
	v_mfma_f32_16x16x32_bf16 v[106:109], v[148:151], v[226:229], v[106:109]
	v_mfma_f32_16x16x32_bf16 v[102:105], v[138:141], v[234:237], v[102:105]
	v_mfma_f32_16x16x32_bf16 v[98:101], v[148:151], v[234:237], v[98:101]
	v_mfma_f32_16x16x32_bf16 v[126:129], v[144:147], v[202:205], v[126:129]
	v_mfma_f32_16x16x32_bf16 v[122:125], v[152:155], v[202:205], v[122:125]
	v_mfma_f32_16x16x32_bf16 v[118:121], v[144:147], v[222:225], v[118:121]
	v_mfma_f32_16x16x32_bf16 v[114:117], v[152:155], v[222:225], v[114:117]
	v_mfma_f32_16x16x32_bf16 v[110:113], v[144:147], v[230:233], v[110:113]
	v_mfma_f32_16x16x32_bf16 v[106:109], v[152:155], v[230:233], v[106:109]
	v_mfma_f32_16x16x32_bf16 v[102:105], v[144:147], v[238:241], v[102:105]
	v_mfma_f32_16x16x32_bf16 v[98:101], v[152:155], v[238:241], v[98:101]
	v_mfma_f32_16x16x32_bf16 v[62:65], v[156:159], v[172:175], v[62:65]
	v_mfma_f32_16x16x32_bf16 v[58:61], v[164:167], v[172:175], v[58:61]
	v_mfma_f32_16x16x32_bf16 v[54:57], v[156:159], v[206:209], v[54:57]
	v_mfma_f32_16x16x32_bf16 v[50:53], v[164:167], v[206:209], v[50:53]
	v_mfma_f32_16x16x32_bf16 v[46:49], v[156:159], v[226:229], v[46:49]
	v_mfma_f32_16x16x32_bf16 v[42:45], v[164:167], v[226:229], v[42:45]
	v_mfma_f32_16x16x32_bf16 v[38:41], v[156:159], v[234:237], v[38:41]
	v_mfma_f32_16x16x32_bf16 v[34:37], v[164:167], v[234:237], v[34:37]
	v_mfma_f32_16x16x32_bf16 v[62:65], v[160:163], v[202:205], v[62:65]
	v_mfma_f32_16x16x32_bf16 v[58:61], v[168:171], v[202:205], v[58:61]
	v_mfma_f32_16x16x32_bf16 v[54:57], v[160:163], v[222:225], v[54:57]
	v_mfma_f32_16x16x32_bf16 v[50:53], v[168:171], v[222:225], v[50:53]
	v_mfma_f32_16x16x32_bf16 v[46:49], v[160:163], v[230:233], v[46:49]
	v_mfma_f32_16x16x32_bf16 v[42:45], v[168:171], v[230:233], v[42:45]
	v_mfma_f32_16x16x32_bf16 v[38:41], v[160:163], v[238:241], v[38:41]
	v_mfma_f32_16x16x32_bf16 v[34:37], v[168:171], v[238:241], v[34:37]
	s_barrier
	s_mov_b32 m0, s37
	v_lshl_add_u64 v[176:177], s[60:61], 0, v[130:131]
	ds_read_b128 v[172:175], v143 offset:16384
	ds_read_b128 v[202:205], v143 offset:17408
	ds_read_b128 v[206:209], v143 offset:18432
	ds_read_b128 v[222:225], v143 offset:19456
	ds_read_b128 v[226:229], v143 offset:20480
	ds_read_b128 v[230:233], v143 offset:21504
	ds_read_b128 v[234:237], v143 offset:22528
	ds_read_b128 v[238:241], v143 offset:23552
	global_load_lds_dwordx4 v[176:177], off
	v_lshl_add_u64 v[178:179], s[60:61], 0, v[132:133]
	s_mov_b32 m0, s77
	v_lshl_add_u64 v[180:181], s[62:63], 0, v[130:131]
	global_load_lds_dwordx4 v[178:179], off
	s_mov_b32 m0, s82
	v_lshl_add_u64 v[182:183], s[58:59], 0, v[132:133]
	global_load_lds_dwordx4 v[180:181], off
	v_lshl_add_u64 v[180:181], s[62:63], 0, v[132:133]
	s_mov_b32 m0, s83
	s_nop 0
	global_load_lds_dwordx4 v[180:181], off
	v_lshl_add_u64 v[180:181], s[58:59], 0, v[130:131]
	s_mov_b32 m0, s71
	s_nop 0
	global_load_lds_dwordx4 v[180:181], off
	s_mov_b32 m0, s72
	s_nop 0
	global_load_lds_dwordx4 v[182:183], off
	s_waitcnt vmcnt(8)
	s_waitcnt lgkmcnt(0)
	s_barrier
	s_waitcnt lgkmcnt(0)
	v_mfma_f32_16x16x32_bf16 v[90:93], v[138:141], v[172:175], v[90:93]
	v_mfma_f32_16x16x32_bf16 v[94:97], v[148:151], v[172:175], v[94:97]
	v_mfma_f32_16x16x32_bf16 v[86:89], v[138:141], v[206:209], v[86:89]
	v_mfma_f32_16x16x32_bf16 v[82:85], v[148:151], v[206:209], v[82:85]
	v_mfma_f32_16x16x32_bf16 v[78:81], v[138:141], v[226:229], v[78:81]
	v_mfma_f32_16x16x32_bf16 v[74:77], v[148:151], v[226:229], v[74:77]
	v_mfma_f32_16x16x32_bf16 v[70:73], v[138:141], v[234:237], v[70:73]
	v_mfma_f32_16x16x32_bf16 v[66:69], v[148:151], v[234:237], v[66:69]
	v_mfma_f32_16x16x32_bf16 v[90:93], v[144:147], v[202:205], v[90:93]
	v_mfma_f32_16x16x32_bf16 v[94:97], v[152:155], v[202:205], v[94:97]
	v_mfma_f32_16x16x32_bf16 v[86:89], v[144:147], v[222:225], v[86:89]
	v_mfma_f32_16x16x32_bf16 v[82:85], v[152:155], v[222:225], v[82:85]
	v_mfma_f32_16x16x32_bf16 v[78:81], v[144:147], v[230:233], v[78:81]
	v_mfma_f32_16x16x32_bf16 v[74:77], v[152:155], v[230:233], v[74:77]
	v_mfma_f32_16x16x32_bf16 v[70:73], v[144:147], v[238:241], v[70:73]
	v_mfma_f32_16x16x32_bf16 v[66:69], v[152:155], v[238:241], v[66:69]
	v_mfma_f32_16x16x32_bf16 v[30:33], v[156:159], v[172:175], v[30:33]
	v_mfma_f32_16x16x32_bf16 v[26:29], v[164:167], v[172:175], v[26:29]
	v_mfma_f32_16x16x32_bf16 v[22:25], v[156:159], v[206:209], v[22:25]
	v_mfma_f32_16x16x32_bf16 v[18:21], v[164:167], v[206:209], v[18:21]
	v_mfma_f32_16x16x32_bf16 v[14:17], v[156:159], v[226:229], v[14:17]
	v_mfma_f32_16x16x32_bf16 v[10:13], v[164:167], v[226:229], v[10:13]
	v_mfma_f32_16x16x32_bf16 v[6:9], v[156:159], v[234:237], v[6:9]
	v_mfma_f32_16x16x32_bf16 v[2:5], v[164:167], v[234:237], v[2:5]
	v_mfma_f32_16x16x32_bf16 v[30:33], v[160:163], v[202:205], v[30:33]
	v_mfma_f32_16x16x32_bf16 v[26:29], v[168:171], v[202:205], v[26:29]
	v_mfma_f32_16x16x32_bf16 v[22:25], v[160:163], v[222:225], v[22:25]
	v_mfma_f32_16x16x32_bf16 v[18:21], v[168:171], v[222:225], v[18:21]
	v_mfma_f32_16x16x32_bf16 v[14:17], v[160:163], v[230:233], v[14:17]
	v_mfma_f32_16x16x32_bf16 v[10:13], v[168:171], v[230:233], v[10:13]
	v_mfma_f32_16x16x32_bf16 v[6:9], v[160:163], v[238:241], v[6:9]
	v_mfma_f32_16x16x32_bf16 v[2:5], v[168:171], v[238:241], v[2:5]
	s_barrier
	v_add_u32_e32 v0, vcc_hi, v142
	ds_read_b128 v[138:141], v0
	ds_read_b128 v[144:147], v0 offset:1024
	ds_read_b128 v[148:151], v0 offset:2048
	ds_read_b128 v[152:155], v0 offset:3072
	v_add_u32_e32 v0, vcc_lo, v142
	ds_read_b128 v[156:159], v0
	ds_read_b128 v[160:163], v0 offset:1024
	ds_read_b128 v[164:167], v0 offset:2048
	ds_read_b128 v[168:171], v0 offset:3072
	s_mov_b32 m0, s73
	v_lshl_add_u64 v[184:185], s[56:57], 0, v[130:131]
	ds_read_b128 v[172:175], v143 offset:32768
	ds_read_b128 v[202:205], v143 offset:33792
	ds_read_b128 v[206:209], v143 offset:34816
	ds_read_b128 v[222:225], v143 offset:35840
	ds_read_b128 v[226:229], v143 offset:36864
	ds_read_b128 v[230:233], v143 offset:37888
	ds_read_b128 v[234:237], v143 offset:38912
	ds_read_b128 v[238:241], v143 offset:39936
	global_load_lds_dwordx4 v[184:185], off
	v_lshl_add_u64 v[184:185], s[56:57], 0, v[132:133]
	s_mov_b32 m0, s81
	s_nop 0
	global_load_lds_dwordx4 v[184:185], off
	s_waitcnt vmcnt(8)
	s_waitcnt lgkmcnt(0)
	s_barrier
	s_waitcnt lgkmcnt(0)
	v_mfma_f32_16x16x32_bf16 v[126:129], v[138:141], v[172:175], v[126:129]
	v_mfma_f32_16x16x32_bf16 v[122:125], v[148:151], v[172:175], v[122:125]
	v_mfma_f32_16x16x32_bf16 v[118:121], v[138:141], v[206:209], v[118:121]
	v_mfma_f32_16x16x32_bf16 v[114:117], v[148:151], v[206:209], v[114:117]
	v_mfma_f32_16x16x32_bf16 v[110:113], v[138:141], v[226:229], v[110:113]
	v_mfma_f32_16x16x32_bf16 v[106:109], v[148:151], v[226:229], v[106:109]
	v_mfma_f32_16x16x32_bf16 v[102:105], v[138:141], v[234:237], v[102:105]
	v_mfma_f32_16x16x32_bf16 v[98:101], v[148:151], v[234:237], v[98:101]
	v_mfma_f32_16x16x32_bf16 v[126:129], v[144:147], v[202:205], v[126:129]
	v_mfma_f32_16x16x32_bf16 v[122:125], v[152:155], v[202:205], v[122:125]
	v_mfma_f32_16x16x32_bf16 v[118:121], v[144:147], v[222:225], v[118:121]
	v_mfma_f32_16x16x32_bf16 v[114:117], v[152:155], v[222:225], v[114:117]
	v_mfma_f32_16x16x32_bf16 v[110:113], v[144:147], v[230:233], v[110:113]
	v_mfma_f32_16x16x32_bf16 v[106:109], v[152:155], v[230:233], v[106:109]
	v_mfma_f32_16x16x32_bf16 v[102:105], v[144:147], v[238:241], v[102:105]
	v_mfma_f32_16x16x32_bf16 v[98:101], v[152:155], v[238:241], v[98:101]
	v_mfma_f32_16x16x32_bf16 v[62:65], v[156:159], v[172:175], v[62:65]
	v_mfma_f32_16x16x32_bf16 v[58:61], v[164:167], v[172:175], v[58:61]
	v_mfma_f32_16x16x32_bf16 v[54:57], v[156:159], v[206:209], v[54:57]
	v_mfma_f32_16x16x32_bf16 v[50:53], v[164:167], v[206:209], v[50:53]
	v_mfma_f32_16x16x32_bf16 v[46:49], v[156:159], v[226:229], v[46:49]
	v_mfma_f32_16x16x32_bf16 v[42:45], v[164:167], v[226:229], v[42:45]
	v_mfma_f32_16x16x32_bf16 v[38:41], v[156:159], v[234:237], v[38:41]
	v_mfma_f32_16x16x32_bf16 v[34:37], v[164:167], v[234:237], v[34:37]
	v_mfma_f32_16x16x32_bf16 v[62:65], v[160:163], v[202:205], v[62:65]
	v_mfma_f32_16x16x32_bf16 v[58:61], v[168:171], v[202:205], v[58:61]
	v_mfma_f32_16x16x32_bf16 v[54:57], v[160:163], v[222:225], v[54:57]
	v_mfma_f32_16x16x32_bf16 v[50:53], v[168:171], v[222:225], v[50:53]
	v_mfma_f32_16x16x32_bf16 v[46:49], v[160:163], v[230:233], v[46:49]
	v_mfma_f32_16x16x32_bf16 v[42:45], v[168:171], v[230:233], v[42:45]
	v_mfma_f32_16x16x32_bf16 v[38:41], v[160:163], v[238:241], v[38:41]
	v_mfma_f32_16x16x32_bf16 v[34:37], v[168:171], v[238:241], v[34:37]
	s_barrier
	s_mov_b32 m0, s97
	v_lshl_add_u64 v[176:177], v[176:177], 0, s[24:25]
	ds_read_b128 v[172:175], v143 offset:49152
	ds_read_b128 v[202:205], v143 offset:50176
	ds_read_b128 v[206:209], v143 offset:51200
	ds_read_b128 v[222:225], v143 offset:52224
	ds_read_b128 v[226:229], v143 offset:53248
	ds_read_b128 v[230:233], v143 offset:54272
	ds_read_b128 v[234:237], v143 offset:55296
	ds_read_b128 v[238:241], v143 offset:56320
	global_load_lds_dwordx4 v[176:177], off
	v_lshl_add_u64 v[176:177], v[178:179], 0, s[24:25]
	s_mov_b32 m0, s96
	s_nop 0
	global_load_lds_dwordx4 v[176:177], off
	v_lshl_add_u64 v[176:177], s[54:55], 0, v[130:131]
	s_mov_b32 m0, s78
	s_nop 0
	global_load_lds_dwordx4 v[176:177], off
	v_lshl_add_u64 v[176:177], s[54:55], 0, v[132:133]
	s_mov_b32 m0, s20
	s_nop 0
	global_load_lds_dwordx4 v[176:177], off
	v_lshl_add_u64 v[176:177], v[180:181], 0, s[24:25]
	s_mov_b32 m0, s86
	s_nop 0
	global_load_lds_dwordx4 v[176:177], off
	v_lshl_add_u64 v[176:177], v[182:183], 0, s[24:25]
	s_mov_b32 m0, s88
	s_nop 0
	global_load_lds_dwordx4 v[176:177], off
	s_waitcnt vmcnt(8)
	s_waitcnt lgkmcnt(0)
	s_barrier
	s_waitcnt lgkmcnt(0)
	v_mfma_f32_16x16x32_bf16 v[90:93], v[138:141], v[172:175], v[90:93]
	v_mfma_f32_16x16x32_bf16 v[94:97], v[148:151], v[172:175], v[94:97]
	v_mfma_f32_16x16x32_bf16 v[86:89], v[138:141], v[206:209], v[86:89]
	v_mfma_f32_16x16x32_bf16 v[82:85], v[148:151], v[206:209], v[82:85]
	v_mfma_f32_16x16x32_bf16 v[78:81], v[138:141], v[226:229], v[78:81]
	v_mfma_f32_16x16x32_bf16 v[74:77], v[148:151], v[226:229], v[74:77]
	v_mfma_f32_16x16x32_bf16 v[70:73], v[138:141], v[234:237], v[70:73]
	v_mfma_f32_16x16x32_bf16 v[66:69], v[148:151], v[234:237], v[66:69]
	v_mfma_f32_16x16x32_bf16 v[90:93], v[144:147], v[202:205], v[90:93]
	v_mfma_f32_16x16x32_bf16 v[94:97], v[152:155], v[202:205], v[94:97]
	v_mfma_f32_16x16x32_bf16 v[86:89], v[144:147], v[222:225], v[86:89]
	v_mfma_f32_16x16x32_bf16 v[82:85], v[152:155], v[222:225], v[82:85]
	v_mfma_f32_16x16x32_bf16 v[78:81], v[144:147], v[230:233], v[78:81]
	v_mfma_f32_16x16x32_bf16 v[74:77], v[152:155], v[230:233], v[74:77]
	v_mfma_f32_16x16x32_bf16 v[70:73], v[144:147], v[238:241], v[70:73]
	v_mfma_f32_16x16x32_bf16 v[66:69], v[152:155], v[238:241], v[66:69]
	v_mfma_f32_16x16x32_bf16 v[30:33], v[156:159], v[172:175], v[30:33]
	v_mfma_f32_16x16x32_bf16 v[26:29], v[164:167], v[172:175], v[26:29]
	v_mfma_f32_16x16x32_bf16 v[22:25], v[156:159], v[206:209], v[22:25]
	v_mfma_f32_16x16x32_bf16 v[18:21], v[164:167], v[206:209], v[18:21]
	v_mfma_f32_16x16x32_bf16 v[14:17], v[156:159], v[226:229], v[14:17]
	v_mfma_f32_16x16x32_bf16 v[10:13], v[164:167], v[226:229], v[10:13]
	v_mfma_f32_16x16x32_bf16 v[6:9], v[156:159], v[234:237], v[6:9]
	v_mfma_f32_16x16x32_bf16 v[2:5], v[164:167], v[234:237], v[2:5]
	v_mfma_f32_16x16x32_bf16 v[30:33], v[160:163], v[202:205], v[30:33]
	v_mfma_f32_16x16x32_bf16 v[26:29], v[168:171], v[202:205], v[26:29]
	v_mfma_f32_16x16x32_bf16 v[22:25], v[160:163], v[222:225], v[22:25]
	v_mfma_f32_16x16x32_bf16 v[18:21], v[168:171], v[222:225], v[18:21]
	v_mfma_f32_16x16x32_bf16 v[14:17], v[160:163], v[230:233], v[14:17]
	v_mfma_f32_16x16x32_bf16 v[10:13], v[168:171], v[230:233], v[10:13]
	v_mfma_f32_16x16x32_bf16 v[6:9], v[160:163], v[238:241], v[6:9]
	v_mfma_f32_16x16x32_bf16 v[2:5], v[168:171], v[238:241], v[2:5]
	s_barrier
	s_movk_i32 s56, 0x100
	s_andn2_b64 vcc, exec, s[4:5]
	s_mov_b64 s[54:55], -1
	s_mov_b64 s[4:5], 0
	s_cbranch_vccz .LBB0_436
	s_and_b64 vcc, exec, s[16:17]
	s_cbranch_vccz .LBB0_439
	s_barrier

.LBB0_495:
	s_ashr_i32 s19, s18, 31
	s_lshl_b64 s[20:21], s[18:19], 16
	s_add_u32 s46, s55, s20
	s_addc_u32 s47, s56, s21
	s_and_b64 s[4:5], s[4:5], exec
	s_cselect_b32 s5, s47, s53
	s_cselect_b32 s4, s46, s52
	s_add_i32 s19, 0, 0x10000
	s_add_i32 s37, 0, 0x14000
	v_add_u32_e32 v14, s19, v141
	v_add_u32_e32 v30, s37, v141
	ds_read_b128 v[2:5], v14
	ds_read_b128 v[6:9], v14 offset:1024
	ds_read_b128 v[10:13], v14 offset:2048
	ds_read_b128 v[14:17], v14 offset:3072
	ds_read_b128 v[18:21], v30
	ds_read_b128 v[22:25], v30 offset:1024
	ds_read_b128 v[26:29], v30 offset:2048
	ds_read_b128 v[30:33], v30 offset:3072
	s_add_u32 s20, s50, 0x8080
	s_addc_u32 s21, s51, 0
	v_lshl_add_u64 v[66:67], s[20:21], 0, v[130:131]
	s_add_i32 m0, s58, 0xc000
	ds_read_b128 v[34:37], v143
	ds_read_b128 v[38:41], v143 offset:1024
	ds_read_b128 v[42:45], v143 offset:2048
	ds_read_b128 v[46:49], v143 offset:3072
	ds_read_b128 v[50:53], v143 offset:4096
	ds_read_b128 v[54:57], v143 offset:5120
	ds_read_b128 v[58:61], v143 offset:6144
	ds_read_b128 v[62:65], v143 offset:7168
	global_load_lds_dwordx4 v[66:67], off
	v_lshl_add_u64 v[66:67], s[20:21], 0, v[132:133]
	s_add_i32 m0, s58, 0xe000
	s_nop 0
	global_load_lds_dwordx4 v[66:67], off
	s_waitcnt vmcnt(8)
	s_waitcnt lgkmcnt(0)
	s_barrier
	s_waitcnt lgkmcnt(0)
	v_mfma_f32_16x16x32_bf16 v[90:93], v[2:5], v[58:61], 0
	v_mfma_f32_16x16x32_bf16 v[66:69], v[2:5], v[34:37], 0
	v_mfma_f32_16x16x32_bf16 v[70:73], v[10:13], v[34:37], 0
	v_mfma_f32_16x16x32_bf16 v[74:77], v[2:5], v[42:45], 0
	v_mfma_f32_16x16x32_bf16 v[78:81], v[10:13], v[42:45], 0
	v_mfma_f32_16x16x32_bf16 v[82:85], v[2:5], v[50:53], 0
	v_mfma_f32_16x16x32_bf16 v[86:89], v[10:13], v[50:53], 0
	v_mfma_f32_16x16x32_bf16 v[98:101], v[6:9], v[62:65], v[90:93]
	v_mfma_f32_16x16x32_bf16 v[90:93], v[10:13], v[58:61], 0
	v_mfma_f32_16x16x32_bf16 v[66:69], v[6:9], v[38:41], v[66:69]
	v_mfma_f32_16x16x32_bf16 v[70:73], v[14:17], v[38:41], v[70:73]
	v_mfma_f32_16x16x32_bf16 v[74:77], v[6:9], v[46:49], v[74:77]
	v_mfma_f32_16x16x32_bf16 v[78:81], v[14:17], v[46:49], v[78:81]
	v_mfma_f32_16x16x32_bf16 v[82:85], v[6:9], v[54:57], v[82:85]
	v_mfma_f32_16x16x32_bf16 v[86:89], v[14:17], v[54:57], v[86:89]
	v_mfma_f32_16x16x32_bf16 v[102:105], v[14:17], v[62:65], v[90:93]
	v_mfma_f32_16x16x32_bf16 v[90:93], v[18:21], v[34:37], 0
	v_mfma_f32_16x16x32_bf16 v[34:37], v[26:29], v[34:37], 0
	v_mfma_f32_16x16x32_bf16 v[114:117], v[22:25], v[38:41], v[90:93]
	v_mfma_f32_16x16x32_bf16 v[34:37], v[30:33], v[38:41], v[34:37]
	v_mfma_f32_16x16x32_bf16 v[38:41], v[18:21], v[42:45], 0
	v_mfma_f32_16x16x32_bf16 v[42:45], v[26:29], v[42:45], 0
	v_mfma_f32_16x16x32_bf16 v[38:41], v[22:25], v[46:49], v[38:41]
	v_mfma_f32_16x16x32_bf16 v[42:45], v[30:33], v[46:49], v[42:45]
	v_mfma_f32_16x16x32_bf16 v[46:49], v[18:21], v[50:53], 0
	v_mfma_f32_16x16x32_bf16 v[50:53], v[26:29], v[50:53], 0
	v_mfma_f32_16x16x32_bf16 v[46:49], v[22:25], v[54:57], v[46:49]
	v_mfma_f32_16x16x32_bf16 v[50:53], v[30:33], v[54:57], v[50:53]
	v_mfma_f32_16x16x32_bf16 v[54:57], v[18:21], v[58:61], 0
	v_mfma_f32_16x16x32_bf16 v[58:61], v[26:29], v[58:61], 0
	v_mfma_f32_16x16x32_bf16 v[54:57], v[22:25], v[62:65], v[54:57]
	v_mfma_f32_16x16x32_bf16 v[62:65], v[30:33], v[62:65], v[58:61]
	s_barrier
	s_add_i32 s19, s19, s57
	v_lshl_add_u64 v[184:185], s[4:5], 0, v[0:1]
	s_mov_b32 m0, s19
	s_nop 0
	ds_read_b128 v[58:61], v143 offset:16384
	ds_read_b128 v[90:93], v143 offset:17408
	ds_read_b128 v[94:97], v143 offset:18432
	ds_read_b128 v[106:109], v143 offset:19456
	ds_read_b128 v[110:113], v143 offset:20480
	ds_read_b128 v[118:121], v143 offset:21504
	ds_read_b128 v[122:125], v143 offset:22528
	ds_read_b128 v[126:129], v143 offset:23552
	global_load_lds_dwordx4 v[184:185], off
	s_add_i32 m0, s19, 0x2000
	s_add_u32 s20, s4, 0x8000
	v_lshl_add_u64 v[190:191], s[4:5], 0, v[134:135]
	s_addc_u32 s21, s5, 0
	s_add_i32 s19, s37, s57
	global_load_lds_dwordx4 v[190:191], off
	v_lshl_add_u64 v[136:137], s[20:21], 0, v[0:1]
	s_mov_b32 m0, s19
	v_lshl_add_u64 v[192:193], s[44:45], 0, v[130:131]
	global_load_lds_dwordx4 v[136:137], off
	v_lshl_add_u64 v[136:137], s[20:21], 0, v[134:135]
	s_add_i32 m0, s19, 0x2000
	v_lshl_add_u64 v[194:195], s[44:45], 0, v[132:133]
	global_load_lds_dwordx4 v[136:137], off
	s_mov_b32 m0, s58
	s_nop 0
	global_load_lds_dwordx4 v[192:193], off
	s_mov_b32 m0, s59
	s_nop 0
	global_load_lds_dwordx4 v[194:195], off
	s_waitcnt vmcnt(8)
	s_waitcnt lgkmcnt(0)
	s_barrier
	s_waitcnt lgkmcnt(0)
	v_mfma_f32_16x16x32_bf16 v[136:139], v[2:5], v[58:61], 0
	v_mfma_f32_16x16x32_bf16 v[148:151], v[2:5], v[94:97], 0
	v_mfma_f32_16x16x32_bf16 v[156:159], v[2:5], v[110:113], 0
	v_mfma_f32_16x16x32_bf16 v[2:5], v[2:5], v[122:125], 0
	v_mfma_f32_16x16x32_bf16 v[136:139], v[6:9], v[90:93], v[136:139]
	v_mfma_f32_16x16x32_bf16 v[148:151], v[6:9], v[106:109], v[148:151]
	v_mfma_f32_16x16x32_bf16 v[156:159], v[6:9], v[118:121], v[156:159]
	v_mfma_f32_16x16x32_bf16 v[2:5], v[6:9], v[126:129], v[2:5]
	v_mfma_f32_16x16x32_bf16 v[6:9], v[10:13], v[122:125], 0
	v_mfma_f32_16x16x32_bf16 v[144:147], v[10:13], v[58:61], 0
	v_mfma_f32_16x16x32_bf16 v[152:155], v[10:13], v[94:97], 0
	v_mfma_f32_16x16x32_bf16 v[160:163], v[10:13], v[110:113], 0
	v_mfma_f32_16x16x32_bf16 v[6:9], v[14:17], v[126:129], v[6:9]
	v_mfma_f32_16x16x32_bf16 v[144:147], v[14:17], v[90:93], v[144:147]
	v_mfma_f32_16x16x32_bf16 v[152:155], v[14:17], v[106:109], v[152:155]
	v_mfma_f32_16x16x32_bf16 v[160:163], v[14:17], v[118:121], v[160:163]
	v_mfma_f32_16x16x32_bf16 v[10:13], v[18:21], v[58:61], 0
	v_mfma_f32_16x16x32_bf16 v[164:167], v[22:25], v[90:93], v[10:13]
	v_mfma_f32_16x16x32_bf16 v[10:13], v[26:29], v[58:61], 0
	v_mfma_f32_16x16x32_bf16 v[168:171], v[30:33], v[90:93], v[10:13]
	v_mfma_f32_16x16x32_bf16 v[10:13], v[18:21], v[94:97], 0
	v_mfma_f32_16x16x32_bf16 v[172:175], v[22:25], v[106:109], v[10:13]
	v_mfma_f32_16x16x32_bf16 v[10:13], v[26:29], v[94:97], 0
	v_mfma_f32_16x16x32_bf16 v[202:205], v[30:33], v[106:109], v[10:13]
	v_mfma_f32_16x16x32_bf16 v[10:13], v[18:21], v[110:113], 0
	v_mfma_f32_16x16x32_bf16 v[206:209], v[22:25], v[118:121], v[10:13]
	v_mfma_f32_16x16x32_bf16 v[10:13], v[26:29], v[110:113], 0
	v_mfma_f32_16x16x32_bf16 v[222:225], v[30:33], v[118:121], v[10:13]
	v_mfma_f32_16x16x32_bf16 v[10:13], v[18:21], v[122:125], 0
	v_mfma_f32_16x16x32_bf16 v[226:229], v[22:25], v[126:129], v[10:13]
	v_mfma_f32_16x16x32_bf16 v[10:13], v[26:29], v[122:125], 0
	v_mfma_f32_16x16x32_bf16 v[230:233], v[30:33], v[126:129], v[10:13]
	s_barrier
	s_add_i32 s19, 0, 0x18000
	s_add_i32 s37, 0, 0x1c000
	v_add_u32_e32 v22, s19, v141
	v_add_u32_e32 v26, s37, v141
	s_nop 0
	ds_read_b128 v[10:13], v22
	ds_read_b128 v[14:17], v22 offset:1024
	ds_read_b128 v[18:21], v22 offset:2048
	ds_read_b128 v[22:25], v22 offset:3072
	ds_read_b128 v[234:237], v26
	ds_read_b128 v[238:241], v26 offset:1024
	ds_read_b128 v[242:245], v26 offset:2048
	ds_read_b128 v[246:249], v26 offset:3072
	s_add_u32 s20, s44, 0x8000
	s_addc_u32 s21, s45, 0
	s_mov_b32 m0, s60
	v_lshl_add_u64 v[90:91], s[20:21], 0, v[130:131]
	ds_read_b128 v[26:29], v143 offset:32768
	ds_read_b128 v[30:33], v143 offset:33792
	ds_read_b128 v[58:61], v143 offset:34816
	ds_read_b128 v[250:253], v143 offset:35840
	ds_read_b128 v[176:179], v143 offset:36864
	ds_read_b128 v[186:189], v143 offset:37888
	ds_read_b128 v[198:201], v143 offset:38912
	ds_read_b128 v[218:221], v143 offset:39936
	global_load_lds_dwordx4 v[90:91], off
	v_lshl_add_u64 v[90:91], s[20:21], 0, v[132:133]
	s_mov_b32 m0, s61
	s_nop 0
	global_load_lds_dwordx4 v[90:91], off
	s_waitcnt vmcnt(8)
	s_waitcnt lgkmcnt(0)
	s_barrier
	s_waitcnt lgkmcnt(0)
	v_mfma_f32_16x16x32_bf16 v[66:69], v[10:13], v[26:29], v[66:69]
	v_mfma_f32_16x16x32_bf16 v[126:129], v[14:17], v[30:33], v[66:69]
	v_mfma_f32_16x16x32_bf16 v[66:69], v[18:21], v[26:29], v[70:73]
	v_mfma_f32_16x16x32_bf16 v[122:125], v[22:25], v[30:33], v[66:69]
	v_mfma_f32_16x16x32_bf16 v[66:69], v[10:13], v[58:61], v[74:77]
	v_mfma_f32_16x16x32_bf16 v[110:113], v[14:17], v[250:253], v[66:69]
	v_mfma_f32_16x16x32_bf16 v[66:69], v[18:21], v[58:61], v[78:81]
	v_mfma_f32_16x16x32_bf16 v[106:109], v[22:25], v[250:253], v[66:69]
	v_mfma_f32_16x16x32_bf16 v[66:69], v[10:13], v[176:179], v[82:85]
	v_mfma_f32_16x16x32_bf16 v[94:97], v[14:17], v[186:189], v[66:69]
	v_mfma_f32_16x16x32_bf16 v[66:69], v[18:21], v[176:179], v[86:89]
	v_mfma_f32_16x16x32_bf16 v[90:93], v[22:25], v[186:189], v[66:69]
	v_mfma_f32_16x16x32_bf16 v[66:69], v[10:13], v[198:201], v[98:101]
	v_mfma_f32_16x16x32_bf16 v[74:77], v[14:17], v[218:221], v[66:69]
	v_mfma_f32_16x16x32_bf16 v[66:69], v[18:21], v[198:201], v[102:105]
	v_mfma_f32_16x16x32_bf16 v[66:69], v[22:25], v[218:221], v[66:69]
	v_mfma_f32_16x16x32_bf16 v[70:73], v[234:237], v[26:29], v[114:117]
	v_mfma_f32_16x16x32_bf16 v[26:29], v[242:245], v[26:29], v[34:37]
	v_mfma_f32_16x16x32_bf16 v[114:117], v[246:249], v[30:33], v[26:29]
	v_mfma_f32_16x16x32_bf16 v[26:29], v[234:237], v[58:61], v[38:41]
	v_mfma_f32_16x16x32_bf16 v[102:105], v[238:241], v[250:253], v[26:29]
	v_mfma_f32_16x16x32_bf16 v[26:29], v[242:245], v[58:61], v[42:45]
	v_mfma_f32_16x16x32_bf16 v[98:101], v[246:249], v[250:253], v[26:29]
	v_mfma_f32_16x16x32_bf16 v[26:29], v[234:237], v[176:179], v[46:49]
	v_mfma_f32_16x16x32_bf16 v[86:89], v[238:241], v[186:189], v[26:29]
	v_mfma_f32_16x16x32_bf16 v[26:29], v[242:245], v[176:179], v[50:53]
	v_mfma_f32_16x16x32_bf16 v[82:85], v[246:249], v[186:189], v[26:29]
	v_mfma_f32_16x16x32_bf16 v[26:29], v[234:237], v[198:201], v[54:57]
	v_mfma_f32_16x16x32_bf16 v[58:61], v[238:241], v[218:221], v[26:29]
	v_mfma_f32_16x16x32_bf16 v[26:29], v[242:245], v[198:201], v[62:65]
	v_mfma_f32_16x16x32_bf16 v[118:121], v[238:241], v[30:33], v[70:73]
	v_mfma_f32_16x16x32_bf16 v[50:53], v[246:249], v[218:221], v[26:29]
	s_barrier
	s_add_i32 s19, s19, s57
	s_nop 2
	v_lshl_add_u64 v[26:27], v[184:185], 0, s[24:25]
	s_mov_b32 m0, s19
	ds_read_b128 v[34:37], v143 offset:49152
	ds_read_b128 v[38:41], v143 offset:50176
	ds_read_b128 v[176:179], v143 offset:51200
	ds_read_b128 v[186:189], v143 offset:52224
	ds_read_b128 v[198:201], v143 offset:53248
	ds_read_b128 v[218:221], v143 offset:54272
	ds_read_b128 v[250:253], v143 offset:55296
	ds_read_b128 v[180:183], v143 offset:56320
	global_load_lds_dwordx4 v[26:27], off
	s_add_i32 m0, s19, 0x2000
	s_add_u32 s4, s4, 0x8080
	v_lshl_add_u64 v[26:27], v[190:191], 0, s[24:25]
	s_addc_u32 s5, s5, 0
	s_add_i32 s19, s37, s57
	global_load_lds_dwordx4 v[26:27], off
	v_lshl_add_u64 v[26:27], s[4:5], 0, v[0:1]
	s_mov_b32 m0, s19
	s_nop 0
	global_load_lds_dwordx4 v[26:27], off
	v_lshl_add_u64 v[26:27], s[4:5], 0, v[134:135]
	s_add_i32 m0, s19, 0x2000
	s_nop 0
	global_load_lds_dwordx4 v[26:27], off
	v_lshl_add_u64 v[26:27], v[192:193], 0, s[24:25]
	s_mov_b32 m0, s62
	s_nop 0
	global_load_lds_dwordx4 v[26:27], off
	v_lshl_add_u64 v[26:27], v[194:195], 0, s[24:25]
	s_mov_b32 m0, s63
	s_nop 0
	global_load_lds_dwordx4 v[26:27], off
	s_waitcnt vmcnt(8)
	s_waitcnt lgkmcnt(0)
	s_barrier
	s_waitcnt lgkmcnt(0)
	v_mfma_f32_16x16x32_bf16 v[26:29], v[10:13], v[34:37], v[136:139]
	v_mfma_f32_16x16x32_bf16 v[78:81], v[14:17], v[38:41], v[26:29]
	v_mfma_f32_16x16x32_bf16 v[26:29], v[18:21], v[34:37], v[144:147]
	v_mfma_f32_16x16x32_bf16 v[70:73], v[22:25], v[38:41], v[26:29]
	v_mfma_f32_16x16x32_bf16 v[26:29], v[10:13], v[176:179], v[148:151]
	v_mfma_f32_16x16x32_bf16 v[46:49], v[14:17], v[186:189], v[26:29]
	v_mfma_f32_16x16x32_bf16 v[26:29], v[18:21], v[176:179], v[152:155]
	v_mfma_f32_16x16x32_bf16 v[42:45], v[22:25], v[186:189], v[26:29]
	v_mfma_f32_16x16x32_bf16 v[26:29], v[10:13], v[198:201], v[156:159]
	v_mfma_f32_16x16x32_bf16 v[2:5], v[10:13], v[250:253], v[2:5]
	v_mfma_f32_16x16x32_bf16 v[30:33], v[14:17], v[218:221], v[26:29]
	v_mfma_f32_16x16x32_bf16 v[26:29], v[18:21], v[198:201], v[160:163]
	v_mfma_f32_16x16x32_bf16 v[14:17], v[14:17], v[180:183], v[2:5]
	v_mfma_f32_16x16x32_bf16 v[2:5], v[18:21], v[250:253], v[6:9]
	v_mfma_f32_16x16x32_bf16 v[26:29], v[22:25], v[218:221], v[26:29]
	v_mfma_f32_16x16x32_bf16 v[10:13], v[22:25], v[180:183], v[2:5]
	v_mfma_f32_16x16x32_bf16 v[2:5], v[234:237], v[34:37], v[164:167]
	v_mfma_f32_16x16x32_bf16 v[62:65], v[238:241], v[38:41], v[2:5]
	v_mfma_f32_16x16x32_bf16 v[2:5], v[242:245], v[34:37], v[168:171]
	v_mfma_f32_16x16x32_bf16 v[54:57], v[246:249], v[38:41], v[2:5]
	v_mfma_f32_16x16x32_bf16 v[2:5], v[234:237], v[176:179], v[172:175]
	v_mfma_f32_16x16x32_bf16 v[38:41], v[238:241], v[186:189], v[2:5]
	v_mfma_f32_16x16x32_bf16 v[2:5], v[242:245], v[176:179], v[202:205]
	v_mfma_f32_16x16x32_bf16 v[34:37], v[246:249], v[186:189], v[2:5]
	v_mfma_f32_16x16x32_bf16 v[2:5], v[234:237], v[198:201], v[206:209]
	v_mfma_f32_16x16x32_bf16 v[22:25], v[238:241], v[218:221], v[2:5]
	v_mfma_f32_16x16x32_bf16 v[2:5], v[242:245], v[198:201], v[222:225]
	v_mfma_f32_16x16x32_bf16 v[18:21], v[246:249], v[218:221], v[2:5]
	v_mfma_f32_16x16x32_bf16 v[2:5], v[234:237], v[250:253], v[226:229]
	v_mfma_f32_16x16x32_bf16 v[6:9], v[238:241], v[180:183], v[2:5]
	v_mfma_f32_16x16x32_bf16 v[2:5], v[242:245], v[250:253], v[230:233]
	v_mfma_f32_16x16x32_bf16 v[2:5], v[246:249], v[180:183], v[2:5]
	s_barrier
	s_andn2_b64 vcc, exec, s[12:13]
	s_cbranch_vccnz .LBB0_497
	s_barrier

.LBB0_551:
	s_ashr_i32 s19, s18, 31
	s_lshl_b64 s[20:21], s[18:19], 16
	s_add_u32 s48, s55, s20
	s_addc_u32 s49, s56, s21
	s_and_b64 s[4:5], s[4:5], exec
	s_cselect_b32 s5, s49, s53
	s_cselect_b32 s4, s48, s52
	s_add_i32 s19, 0, 0x10000
	s_add_i32 s37, 0, 0x14000
	v_add_u32_e32 v14, s19, v136
	v_add_u32_e32 v30, s37, v136
	ds_read_b128 v[2:5], v14
	ds_read_b128 v[6:9], v14 offset:1024
	ds_read_b128 v[10:13], v14 offset:2048
	ds_read_b128 v[14:17], v14 offset:3072
	ds_read_b128 v[18:21], v30
	ds_read_b128 v[22:25], v30 offset:1024
	ds_read_b128 v[26:29], v30 offset:2048
	ds_read_b128 v[30:33], v30 offset:3072
	s_add_u32 s20, s50, 0x8080
	s_addc_u32 s21, s51, 0
	v_lshl_add_u64 v[66:67], s[20:21], 0, v[130:131]
	s_add_i32 m0, s58, 0xc000
	ds_read_b128 v[34:37], v137
	ds_read_b128 v[38:41], v137 offset:1024
	ds_read_b128 v[42:45], v137 offset:2048
	ds_read_b128 v[46:49], v137 offset:3072
	ds_read_b128 v[50:53], v137 offset:4096
	ds_read_b128 v[54:57], v137 offset:5120
	ds_read_b128 v[58:61], v137 offset:6144
	ds_read_b128 v[62:65], v137 offset:7168
	global_load_lds_dwordx4 v[66:67], off
	v_lshl_add_u64 v[66:67], s[20:21], 0, v[132:133]
	s_add_i32 m0, s58, 0xe000
	s_nop 0
	global_load_lds_dwordx4 v[66:67], off
	s_waitcnt vmcnt(8)
	s_waitcnt lgkmcnt(0)
	s_barrier
	s_waitcnt lgkmcnt(0)
	v_mfma_f32_16x16x32_bf16 v[90:93], v[2:5], v[58:61], 0
	v_mfma_f32_16x16x32_bf16 v[66:69], v[2:5], v[34:37], 0
	v_mfma_f32_16x16x32_bf16 v[70:73], v[10:13], v[34:37], 0
	v_mfma_f32_16x16x32_bf16 v[74:77], v[2:5], v[42:45], 0
	v_mfma_f32_16x16x32_bf16 v[78:81], v[10:13], v[42:45], 0
	v_mfma_f32_16x16x32_bf16 v[82:85], v[2:5], v[50:53], 0
	v_mfma_f32_16x16x32_bf16 v[86:89], v[10:13], v[50:53], 0
	v_mfma_f32_16x16x32_bf16 v[94:97], v[6:9], v[62:65], v[90:93]
	v_mfma_f32_16x16x32_bf16 v[90:93], v[10:13], v[58:61], 0
	v_mfma_f32_16x16x32_bf16 v[66:69], v[6:9], v[38:41], v[66:69]
	v_mfma_f32_16x16x32_bf16 v[70:73], v[14:17], v[38:41], v[70:73]
	v_mfma_f32_16x16x32_bf16 v[74:77], v[6:9], v[46:49], v[74:77]
	v_mfma_f32_16x16x32_bf16 v[78:81], v[14:17], v[46:49], v[78:81]
	v_mfma_f32_16x16x32_bf16 v[82:85], v[6:9], v[54:57], v[82:85]
	v_mfma_f32_16x16x32_bf16 v[86:89], v[14:17], v[54:57], v[86:89]
	v_mfma_f32_16x16x32_bf16 v[102:105], v[14:17], v[62:65], v[90:93]
	v_mfma_f32_16x16x32_bf16 v[90:93], v[18:21], v[34:37], 0
	v_mfma_f32_16x16x32_bf16 v[34:37], v[26:29], v[34:37], 0
	v_mfma_f32_16x16x32_bf16 v[110:113], v[22:25], v[38:41], v[90:93]
	v_mfma_f32_16x16x32_bf16 v[34:37], v[30:33], v[38:41], v[34:37]
	v_mfma_f32_16x16x32_bf16 v[38:41], v[18:21], v[42:45], 0
	v_mfma_f32_16x16x32_bf16 v[42:45], v[26:29], v[42:45], 0
	v_mfma_f32_16x16x32_bf16 v[38:41], v[22:25], v[46:49], v[38:41]
	v_mfma_f32_16x16x32_bf16 v[42:45], v[30:33], v[46:49], v[42:45]
	v_mfma_f32_16x16x32_bf16 v[46:49], v[18:21], v[50:53], 0
	v_mfma_f32_16x16x32_bf16 v[50:53], v[26:29], v[50:53], 0
	v_mfma_f32_16x16x32_bf16 v[46:49], v[22:25], v[54:57], v[46:49]
	v_mfma_f32_16x16x32_bf16 v[54:57], v[30:33], v[54:57], v[50:53]
	v_mfma_f32_16x16x32_bf16 v[50:53], v[18:21], v[58:61], 0
	v_mfma_f32_16x16x32_bf16 v[142:145], v[22:25], v[62:65], v[50:53]
	v_mfma_f32_16x16x32_bf16 v[50:53], v[26:29], v[58:61], 0
	v_mfma_f32_16x16x32_bf16 v[146:149], v[30:33], v[62:65], v[50:53]
	s_barrier
	s_add_i32 s19, s19, s57
	v_lshl_add_u64 v[190:191], s[4:5], 0, v[0:1]
	s_mov_b32 m0, s19
	s_nop 1
	ds_read_b128 v[50:53], v137 offset:16384
	ds_read_b128 v[58:61], v137 offset:17408
	ds_read_b128 v[62:65], v137 offset:18432
	ds_read_b128 v[90:93], v137 offset:19456
	ds_read_b128 v[98:101], v137 offset:20480
	ds_read_b128 v[106:109], v137 offset:21504
	ds_read_b128 v[114:117], v137 offset:22528
	ds_read_b128 v[118:121], v137 offset:23552
	global_load_lds_dwordx4 v[190:191], off
	s_add_i32 m0, s19, 0x2000
	s_add_u32 s20, s4, 0x8000
	v_lshl_add_u64 v[192:193], s[4:5], 0, v[134:135]
	s_addc_u32 s21, s5, 0
	s_add_i32 s19, s37, s57
	global_load_lds_dwordx4 v[192:193], off
	v_lshl_add_u64 v[122:123], s[20:21], 0, v[0:1]
	s_mov_b32 m0, s19
	v_lshl_add_u64 v[210:211], s[44:45], 0, v[130:131]
	global_load_lds_dwordx4 v[122:123], off
	v_lshl_add_u64 v[122:123], s[20:21], 0, v[134:135]
	s_add_i32 m0, s19, 0x2000
	v_lshl_add_u64 v[214:215], s[44:45], 0, v[132:133]
	global_load_lds_dwordx4 v[122:123], off
	s_mov_b32 m0, s58
	s_nop 0
	global_load_lds_dwordx4 v[210:211], off
	s_mov_b32 m0, s59
	s_nop 0
	global_load_lds_dwordx4 v[214:215], off
	s_waitcnt vmcnt(8)
	s_waitcnt lgkmcnt(0)
	s_barrier
	s_waitcnt lgkmcnt(0)
	v_mfma_f32_16x16x32_bf16 v[122:125], v[2:5], v[50:53], 0
	v_mfma_f32_16x16x32_bf16 v[150:153], v[6:9], v[58:61], v[122:125]
	v_mfma_f32_16x16x32_bf16 v[122:125], v[10:13], v[50:53], 0
	v_mfma_f32_16x16x32_bf16 v[154:157], v[14:17], v[58:61], v[122:125]
	v_mfma_f32_16x16x32_bf16 v[122:125], v[2:5], v[62:65], 0
	v_mfma_f32_16x16x32_bf16 v[158:161], v[6:9], v[90:93], v[122:125]
	v_mfma_f32_16x16x32_bf16 v[122:125], v[10:13], v[62:65], 0
	v_mfma_f32_16x16x32_bf16 v[162:165], v[14:17], v[90:93], v[122:125]
	v_mfma_f32_16x16x32_bf16 v[122:125], v[2:5], v[98:101], 0
	v_mfma_f32_16x16x32_bf16 v[2:5], v[2:5], v[114:117], 0
	v_mfma_f32_16x16x32_bf16 v[166:169], v[6:9], v[106:109], v[122:125]
	v_mfma_f32_16x16x32_bf16 v[2:5], v[6:9], v[118:121], v[2:5]
	v_mfma_f32_16x16x32_bf16 v[6:9], v[10:13], v[114:117], 0
	v_mfma_f32_16x16x32_bf16 v[122:125], v[10:13], v[98:101], 0
	v_mfma_f32_16x16x32_bf16 v[6:9], v[14:17], v[118:121], v[6:9]
	v_mfma_f32_16x16x32_bf16 v[170:173], v[14:17], v[106:109], v[122:125]
	v_mfma_f32_16x16x32_bf16 v[10:13], v[18:21], v[50:53], 0
	v_mfma_f32_16x16x32_bf16 v[14:17], v[22:25], v[58:61], v[10:13]
	v_mfma_f32_16x16x32_bf16 v[10:13], v[26:29], v[50:53], 0
	v_mfma_f32_16x16x32_bf16 v[174:177], v[30:33], v[58:61], v[10:13]
	v_mfma_f32_16x16x32_bf16 v[10:13], v[18:21], v[62:65], 0
	v_mfma_f32_16x16x32_bf16 v[178:181], v[22:25], v[90:93], v[10:13]
	v_mfma_f32_16x16x32_bf16 v[10:13], v[26:29], v[62:65], 0
	v_mfma_f32_16x16x32_bf16 v[186:189], v[30:33], v[90:93], v[10:13]
	v_mfma_f32_16x16x32_bf16 v[10:13], v[18:21], v[98:101], 0
	v_mfma_f32_16x16x32_bf16 v[198:201], v[22:25], v[106:109], v[10:13]
	v_mfma_f32_16x16x32_bf16 v[10:13], v[26:29], v[98:101], 0
	v_mfma_f32_16x16x32_bf16 v[202:205], v[30:33], v[106:109], v[10:13]
	v_mfma_f32_16x16x32_bf16 v[10:13], v[18:21], v[114:117], 0
	v_mfma_f32_16x16x32_bf16 v[206:209], v[22:25], v[118:121], v[10:13]
	v_mfma_f32_16x16x32_bf16 v[10:13], v[26:29], v[114:117], 0
	v_mfma_f32_16x16x32_bf16 v[218:221], v[30:33], v[118:121], v[10:13]
	s_barrier
	s_add_i32 s19, 0, 0x18000
	v_add_u32_e32 v18, s19, v136
	s_add_i32 s37, 0, 0x1c000
	s_nop 1
	ds_read_b128 v[10:13], v18
	ds_read_b128 v[22:25], v18 offset:1024
	ds_read_b128 v[30:33], v18 offset:2048
	ds_read_b128 v[222:225], v18 offset:3072
	v_add_u32_e32 v18, s37, v136
	ds_read_b128 v[226:229], v18
	ds_read_b128 v[230:233], v18 offset:1024
	ds_read_b128 v[234:237], v18 offset:2048
	ds_read_b128 v[238:241], v18 offset:3072
	s_add_u32 s20, s44, 0x8000
	s_addc_u32 s21, s45, 0
	s_mov_b32 m0, s60
	v_lshl_add_u64 v[50:51], s[20:21], 0, v[130:131]
	ds_read_b128 v[18:21], v137 offset:32768
	ds_read_b128 v[26:29], v137 offset:33792
	ds_read_b128 v[62:65], v137 offset:34816
	ds_read_b128 v[242:245], v137 offset:35840
	ds_read_b128 v[246:249], v137 offset:36864
	ds_read_b128 v[250:253], v137 offset:37888
	ds_read_b128 v[182:185], v137 offset:38912
	ds_read_b128 v[194:197], v137 offset:39936
	global_load_lds_dwordx4 v[50:51], off
	v_lshl_add_u64 v[50:51], s[20:21], 0, v[132:133]
	s_mov_b32 m0, s61
	s_nop 0
	global_load_lds_dwordx4 v[50:51], off
	s_waitcnt vmcnt(8)
	s_waitcnt lgkmcnt(0)
	s_barrier
	s_waitcnt lgkmcnt(0)
	v_mfma_f32_16x16x32_bf16 v[50:53], v[10:13], v[18:21], v[66:69]
	v_mfma_f32_16x16x32_bf16 v[126:129], v[22:25], v[26:29], v[50:53]
	v_mfma_f32_16x16x32_bf16 v[50:53], v[30:33], v[18:21], v[70:73]
	v_mfma_f32_16x16x32_bf16 v[122:125], v[222:225], v[26:29], v[50:53]
	v_mfma_f32_16x16x32_bf16 v[50:53], v[10:13], v[62:65], v[74:77]
	v_mfma_f32_16x16x32_bf16 v[106:109], v[22:25], v[242:245], v[50:53]
	v_mfma_f32_16x16x32_bf16 v[50:53], v[30:33], v[62:65], v[78:81]
	v_mfma_f32_16x16x32_bf16 v[98:101], v[222:225], v[242:245], v[50:53]
	v_mfma_f32_16x16x32_bf16 v[50:53], v[10:13], v[246:249], v[82:85]
	v_mfma_f32_16x16x32_bf16 v[90:93], v[22:25], v[250:253], v[50:53]
	v_mfma_f32_16x16x32_bf16 v[50:53], v[30:33], v[246:249], v[86:89]
	v_mfma_f32_16x16x32_bf16 v[78:81], v[222:225], v[250:253], v[50:53]
	v_mfma_f32_16x16x32_bf16 v[50:53], v[10:13], v[182:185], v[94:97]
	v_mfma_f32_16x16x32_bf16 v[58:61], v[22:25], v[194:197], v[50:53]
	v_mfma_f32_16x16x32_bf16 v[50:53], v[30:33], v[182:185], v[102:105]
	v_mfma_f32_16x16x32_bf16 v[50:53], v[222:225], v[194:197], v[50:53]
	v_mfma_f32_16x16x32_bf16 v[66:69], v[226:229], v[18:21], v[110:113]
	v_mfma_f32_16x16x32_bf16 v[18:21], v[234:237], v[18:21], v[34:37]
	v_mfma_f32_16x16x32_bf16 v[114:117], v[238:241], v[26:29], v[18:21]
	v_mfma_f32_16x16x32_bf16 v[18:21], v[226:229], v[62:65], v[38:41]
	v_mfma_f32_16x16x32_bf16 v[110:113], v[230:233], v[242:245], v[18:21]
	v_mfma_f32_16x16x32_bf16 v[18:21], v[234:237], v[62:65], v[42:45]
	v_mfma_f32_16x16x32_bf16 v[102:105], v[238:241], v[242:245], v[18:21]
	v_mfma_f32_16x16x32_bf16 v[18:21], v[226:229], v[246:249], v[46:49]
	v_mfma_f32_16x16x32_bf16 v[94:97], v[230:233], v[250:253], v[18:21]
	v_mfma_f32_16x16x32_bf16 v[18:21], v[234:237], v[246:249], v[54:57]
	v_mfma_f32_16x16x32_bf16 v[82:85], v[238:241], v[250:253], v[18:21]
	v_mfma_f32_16x16x32_bf16 v[18:21], v[226:229], v[182:185], v[142:145]
	v_mfma_f32_16x16x32_bf16 v[62:65], v[230:233], v[194:197], v[18:21]
	v_mfma_f32_16x16x32_bf16 v[18:21], v[234:237], v[182:185], v[146:149]
	v_mfma_f32_16x16x32_bf16 v[118:121], v[230:233], v[26:29], v[66:69]
	v_mfma_f32_16x16x32_bf16 v[54:57], v[238:241], v[194:197], v[18:21]
	s_barrier
	s_add_i32 s19, s19, s57
	s_nop 2
	v_lshl_add_u64 v[18:19], v[190:191], 0, s[24:25]
	s_mov_b32 m0, s19
	ds_read_b128 v[38:41], v137 offset:49152
	ds_read_b128 v[46:49], v137 offset:50176
	ds_read_b128 v[142:145], v137 offset:51200
	ds_read_b128 v[146:149], v137 offset:52224
	ds_read_b128 v[182:185], v137 offset:53248
	ds_read_b128 v[194:197], v137 offset:54272
	ds_read_b128 v[242:245], v137 offset:55296
	ds_read_b128 v[246:249], v137 offset:56320
	global_load_lds_dwordx4 v[18:19], off
	s_add_i32 m0, s19, 0x2000
	s_add_u32 s4, s4, 0x8080
	v_lshl_add_u64 v[18:19], v[192:193], 0, s[24:25]
	s_addc_u32 s5, s5, 0
	s_add_i32 s19, s37, s57
	global_load_lds_dwordx4 v[18:19], off
	v_lshl_add_u64 v[18:19], s[4:5], 0, v[0:1]
	s_mov_b32 m0, s19
	s_nop 0
	global_load_lds_dwordx4 v[18:19], off
	v_lshl_add_u64 v[18:19], s[4:5], 0, v[134:135]
	s_add_i32 m0, s19, 0x2000
	s_nop 0
	global_load_lds_dwordx4 v[18:19], off
	v_lshl_add_u64 v[18:19], v[210:211], 0, s[24:25]
	s_mov_b32 m0, s66
	s_nop 0
	global_load_lds_dwordx4 v[18:19], off
	v_lshl_add_u64 v[18:19], v[214:215], 0, s[24:25]
	s_mov_b32 m0, s67
	s_nop 0
	global_load_lds_dwordx4 v[18:19], off
	s_waitcnt vmcnt(8)
	s_waitcnt lgkmcnt(0)
	s_barrier
	s_waitcnt lgkmcnt(0)
	v_mfma_f32_16x16x32_bf16 v[18:21], v[10:13], v[38:41], v[150:153]
	v_mfma_f32_16x16x32_bf16 v[86:89], v[22:25], v[46:49], v[18:21]
	v_mfma_f32_16x16x32_bf16 v[18:21], v[30:33], v[38:41], v[154:157]
	v_mfma_f32_16x16x32_bf16 v[74:77], v[222:225], v[46:49], v[18:21]
	v_mfma_f32_16x16x32_bf16 v[18:21], v[10:13], v[142:145], v[158:161]
	v_mfma_f32_16x16x32_bf16 v[42:45], v[22:25], v[146:149], v[18:21]
	v_mfma_f32_16x16x32_bf16 v[18:21], v[30:33], v[142:145], v[162:165]
	v_mfma_f32_16x16x32_bf16 v[34:37], v[222:225], v[146:149], v[18:21]
	v_mfma_f32_16x16x32_bf16 v[18:21], v[10:13], v[182:185], v[166:169]
	v_mfma_f32_16x16x32_bf16 v[2:5], v[10:13], v[242:245], v[2:5]
	v_mfma_f32_16x16x32_bf16 v[26:29], v[22:25], v[194:197], v[18:21]
	v_mfma_f32_16x16x32_bf16 v[18:21], v[30:33], v[182:185], v[170:173]
	v_mfma_f32_16x16x32_bf16 v[10:13], v[22:25], v[246:249], v[2:5]
	v_mfma_f32_16x16x32_bf16 v[2:5], v[30:33], v[242:245], v[6:9]
	v_mfma_f32_16x16x32_bf16 v[18:21], v[222:225], v[194:197], v[18:21]
	v_mfma_f32_16x16x32_bf16 v[2:5], v[222:225], v[246:249], v[2:5]
	v_mfma_f32_16x16x32_bf16 v[6:9], v[226:229], v[38:41], v[14:17]
	v_mfma_f32_16x16x32_bf16 v[70:73], v[230:233], v[46:49], v[6:9]
	v_mfma_f32_16x16x32_bf16 v[6:9], v[234:237], v[38:41], v[174:177]
	v_mfma_f32_16x16x32_bf16 v[66:69], v[238:241], v[46:49], v[6:9]
	v_mfma_f32_16x16x32_bf16 v[6:9], v[226:229], v[142:145], v[178:181]
	v_mfma_f32_16x16x32_bf16 v[46:49], v[230:233], v[146:149], v[6:9]
	v_mfma_f32_16x16x32_bf16 v[6:9], v[234:237], v[142:145], v[186:189]
	v_mfma_f32_16x16x32_bf16 v[38:41], v[238:241], v[146:149], v[6:9]
	v_mfma_f32_16x16x32_bf16 v[6:9], v[226:229], v[182:185], v[198:201]
	v_mfma_f32_16x16x32_bf16 v[30:33], v[230:233], v[194:197], v[6:9]
	v_mfma_f32_16x16x32_bf16 v[6:9], v[234:237], v[182:185], v[202:205]
	v_mfma_f32_16x16x32_bf16 v[22:25], v[238:241], v[194:197], v[6:9]
	v_mfma_f32_16x16x32_bf16 v[6:9], v[226:229], v[242:245], v[206:209]
	v_mfma_f32_16x16x32_bf16 v[14:17], v[230:233], v[246:249], v[6:9]
	v_mfma_f32_16x16x32_bf16 v[6:9], v[234:237], v[242:245], v[218:221]
	v_mfma_f32_16x16x32_bf16 v[6:9], v[238:241], v[246:249], v[6:9]
	s_barrier
	s_andn2_b64 vcc, exec, s[8:9]
	s_cbranch_vccnz .LBB0_553
	s_barrier

.LBB0_571:
	s_ashr_i32 s55, s54, 31
	s_lshl_b64 s[20:21], s[54:55], 16
	s_add_u32 s58, s69, s20
	s_addc_u32 s59, s70, s21
	s_and_b64 s[6:7], s[6:7], exec
	s_cselect_b32 s7, s59, s61
	s_cselect_b32 s6, s58, s60
	s_add_i32 s9, 0, 0x10000
	s_add_i32 s37, 0, 0x14000
	v_add_u32_e32 v14, s9, v160
	v_add_u32_e32 v30, s37, v160
	ds_read_b128 v[2:5], v14
	ds_read_b128 v[6:9], v14 offset:1024
	ds_read_b128 v[10:13], v14 offset:2048
	ds_read_b128 v[14:17], v14 offset:3072
	ds_read_b128 v[18:21], v30
	ds_read_b128 v[22:25], v30 offset:1024
	ds_read_b128 v[26:29], v30 offset:2048
	ds_read_b128 v[30:33], v30 offset:3072
	s_add_u32 s20, s62, 0x10080
	s_addc_u32 s21, s63, 0
	v_lshl_add_u64 v[66:67], s[20:21], 0, v[138:139]
	s_add_i32 m0, s71, 0xc000
	ds_read_b128 v[34:37], v161
	ds_read_b128 v[38:41], v161 offset:1024
	ds_read_b128 v[42:45], v161 offset:2048
	ds_read_b128 v[46:49], v161 offset:3072
	ds_read_b128 v[50:53], v161 offset:4096
	ds_read_b128 v[54:57], v161 offset:5120
	ds_read_b128 v[58:61], v161 offset:6144
	ds_read_b128 v[62:65], v161 offset:7168
	global_load_lds_dwordx4 v[66:67], off
	v_lshl_add_u64 v[66:67], s[20:21], 0, v[140:141]
	s_add_i32 m0, s71, 0xe000
	s_nop 0
	global_load_lds_dwordx4 v[66:67], off
	s_waitcnt vmcnt(8)
	s_waitcnt lgkmcnt(0)
	s_barrier
	s_waitcnt lgkmcnt(0)
	v_mfma_f32_16x16x32_bf16 v[66:69], v[2:5], v[34:37], 0
	v_mfma_f32_16x16x32_bf16 v[70:73], v[10:13], v[34:37], 0
	v_mfma_f32_16x16x32_bf16 v[74:77], v[2:5], v[42:45], 0
	v_mfma_f32_16x16x32_bf16 v[78:81], v[10:13], v[42:45], 0
	v_mfma_f32_16x16x32_bf16 v[82:85], v[2:5], v[50:53], 0
	v_mfma_f32_16x16x32_bf16 v[86:89], v[10:13], v[50:53], 0
	v_mfma_f32_16x16x32_bf16 v[90:93], v[2:5], v[58:61], 0
	v_mfma_f32_16x16x32_bf16 v[94:97], v[10:13], v[58:61], 0
	v_mfma_f32_16x16x32_bf16 v[66:69], v[6:9], v[38:41], v[66:69]
	v_mfma_f32_16x16x32_bf16 v[70:73], v[14:17], v[38:41], v[70:73]
	v_mfma_f32_16x16x32_bf16 v[74:77], v[6:9], v[46:49], v[74:77]
	v_mfma_f32_16x16x32_bf16 v[78:81], v[14:17], v[46:49], v[78:81]
	v_mfma_f32_16x16x32_bf16 v[82:85], v[6:9], v[54:57], v[82:85]
	v_mfma_f32_16x16x32_bf16 v[86:89], v[14:17], v[54:57], v[86:89]
	v_mfma_f32_16x16x32_bf16 v[90:93], v[6:9], v[62:65], v[90:93]
	v_mfma_f32_16x16x32_bf16 v[94:97], v[14:17], v[62:65], v[94:97]
	v_mfma_f32_16x16x32_bf16 v[98:101], v[18:21], v[34:37], 0
	v_mfma_f32_16x16x32_bf16 v[34:37], v[26:29], v[34:37], 0
	v_mfma_f32_16x16x32_bf16 v[98:101], v[22:25], v[38:41], v[98:101]
	v_mfma_f32_16x16x32_bf16 v[34:37], v[30:33], v[38:41], v[34:37]
	v_mfma_f32_16x16x32_bf16 v[38:41], v[18:21], v[42:45], 0
	v_mfma_f32_16x16x32_bf16 v[42:45], v[26:29], v[42:45], 0
	v_mfma_f32_16x16x32_bf16 v[38:41], v[22:25], v[46:49], v[38:41]
	v_mfma_f32_16x16x32_bf16 v[42:45], v[30:33], v[46:49], v[42:45]
	v_mfma_f32_16x16x32_bf16 v[46:49], v[18:21], v[50:53], 0
	v_mfma_f32_16x16x32_bf16 v[50:53], v[26:29], v[50:53], 0
	v_mfma_f32_16x16x32_bf16 v[46:49], v[22:25], v[54:57], v[46:49]
	v_mfma_f32_16x16x32_bf16 v[50:53], v[30:33], v[54:57], v[50:53]
	v_mfma_f32_16x16x32_bf16 v[54:57], v[18:21], v[58:61], 0
	v_mfma_f32_16x16x32_bf16 v[58:61], v[26:29], v[58:61], 0
	v_mfma_f32_16x16x32_bf16 v[54:57], v[22:25], v[62:65], v[54:57]
	v_mfma_f32_16x16x32_bf16 v[102:105], v[30:33], v[62:65], v[58:61]
	s_barrier
	s_add_i32 s9, s9, s66
	v_lshl_add_u64 v[156:157], s[6:7], 0, v[0:1]
	s_mov_b32 m0, s9
	s_nop 0
	ds_read_b128 v[58:61], v161 offset:16384
	ds_read_b128 v[62:65], v161 offset:17408
	ds_read_b128 v[106:109], v161 offset:18432
	ds_read_b128 v[110:113], v161 offset:19456
	ds_read_b128 v[114:117], v161 offset:20480
	ds_read_b128 v[118:121], v161 offset:21504
	ds_read_b128 v[122:125], v161 offset:22528
	ds_read_b128 v[126:129], v161 offset:23552
	global_load_lds_dwordx4 v[156:157], off
	s_add_i32 m0, s9, 0x2000
	s_add_u32 s20, s6, 0x8000
	v_lshl_add_u64 v[210:211], s[6:7], 0, v[142:143]
	s_addc_u32 s21, s7, 0
	s_add_i32 s9, s37, s66
	global_load_lds_dwordx4 v[210:211], off
	v_lshl_add_u64 v[130:131], s[20:21], 0, v[0:1]
	s_mov_b32 m0, s9
	v_lshl_add_u64 v[214:215], s[56:57], 0, v[138:139]
	global_load_lds_dwordx4 v[130:131], off
	v_lshl_add_u64 v[130:131], s[20:21], 0, v[142:143]
	s_add_i32 m0, s9, 0x2000
	v_lshl_add_u64 v[216:217], s[56:57], 0, v[140:141]
	global_load_lds_dwordx4 v[130:131], off
	s_mov_b32 m0, s71
	s_nop 0
	global_load_lds_dwordx4 v[214:215], off
	s_mov_b32 m0, s72
	s_nop 0
	global_load_lds_dwordx4 v[216:217], off
	s_waitcnt vmcnt(8)
	s_waitcnt lgkmcnt(0)
	s_barrier
	s_waitcnt lgkmcnt(0)
	v_mfma_f32_16x16x32_bf16 v[130:133], v[2:5], v[58:61], 0
	v_mfma_f32_16x16x32_bf16 v[144:147], v[6:9], v[62:65], v[130:133]
	v_mfma_f32_16x16x32_bf16 v[130:133], v[10:13], v[58:61], 0
	v_mfma_f32_16x16x32_bf16 v[148:151], v[14:17], v[62:65], v[130:133]
	v_mfma_f32_16x16x32_bf16 v[130:133], v[2:5], v[106:109], 0
	v_mfma_f32_16x16x32_bf16 v[152:155], v[6:9], v[110:113], v[130:133]
	v_mfma_f32_16x16x32_bf16 v[130:133], v[10:13], v[106:109], 0
	v_mfma_f32_16x16x32_bf16 v[162:165], v[14:17], v[110:113], v[130:133]
	v_mfma_f32_16x16x32_bf16 v[130:133], v[2:5], v[114:117], 0
	v_mfma_f32_16x16x32_bf16 v[2:5], v[2:5], v[122:125], 0
	v_mfma_f32_16x16x32_bf16 v[166:169], v[6:9], v[118:121], v[130:133]
	v_mfma_f32_16x16x32_bf16 v[130:133], v[10:13], v[114:117], 0
	v_mfma_f32_16x16x32_bf16 v[174:177], v[6:9], v[126:129], v[2:5]
	v_mfma_f32_16x16x32_bf16 v[2:5], v[10:13], v[122:125], 0
	v_mfma_f32_16x16x32_bf16 v[170:173], v[14:17], v[118:121], v[130:133]
	v_mfma_f32_16x16x32_bf16 v[10:13], v[14:17], v[126:129], v[2:5]
	v_mfma_f32_16x16x32_bf16 v[2:5], v[18:21], v[58:61], 0
	v_mfma_f32_16x16x32_bf16 v[14:17], v[22:25], v[62:65], v[2:5]
	v_mfma_f32_16x16x32_bf16 v[2:5], v[26:29], v[58:61], 0
	v_mfma_f32_16x16x32_bf16 v[178:181], v[30:33], v[62:65], v[2:5]
	v_mfma_f32_16x16x32_bf16 v[2:5], v[18:21], v[106:109], 0
	v_mfma_f32_16x16x32_bf16 v[182:185], v[22:25], v[110:113], v[2:5]
	v_mfma_f32_16x16x32_bf16 v[2:5], v[26:29], v[106:109], 0
	v_mfma_f32_16x16x32_bf16 v[186:189], v[30:33], v[110:113], v[2:5]
	v_mfma_f32_16x16x32_bf16 v[2:5], v[18:21], v[114:117], 0
	v_mfma_f32_16x16x32_bf16 v[194:197], v[22:25], v[118:121], v[2:5]
	v_mfma_f32_16x16x32_bf16 v[2:5], v[26:29], v[114:117], 0
	v_mfma_f32_16x16x32_bf16 v[198:201], v[30:33], v[118:121], v[2:5]
	v_mfma_f32_16x16x32_bf16 v[2:5], v[18:21], v[122:125], 0
	v_mfma_f32_16x16x32_bf16 v[18:21], v[22:25], v[126:129], v[2:5]
	v_mfma_f32_16x16x32_bf16 v[2:5], v[26:29], v[122:125], 0
	v_mfma_f32_16x16x32_bf16 v[202:205], v[30:33], v[126:129], v[2:5]
	s_barrier
	s_add_i32 s9, 0, 0x18000
	s_nop 3
	v_add_u32_e32 v2, s9, v160
	s_add_i32 s37, 0, 0x1c000
	ds_read_b128 v[22:25], v2
	ds_read_b128 v[26:29], v2 offset:1024
	ds_read_b128 v[30:33], v2 offset:2048
	ds_read_b128 v[206:209], v2 offset:3072
	v_add_u32_e32 v2, s37, v160
	ds_read_b128 v[218:221], v2
	ds_read_b128 v[222:225], v2 offset:1024
	ds_read_b128 v[226:229], v2 offset:2048
	ds_read_b128 v[230:233], v2 offset:3072
	s_add_u32 s20, s56, 0x10000
	s_addc_u32 s21, s57, 0
	s_mov_b32 m0, s73
	v_lshl_add_u64 v[2:3], s[20:21], 0, v[138:139]
	ds_read_b128 v[58:61], v161 offset:32768
	ds_read_b128 v[62:65], v161 offset:33792
	ds_read_b128 v[106:109], v161 offset:34816
	ds_read_b128 v[110:113], v161 offset:35840
	ds_read_b128 v[234:237], v161 offset:36864
	ds_read_b128 v[238:241], v161 offset:37888
	ds_read_b128 v[242:245], v161 offset:38912
	ds_read_b128 v[246:249], v161 offset:39936
	global_load_lds_dwordx4 v[2:3], off
	v_lshl_add_u64 v[2:3], s[20:21], 0, v[140:141]
	s_mov_b32 m0, s92
	s_nop 0
	global_load_lds_dwordx4 v[2:3], off
	s_waitcnt vmcnt(8)
	s_waitcnt lgkmcnt(0)
	s_barrier
	s_waitcnt lgkmcnt(0)
	v_mfma_f32_16x16x32_bf16 v[2:5], v[22:25], v[58:61], v[66:69]
	v_mfma_f32_16x16x32_bf16 v[66:69], v[22:25], v[106:109], v[74:77]
	v_mfma_f32_16x16x32_bf16 v[134:137], v[26:29], v[110:113], v[66:69]
	v_mfma_f32_16x16x32_bf16 v[66:69], v[30:33], v[106:109], v[78:81]
	v_mfma_f32_16x16x32_bf16 v[130:133], v[206:209], v[110:113], v[66:69]
	v_mfma_f32_16x16x32_bf16 v[66:69], v[22:25], v[234:237], v[82:85]
	v_mfma_f32_16x16x32_bf16 v[126:129], v[26:29], v[238:241], v[66:69]
	v_mfma_f32_16x16x32_bf16 v[66:69], v[30:33], v[234:237], v[86:89]
	v_mfma_f32_16x16x32_bf16 v[122:125], v[206:209], v[238:241], v[66:69]
	v_mfma_f32_16x16x32_bf16 v[66:69], v[22:25], v[242:245], v[90:93]
	v_mfma_f32_16x16x32_bf16 v[6:9], v[26:29], v[62:65], v[2:5]
	v_mfma_f32_16x16x32_bf16 v[2:5], v[30:33], v[58:61], v[70:73]
	v_mfma_f32_16x16x32_bf16 v[118:121], v[26:29], v[246:249], v[66:69]
	v_mfma_f32_16x16x32_bf16 v[66:69], v[30:33], v[242:245], v[94:97]
	v_mfma_f32_16x16x32_bf16 v[2:5], v[206:209], v[62:65], v[2:5]
	v_mfma_f32_16x16x32_bf16 v[114:117], v[206:209], v[246:249], v[66:69]
	v_mfma_f32_16x16x32_bf16 v[34:37], v[226:229], v[58:61], v[34:37]
	v_mfma_f32_16x16x32_bf16 v[74:77], v[230:233], v[62:65], v[34:37]
	v_mfma_f32_16x16x32_bf16 v[34:37], v[218:221], v[106:109], v[38:41]
	v_mfma_f32_16x16x32_bf16 v[66:69], v[218:221], v[58:61], v[98:101]
	v_mfma_f32_16x16x32_bf16 v[70:73], v[222:225], v[110:113], v[34:37]
	v_mfma_f32_16x16x32_bf16 v[34:37], v[226:229], v[106:109], v[42:45]
	v_mfma_f32_16x16x32_bf16 v[78:81], v[222:225], v[62:65], v[66:69]
	v_mfma_f32_16x16x32_bf16 v[66:69], v[230:233], v[110:113], v[34:37]
	v_mfma_f32_16x16x32_bf16 v[34:37], v[218:221], v[234:237], v[46:49]
	v_mfma_f32_16x16x32_bf16 v[62:65], v[222:225], v[238:241], v[34:37]
	v_mfma_f32_16x16x32_bf16 v[34:37], v[226:229], v[234:237], v[50:53]
	v_mfma_f32_16x16x32_bf16 v[58:61], v[230:233], v[238:241], v[34:37]
	v_mfma_f32_16x16x32_bf16 v[34:37], v[218:221], v[242:245], v[54:57]
	v_mfma_f32_16x16x32_bf16 v[54:57], v[222:225], v[246:249], v[34:37]
	v_mfma_f32_16x16x32_bf16 v[34:37], v[226:229], v[242:245], v[102:105]
	v_mfma_f32_16x16x32_bf16 v[50:53], v[230:233], v[246:249], v[34:37]
	s_barrier
	s_add_i32 s9, s9, s66
	v_lshl_add_u64 v[42:43], v[156:157], 0, s[24:25]
	s_mov_b32 m0, s9
	s_nop 1
	ds_read_b128 v[34:37], v161 offset:49152
	ds_read_b128 v[38:41], v161 offset:50176
	ds_read_b128 v[234:237], v161 offset:51200
	ds_read_b128 v[238:241], v161 offset:52224
	ds_read_b128 v[242:245], v161 offset:53248
	ds_read_b128 v[246:249], v161 offset:54272
	ds_read_b128 v[250:253], v161 offset:55296
	ds_read_b128 v[190:193], v161 offset:56320
	global_load_lds_dwordx4 v[42:43], off
	s_add_i32 m0, s9, 0x2000
	s_add_u32 s6, s6, 0x8080
	v_lshl_add_u64 v[42:43], v[210:211], 0, s[24:25]
	s_addc_u32 s7, s7, 0
	s_add_i32 s9, s37, s66
	global_load_lds_dwordx4 v[42:43], off
	v_lshl_add_u64 v[42:43], s[6:7], 0, v[0:1]
	s_mov_b32 m0, s9
	s_nop 0
	global_load_lds_dwordx4 v[42:43], off
	v_lshl_add_u64 v[42:43], s[6:7], 0, v[142:143]
	s_add_i32 m0, s9, 0x2000
	s_nop 0
	global_load_lds_dwordx4 v[42:43], off
	v_lshl_add_u64 v[42:43], v[214:215], 0, s[24:25]
	s_mov_b32 m0, s95
	s_nop 0
	global_load_lds_dwordx4 v[42:43], off
	v_lshl_add_u64 v[42:43], v[216:217], 0, s[24:25]
	s_mov_b32 m0, s96
	s_nop 0
	global_load_lds_dwordx4 v[42:43], off
	s_waitcnt vmcnt(8)
	s_waitcnt lgkmcnt(0)
	s_barrier
	s_waitcnt lgkmcnt(0)
	v_mfma_f32_16x16x32_bf16 v[42:45], v[22:25], v[34:37], v[144:147]
	v_mfma_f32_16x16x32_bf16 v[110:113], v[26:29], v[38:41], v[42:45]
	v_mfma_f32_16x16x32_bf16 v[42:45], v[30:33], v[34:37], v[148:151]
	v_mfma_f32_16x16x32_bf16 v[106:109], v[206:209], v[38:41], v[42:45]
	v_mfma_f32_16x16x32_bf16 v[42:45], v[22:25], v[234:237], v[152:155]
	v_mfma_f32_16x16x32_bf16 v[102:105], v[26:29], v[238:241], v[42:45]
	v_mfma_f32_16x16x32_bf16 v[42:45], v[30:33], v[234:237], v[162:165]
	v_mfma_f32_16x16x32_bf16 v[98:101], v[206:209], v[238:241], v[42:45]
	v_mfma_f32_16x16x32_bf16 v[42:45], v[22:25], v[242:245], v[166:169]
	v_mfma_f32_16x16x32_bf16 v[94:97], v[26:29], v[246:249], v[42:45]
	v_mfma_f32_16x16x32_bf16 v[42:45], v[30:33], v[242:245], v[170:173]
	v_mfma_f32_16x16x32_bf16 v[22:25], v[22:25], v[250:253], v[174:177]
	v_mfma_f32_16x16x32_bf16 v[10:13], v[30:33], v[250:253], v[10:13]
	v_mfma_f32_16x16x32_bf16 v[90:93], v[206:209], v[246:249], v[42:45]
	v_mfma_f32_16x16x32_bf16 v[86:89], v[26:29], v[190:193], v[22:25]
	v_mfma_f32_16x16x32_bf16 v[82:85], v[206:209], v[190:193], v[10:13]
	v_mfma_f32_16x16x32_bf16 v[10:13], v[218:221], v[34:37], v[14:17]
	v_mfma_f32_16x16x32_bf16 v[46:49], v[222:225], v[38:41], v[10:13]
	v_mfma_f32_16x16x32_bf16 v[10:13], v[226:229], v[34:37], v[178:181]
	v_mfma_f32_16x16x32_bf16 v[42:45], v[230:233], v[38:41], v[10:13]
	v_mfma_f32_16x16x32_bf16 v[10:13], v[218:221], v[234:237], v[182:185]
	v_mfma_f32_16x16x32_bf16 v[38:41], v[222:225], v[238:241], v[10:13]
	v_mfma_f32_16x16x32_bf16 v[10:13], v[226:229], v[234:237], v[186:189]
	v_mfma_f32_16x16x32_bf16 v[34:37], v[230:233], v[238:241], v[10:13]
	v_mfma_f32_16x16x32_bf16 v[10:13], v[218:221], v[242:245], v[194:197]
	v_mfma_f32_16x16x32_bf16 v[30:33], v[222:225], v[246:249], v[10:13]
	v_mfma_f32_16x16x32_bf16 v[10:13], v[226:229], v[242:245], v[198:201]
	v_mfma_f32_16x16x32_bf16 v[26:29], v[230:233], v[246:249], v[10:13]
	v_mfma_f32_16x16x32_bf16 v[10:13], v[218:221], v[250:253], v[18:21]
	v_mfma_f32_16x16x32_bf16 v[22:25], v[222:225], v[190:193], v[10:13]
	v_mfma_f32_16x16x32_bf16 v[10:13], v[226:229], v[250:253], v[202:205]
	v_mfma_f32_16x16x32_bf16 v[18:21], v[230:233], v[190:193], v[10:13]
	s_barrier
	s_andn2_b64 vcc, exec, s[50:51]
	s_cbranch_vccnz .LBB0_573
	s_barrier

.LBB0_1525:
	s_add_u32 s20, s6, 0xfffc0080
	s_addc_u32 s21, s7, -1
	s_add_i32 s37, 0, 0x10000
	s_cmp_eq_u32 s71, 12
	s_cselect_b32 s51, s19, s21
	s_cselect_b32 s50, s18, s20
	s_cselect_b32 s49, s17, s70
	s_cselect_b32 s48, s47, s69
	s_add_i32 s72, 0, 0x14000
	v_add_u32_e32 v156, s37, v145
	v_add_u32_e32 v172, s72, v145
	ds_read_b128 v[140:143], v156
	ds_read_b128 v[148:151], v156 offset:1024
	ds_read_b128 v[152:155], v156 offset:2048
	ds_read_b128 v[156:159], v156 offset:3072
	ds_read_b128 v[160:163], v172
	ds_read_b128 v[164:167], v172 offset:1024
	ds_read_b128 v[168:171], v172 offset:2048
	ds_read_b128 v[172:175], v172 offset:3072
	v_lshl_add_u64 v[208:209], s[6:7], 0, v[136:137]
	s_add_i32 m0, s58, 0xc000
	ds_read_b128 v[176:179], v147
	ds_read_b128 v[180:183], v147 offset:1024
	ds_read_b128 v[184:187], v147 offset:2048
	ds_read_b128 v[188:191], v147 offset:3072
	ds_read_b128 v[192:195], v147 offset:4096
	ds_read_b128 v[196:199], v147 offset:5120
	ds_read_b128 v[200:203], v147 offset:6144
	ds_read_b128 v[204:207], v147 offset:7168
	global_load_lds_dwordx4 v[208:209], off
	v_lshl_add_u64 v[208:209], s[6:7], 0, v[138:139]
	s_add_i32 m0, s58, 0xe000
	s_nop 0
	global_load_lds_dwordx4 v[208:209], off
	s_waitcnt vmcnt(8)
	s_waitcnt lgkmcnt(0)
	s_barrier
	s_waitcnt lgkmcnt(0)
	v_mfma_f32_16x16x32_bf16 v[126:129], v[140:143], v[176:179], v[126:129]
	v_mfma_f32_16x16x32_bf16 v[122:125], v[152:155], v[176:179], v[122:125]
	v_mfma_f32_16x16x32_bf16 v[114:117], v[140:143], v[184:187], v[114:117]
	v_mfma_f32_16x16x32_bf16 v[106:109], v[152:155], v[184:187], v[106:109]
	v_mfma_f32_16x16x32_bf16 v[98:101], v[140:143], v[192:195], v[98:101]
	v_mfma_f32_16x16x32_bf16 v[90:93], v[152:155], v[192:195], v[90:93]
	v_mfma_f32_16x16x32_bf16 v[82:85], v[140:143], v[200:203], v[82:85]
	v_mfma_f32_16x16x32_bf16 v[74:77], v[152:155], v[200:203], v[74:77]
	v_mfma_f32_16x16x32_bf16 v[126:129], v[148:151], v[180:183], v[126:129]
	v_mfma_f32_16x16x32_bf16 v[122:125], v[156:159], v[180:183], v[122:125]
	v_mfma_f32_16x16x32_bf16 v[114:117], v[148:151], v[188:191], v[114:117]
	v_mfma_f32_16x16x32_bf16 v[106:109], v[156:159], v[188:191], v[106:109]
	v_mfma_f32_16x16x32_bf16 v[98:101], v[148:151], v[196:199], v[98:101]
	v_mfma_f32_16x16x32_bf16 v[90:93], v[156:159], v[196:199], v[90:93]
	v_mfma_f32_16x16x32_bf16 v[82:85], v[148:151], v[204:207], v[82:85]
	v_mfma_f32_16x16x32_bf16 v[74:77], v[156:159], v[204:207], v[74:77]
	v_mfma_f32_16x16x32_bf16 v[118:121], v[160:163], v[176:179], v[118:121]
	v_mfma_f32_16x16x32_bf16 v[110:113], v[168:171], v[176:179], v[110:113]
	v_mfma_f32_16x16x32_bf16 v[102:105], v[160:163], v[184:187], v[102:105]
	v_mfma_f32_16x16x32_bf16 v[94:97], v[168:171], v[184:187], v[94:97]
	v_mfma_f32_16x16x32_bf16 v[86:89], v[160:163], v[192:195], v[86:89]
	v_mfma_f32_16x16x32_bf16 v[78:81], v[168:171], v[192:195], v[78:81]
	v_mfma_f32_16x16x32_bf16 v[70:73], v[160:163], v[200:203], v[70:73]
	v_mfma_f32_16x16x32_bf16 v[66:69], v[168:171], v[200:203], v[66:69]
	v_mfma_f32_16x16x32_bf16 v[118:121], v[164:167], v[180:183], v[118:121]
	v_mfma_f32_16x16x32_bf16 v[110:113], v[172:175], v[180:183], v[110:113]
	v_mfma_f32_16x16x32_bf16 v[102:105], v[164:167], v[188:191], v[102:105]
	v_mfma_f32_16x16x32_bf16 v[94:97], v[172:175], v[188:191], v[94:97]
	v_mfma_f32_16x16x32_bf16 v[86:89], v[164:167], v[196:199], v[86:89]
	v_mfma_f32_16x16x32_bf16 v[78:81], v[172:175], v[196:199], v[78:81]
	v_mfma_f32_16x16x32_bf16 v[70:73], v[164:167], v[204:207], v[70:73]
	v_mfma_f32_16x16x32_bf16 v[66:69], v[172:175], v[204:207], v[66:69]
	s_barrier
	s_add_i32 s20, s37, s57
	v_lshl_add_u64 v[208:209], s[48:49], 0, v[0:1]
	s_mov_b32 m0, s20
	ds_read_b128 v[176:179], v147 offset:16384
	ds_read_b128 v[180:183], v147 offset:17408
	ds_read_b128 v[184:187], v147 offset:18432
	ds_read_b128 v[188:191], v147 offset:19456
	ds_read_b128 v[192:195], v147 offset:20480
	ds_read_b128 v[196:199], v147 offset:21504
	ds_read_b128 v[200:203], v147 offset:22528
	ds_read_b128 v[204:207], v147 offset:23552
	global_load_lds_dwordx4 v[208:209], off
	s_add_i32 m0, s20, 0x2000
	s_add_u32 s20, s48, 0x40000
	v_lshl_add_u64 v[210:211], s[48:49], 0, v[134:135]
	s_addc_u32 s21, s49, 0
	s_add_i32 s37, s72, s57
	global_load_lds_dwordx4 v[210:211], off
	v_lshl_add_u64 v[214:215], s[20:21], 0, v[0:1]
	s_mov_b32 m0, s37
	v_lshl_add_u64 v[216:217], s[50:51], 0, v[132:133]
	global_load_lds_dwordx4 v[214:215], off
	v_lshl_add_u64 v[214:215], s[20:21], 0, v[134:135]
	s_add_i32 m0, s37, 0x2000
	s_nop 0
	global_load_lds_dwordx4 v[214:215], off
	v_lshl_add_u64 v[214:215], s[50:51], 0, v[130:131]
	s_mov_b32 m0, s58
	s_nop 0
	global_load_lds_dwordx4 v[214:215], off
	s_mov_b32 m0, s59
	s_nop 0
	global_load_lds_dwordx4 v[216:217], off
	s_waitcnt vmcnt(8)
	s_waitcnt lgkmcnt(0)
	s_barrier
	s_waitcnt lgkmcnt(0)
	v_mfma_f32_16x16x32_bf16 v[62:65], v[140:143], v[176:179], v[62:65]
	v_mfma_f32_16x16x32_bf16 v[58:61], v[152:155], v[176:179], v[58:61]
	v_mfma_f32_16x16x32_bf16 v[50:53], v[140:143], v[184:187], v[50:53]
	v_mfma_f32_16x16x32_bf16 v[42:45], v[152:155], v[184:187], v[42:45]
	v_mfma_f32_16x16x32_bf16 v[34:37], v[140:143], v[192:195], v[34:37]
	v_mfma_f32_16x16x32_bf16 v[26:29], v[152:155], v[192:195], v[26:29]
	v_mfma_f32_16x16x32_bf16 v[18:21], v[140:143], v[200:203], v[18:21]
	v_mfma_f32_16x16x32_bf16 v[10:13], v[152:155], v[200:203], v[10:13]
	v_mfma_f32_16x16x32_bf16 v[62:65], v[148:151], v[180:183], v[62:65]
	v_mfma_f32_16x16x32_bf16 v[58:61], v[156:159], v[180:183], v[58:61]
	v_mfma_f32_16x16x32_bf16 v[50:53], v[148:151], v[188:191], v[50:53]
	v_mfma_f32_16x16x32_bf16 v[42:45], v[156:159], v[188:191], v[42:45]
	v_mfma_f32_16x16x32_bf16 v[34:37], v[148:151], v[196:199], v[34:37]
	v_mfma_f32_16x16x32_bf16 v[26:29], v[156:159], v[196:199], v[26:29]
	v_mfma_f32_16x16x32_bf16 v[18:21], v[148:151], v[204:207], v[18:21]
	v_mfma_f32_16x16x32_bf16 v[10:13], v[156:159], v[204:207], v[10:13]
	v_mfma_f32_16x16x32_bf16 v[54:57], v[160:163], v[176:179], v[54:57]
	v_mfma_f32_16x16x32_bf16 v[46:49], v[168:171], v[176:179], v[46:49]
	v_mfma_f32_16x16x32_bf16 v[38:41], v[160:163], v[184:187], v[38:41]
	v_mfma_f32_16x16x32_bf16 v[30:33], v[168:171], v[184:187], v[30:33]
	v_mfma_f32_16x16x32_bf16 v[22:25], v[160:163], v[192:195], v[22:25]
	v_mfma_f32_16x16x32_bf16 v[14:17], v[168:171], v[192:195], v[14:17]
	v_mfma_f32_16x16x32_bf16 v[6:9], v[160:163], v[200:203], v[6:9]
	v_mfma_f32_16x16x32_bf16 v[2:5], v[168:171], v[200:203], v[2:5]
	v_mfma_f32_16x16x32_bf16 v[54:57], v[164:167], v[180:183], v[54:57]
	v_mfma_f32_16x16x32_bf16 v[46:49], v[172:175], v[180:183], v[46:49]
	v_mfma_f32_16x16x32_bf16 v[38:41], v[164:167], v[188:191], v[38:41]
	v_mfma_f32_16x16x32_bf16 v[30:33], v[172:175], v[188:191], v[30:33]
	v_mfma_f32_16x16x32_bf16 v[22:25], v[164:167], v[196:199], v[22:25]
	v_mfma_f32_16x16x32_bf16 v[14:17], v[172:175], v[196:199], v[14:17]
	v_mfma_f32_16x16x32_bf16 v[6:9], v[164:167], v[204:207], v[6:9]
	v_mfma_f32_16x16x32_bf16 v[2:5], v[172:175], v[204:207], v[2:5]
	s_barrier
	s_add_i32 s37, 0, 0x18000
	s_add_i32 s72, 0, 0x1c000
	v_add_u32_e32 v156, s37, v145
	v_add_u32_e32 v172, s72, v145
	ds_read_b128 v[140:143], v156
	ds_read_b128 v[148:151], v156 offset:1024
	ds_read_b128 v[152:155], v156 offset:2048
	ds_read_b128 v[156:159], v156 offset:3072
	ds_read_b128 v[160:163], v172
	ds_read_b128 v[164:167], v172 offset:1024
	ds_read_b128 v[168:171], v172 offset:2048
	ds_read_b128 v[172:175], v172 offset:3072
	s_add_u32 s20, s50, 0x40000
	s_addc_u32 s21, s51, 0
	s_mov_b32 m0, s60
	v_lshl_add_u64 v[218:219], s[20:21], 0, v[130:131]
	ds_read_b128 v[176:179], v147 offset:32768
	ds_read_b128 v[180:183], v147 offset:33792
	ds_read_b128 v[184:187], v147 offset:34816
	ds_read_b128 v[188:191], v147 offset:35840
	ds_read_b128 v[192:195], v147 offset:36864
	ds_read_b128 v[196:199], v147 offset:37888
	ds_read_b128 v[200:203], v147 offset:38912
	ds_read_b128 v[204:207], v147 offset:39936
	global_load_lds_dwordx4 v[218:219], off
	v_lshl_add_u64 v[218:219], s[20:21], 0, v[132:133]
	s_mov_b32 m0, s61
	s_nop 0
	global_load_lds_dwordx4 v[218:219], off
	s_waitcnt vmcnt(8)
	s_waitcnt lgkmcnt(0)
	s_barrier
	s_waitcnt lgkmcnt(0)
	v_mfma_f32_16x16x32_bf16 v[126:129], v[140:143], v[176:179], v[126:129]
	v_mfma_f32_16x16x32_bf16 v[122:125], v[152:155], v[176:179], v[122:125]
	v_mfma_f32_16x16x32_bf16 v[114:117], v[140:143], v[184:187], v[114:117]
	v_mfma_f32_16x16x32_bf16 v[106:109], v[152:155], v[184:187], v[106:109]
	v_mfma_f32_16x16x32_bf16 v[98:101], v[140:143], v[192:195], v[98:101]
	v_mfma_f32_16x16x32_bf16 v[90:93], v[152:155], v[192:195], v[90:93]
	v_mfma_f32_16x16x32_bf16 v[82:85], v[140:143], v[200:203], v[82:85]
	v_mfma_f32_16x16x32_bf16 v[74:77], v[152:155], v[200:203], v[74:77]
	v_mfma_f32_16x16x32_bf16 v[126:129], v[148:151], v[180:183], v[126:129]
	v_mfma_f32_16x16x32_bf16 v[122:125], v[156:159], v[180:183], v[122:125]
	v_mfma_f32_16x16x32_bf16 v[114:117], v[148:151], v[188:191], v[114:117]
	v_mfma_f32_16x16x32_bf16 v[106:109], v[156:159], v[188:191], v[106:109]
	v_mfma_f32_16x16x32_bf16 v[98:101], v[148:151], v[196:199], v[98:101]
	v_mfma_f32_16x16x32_bf16 v[90:93], v[156:159], v[196:199], v[90:93]
	v_mfma_f32_16x16x32_bf16 v[82:85], v[148:151], v[204:207], v[82:85]
	v_mfma_f32_16x16x32_bf16 v[74:77], v[156:159], v[204:207], v[74:77]
	v_mfma_f32_16x16x32_bf16 v[118:121], v[160:163], v[176:179], v[118:121]
	v_mfma_f32_16x16x32_bf16 v[110:113], v[168:171], v[176:179], v[110:113]
	v_mfma_f32_16x16x32_bf16 v[102:105], v[160:163], v[184:187], v[102:105]
	v_mfma_f32_16x16x32_bf16 v[94:97], v[168:171], v[184:187], v[94:97]
	v_mfma_f32_16x16x32_bf16 v[86:89], v[160:163], v[192:195], v[86:89]
	v_mfma_f32_16x16x32_bf16 v[78:81], v[168:171], v[192:195], v[78:81]
	v_mfma_f32_16x16x32_bf16 v[70:73], v[160:163], v[200:203], v[70:73]
	v_mfma_f32_16x16x32_bf16 v[66:69], v[168:171], v[200:203], v[66:69]
	v_mfma_f32_16x16x32_bf16 v[118:121], v[164:167], v[180:183], v[118:121]
	v_mfma_f32_16x16x32_bf16 v[110:113], v[172:175], v[180:183], v[110:113]
	v_mfma_f32_16x16x32_bf16 v[102:105], v[164:167], v[188:191], v[102:105]
	v_mfma_f32_16x16x32_bf16 v[94:97], v[172:175], v[188:191], v[94:97]
	v_mfma_f32_16x16x32_bf16 v[86:89], v[164:167], v[196:199], v[86:89]
	v_mfma_f32_16x16x32_bf16 v[78:81], v[172:175], v[196:199], v[78:81]
	v_mfma_f32_16x16x32_bf16 v[70:73], v[164:167], v[204:207], v[70:73]
	v_mfma_f32_16x16x32_bf16 v[66:69], v[172:175], v[204:207], v[66:69]
	s_barrier
	s_add_i32 s20, s37, s57
	v_lshl_add_u64 v[208:209], v[208:209], 0, s[24:25]
	s_mov_b32 m0, s20
	ds_read_b128 v[176:179], v147 offset:49152
	ds_read_b128 v[180:183], v147 offset:50176
	ds_read_b128 v[184:187], v147 offset:51200
	ds_read_b128 v[188:191], v147 offset:52224
	ds_read_b128 v[192:195], v147 offset:53248
	ds_read_b128 v[196:199], v147 offset:54272
	ds_read_b128 v[200:203], v147 offset:55296
	ds_read_b128 v[204:207], v147 offset:56320
	global_load_lds_dwordx4 v[208:209], off
	s_add_i32 m0, s20, 0x2000
	s_add_u32 s20, s48, 0x40080
	v_lshl_add_u64 v[208:209], v[210:211], 0, s[24:25]
	s_addc_u32 s21, s49, 0
	s_add_i32 s37, s72, s57
	global_load_lds_dwordx4 v[208:209], off
	v_lshl_add_u64 v[208:209], s[20:21], 0, v[0:1]
	s_mov_b32 m0, s37
	s_nop 0
	global_load_lds_dwordx4 v[208:209], off
	v_lshl_add_u64 v[208:209], s[20:21], 0, v[134:135]
	s_add_i32 m0, s37, 0x2000
	s_nop 0
	global_load_lds_dwordx4 v[208:209], off
	v_lshl_add_u64 v[208:209], v[214:215], 0, s[24:25]
	s_mov_b32 m0, s62
	s_nop 0
	global_load_lds_dwordx4 v[208:209], off
	v_lshl_add_u64 v[208:209], v[216:217], 0, s[24:25]
	s_mov_b32 m0, s63
	s_nop 0
	global_load_lds_dwordx4 v[208:209], off
	s_waitcnt vmcnt(8)
	s_waitcnt lgkmcnt(0)
	s_barrier
	s_waitcnt lgkmcnt(0)
	v_mfma_f32_16x16x32_bf16 v[62:65], v[140:143], v[176:179], v[62:65]
	v_mfma_f32_16x16x32_bf16 v[58:61], v[152:155], v[176:179], v[58:61]
	v_mfma_f32_16x16x32_bf16 v[50:53], v[140:143], v[184:187], v[50:53]
	v_mfma_f32_16x16x32_bf16 v[42:45], v[152:155], v[184:187], v[42:45]
	v_mfma_f32_16x16x32_bf16 v[34:37], v[140:143], v[192:195], v[34:37]
	v_mfma_f32_16x16x32_bf16 v[26:29], v[152:155], v[192:195], v[26:29]
	v_mfma_f32_16x16x32_bf16 v[18:21], v[140:143], v[200:203], v[18:21]
	v_mfma_f32_16x16x32_bf16 v[10:13], v[152:155], v[200:203], v[10:13]
	v_mfma_f32_16x16x32_bf16 v[62:65], v[148:151], v[180:183], v[62:65]
	v_mfma_f32_16x16x32_bf16 v[58:61], v[156:159], v[180:183], v[58:61]
	v_mfma_f32_16x16x32_bf16 v[50:53], v[148:151], v[188:191], v[50:53]
	v_mfma_f32_16x16x32_bf16 v[42:45], v[156:159], v[188:191], v[42:45]
	v_mfma_f32_16x16x32_bf16 v[34:37], v[148:151], v[196:199], v[34:37]
	v_mfma_f32_16x16x32_bf16 v[26:29], v[156:159], v[196:199], v[26:29]
	v_mfma_f32_16x16x32_bf16 v[18:21], v[148:151], v[204:207], v[18:21]
	v_mfma_f32_16x16x32_bf16 v[10:13], v[156:159], v[204:207], v[10:13]
	v_mfma_f32_16x16x32_bf16 v[54:57], v[160:163], v[176:179], v[54:57]
	v_mfma_f32_16x16x32_bf16 v[46:49], v[168:171], v[176:179], v[46:49]
	v_mfma_f32_16x16x32_bf16 v[38:41], v[160:163], v[184:187], v[38:41]
	v_mfma_f32_16x16x32_bf16 v[30:33], v[168:171], v[184:187], v[30:33]
	v_mfma_f32_16x16x32_bf16 v[22:25], v[160:163], v[192:195], v[22:25]
	v_mfma_f32_16x16x32_bf16 v[14:17], v[168:171], v[192:195], v[14:17]
	v_mfma_f32_16x16x32_bf16 v[6:9], v[160:163], v[200:203], v[6:9]
	v_mfma_f32_16x16x32_bf16 v[2:5], v[168:171], v[200:203], v[2:5]
	v_mfma_f32_16x16x32_bf16 v[54:57], v[164:167], v[180:183], v[54:57]
	v_mfma_f32_16x16x32_bf16 v[46:49], v[172:175], v[180:183], v[46:49]
	v_mfma_f32_16x16x32_bf16 v[38:41], v[164:167], v[188:191], v[38:41]
	v_mfma_f32_16x16x32_bf16 v[30:33], v[172:175], v[188:191], v[30:33]
	v_mfma_f32_16x16x32_bf16 v[22:25], v[164:167], v[196:199], v[22:25]
	v_mfma_f32_16x16x32_bf16 v[14:17], v[172:175], v[196:199], v[14:17]
	v_mfma_f32_16x16x32_bf16 v[6:9], v[164:167], v[204:207], v[6:9]
	v_mfma_f32_16x16x32_bf16 v[2:5], v[172:175], v[204:207], v[2:5]
	s_barrier
	s_add_i32 s71, s71, 2
	s_add_u32 s6, s6, 0x100
	s_addc_u32 s7, s7, 0
	s_add_u32 s69, s69, 0x100
	s_addc_u32 s70, s70, 0
	s_cmp_gt_u32 s71, 13
	s_cbranch_scc0 .LBB0_1525
	s_and_b64 vcc, exec, s[12:13]
	s_cbranch_vccz .LBB0_1528
	s_barrier

.LBB0_1880:
	s_add_u32 s20, s4, 0xfffc0080
	s_addc_u32 s21, s5, -1
	s_add_i32 s37, 0, 0x10000
	s_cmp_eq_u32 s85, 12
	s_cselect_b32 s53, s45, s21
	s_cselect_b32 s52, s44, s20
	s_cselect_b32 s51, s43, s81
	s_cselect_b32 s50, s49, s73
	s_add_i32 s77, 0, 0x14000
	v_add_u32_e32 v152, s37, v142
	v_add_u32_e32 v168, s77, v142
	ds_read_b128 v[136:139], v152
	ds_read_b128 v[144:147], v152 offset:1024
	ds_read_b128 v[148:151], v152 offset:2048
	ds_read_b128 v[152:155], v152 offset:3072
	ds_read_b128 v[156:159], v168
	ds_read_b128 v[160:163], v168 offset:1024
	ds_read_b128 v[164:167], v168 offset:2048
	ds_read_b128 v[168:171], v168 offset:3072
	v_lshl_add_u64 v[204:205], s[4:5], 0, v[132:133]
	s_add_i32 m0, s60, 0xc000
	ds_read_b128 v[172:175], v143
	ds_read_b128 v[176:179], v143 offset:1024
	ds_read_b128 v[180:183], v143 offset:2048
	ds_read_b128 v[184:187], v143 offset:3072
	ds_read_b128 v[188:191], v143 offset:4096
	ds_read_b128 v[192:195], v143 offset:5120
	ds_read_b128 v[196:199], v143 offset:6144
	ds_read_b128 v[200:203], v143 offset:7168
	global_load_lds_dwordx4 v[204:205], off
	v_lshl_add_u64 v[204:205], s[4:5], 0, v[134:135]
	s_add_i32 m0, s60, 0xe000
	s_nop 0
	global_load_lds_dwordx4 v[204:205], off
	s_waitcnt vmcnt(8)
	s_waitcnt lgkmcnt(0)
	s_barrier
	s_waitcnt lgkmcnt(0)
	v_mfma_f32_16x16x32_bf16 v[126:129], v[136:139], v[172:175], v[126:129]
	v_mfma_f32_16x16x32_bf16 v[122:125], v[148:151], v[172:175], v[122:125]
	v_mfma_f32_16x16x32_bf16 v[110:113], v[136:139], v[180:183], v[110:113]
	v_mfma_f32_16x16x32_bf16 v[106:109], v[148:151], v[180:183], v[106:109]
	v_mfma_f32_16x16x32_bf16 v[94:97], v[136:139], v[188:191], v[94:97]
	v_mfma_f32_16x16x32_bf16 v[90:93], v[148:151], v[188:191], v[90:93]
	v_mfma_f32_16x16x32_bf16 v[78:81], v[136:139], v[196:199], v[78:81]
	v_mfma_f32_16x16x32_bf16 v[74:77], v[148:151], v[196:199], v[74:77]
	v_mfma_f32_16x16x32_bf16 v[126:129], v[144:147], v[176:179], v[126:129]
	v_mfma_f32_16x16x32_bf16 v[122:125], v[152:155], v[176:179], v[122:125]
	v_mfma_f32_16x16x32_bf16 v[110:113], v[144:147], v[184:187], v[110:113]
	v_mfma_f32_16x16x32_bf16 v[106:109], v[152:155], v[184:187], v[106:109]
	v_mfma_f32_16x16x32_bf16 v[94:97], v[144:147], v[192:195], v[94:97]
	v_mfma_f32_16x16x32_bf16 v[90:93], v[152:155], v[192:195], v[90:93]
	v_mfma_f32_16x16x32_bf16 v[78:81], v[144:147], v[200:203], v[78:81]
	v_mfma_f32_16x16x32_bf16 v[74:77], v[152:155], v[200:203], v[74:77]
	v_mfma_f32_16x16x32_bf16 v[118:121], v[156:159], v[172:175], v[118:121]
	v_mfma_f32_16x16x32_bf16 v[114:117], v[164:167], v[172:175], v[114:117]
	v_mfma_f32_16x16x32_bf16 v[102:105], v[156:159], v[180:183], v[102:105]
	v_mfma_f32_16x16x32_bf16 v[98:101], v[164:167], v[180:183], v[98:101]
	v_mfma_f32_16x16x32_bf16 v[86:89], v[156:159], v[188:191], v[86:89]
	v_mfma_f32_16x16x32_bf16 v[82:85], v[164:167], v[188:191], v[82:85]
	v_mfma_f32_16x16x32_bf16 v[70:73], v[156:159], v[196:199], v[70:73]
	v_mfma_f32_16x16x32_bf16 v[66:69], v[164:167], v[196:199], v[66:69]
	v_mfma_f32_16x16x32_bf16 v[118:121], v[160:163], v[176:179], v[118:121]
	v_mfma_f32_16x16x32_bf16 v[114:117], v[168:171], v[176:179], v[114:117]
	v_mfma_f32_16x16x32_bf16 v[102:105], v[160:163], v[184:187], v[102:105]
	v_mfma_f32_16x16x32_bf16 v[98:101], v[168:171], v[184:187], v[98:101]
	v_mfma_f32_16x16x32_bf16 v[86:89], v[160:163], v[192:195], v[86:89]
	v_mfma_f32_16x16x32_bf16 v[82:85], v[168:171], v[192:195], v[82:85]
	v_mfma_f32_16x16x32_bf16 v[70:73], v[160:163], v[200:203], v[70:73]
	v_mfma_f32_16x16x32_bf16 v[66:69], v[168:171], v[200:203], v[66:69]
	s_barrier
	s_add_i32 s20, s37, s59
	v_lshl_add_u64 v[204:205], s[50:51], 0, v[0:1]
	s_mov_b32 m0, s20
	ds_read_b128 v[172:175], v143 offset:16384
	ds_read_b128 v[176:179], v143 offset:17408
	ds_read_b128 v[180:183], v143 offset:18432
	ds_read_b128 v[184:187], v143 offset:19456
	ds_read_b128 v[188:191], v143 offset:20480
	ds_read_b128 v[192:195], v143 offset:21504
	ds_read_b128 v[196:199], v143 offset:22528
	ds_read_b128 v[200:203], v143 offset:23552
	global_load_lds_dwordx4 v[204:205], off
	s_add_i32 m0, s20, 0x2000
	s_add_u32 s20, s50, 0x40000
	v_lshl_add_u64 v[206:207], s[50:51], 0, v[130:131]
	s_addc_u32 s21, s51, 0
	s_add_i32 s37, s77, s59
	global_load_lds_dwordx4 v[206:207], off
	v_lshl_add_u64 v[208:209], s[20:21], 0, v[0:1]
	s_mov_b32 m0, s37
	v_lshl_add_u64 v[210:211], s[52:53], 0, v[130:131]
	global_load_lds_dwordx4 v[208:209], off
	v_lshl_add_u64 v[208:209], s[20:21], 0, v[130:131]
	s_add_i32 m0, s37, 0x2000
	s_nop 0
	global_load_lds_dwordx4 v[208:209], off
	v_lshl_add_u64 v[208:209], s[52:53], 0, v[0:1]
	s_mov_b32 m0, s60
	s_nop 0
	global_load_lds_dwordx4 v[208:209], off
	s_mov_b32 m0, s61
	s_nop 0
	global_load_lds_dwordx4 v[210:211], off
	s_waitcnt vmcnt(8)
	s_waitcnt lgkmcnt(0)
	s_barrier
	s_waitcnt lgkmcnt(0)
	v_mfma_f32_16x16x32_bf16 v[62:65], v[136:139], v[172:175], v[62:65]
	v_mfma_f32_16x16x32_bf16 v[58:61], v[148:151], v[172:175], v[58:61]
	v_mfma_f32_16x16x32_bf16 v[46:49], v[136:139], v[180:183], v[46:49]
	v_mfma_f32_16x16x32_bf16 v[42:45], v[148:151], v[180:183], v[42:45]
	v_mfma_f32_16x16x32_bf16 v[30:33], v[136:139], v[188:191], v[30:33]
	v_mfma_f32_16x16x32_bf16 v[26:29], v[148:151], v[188:191], v[26:29]
	v_mfma_f32_16x16x32_bf16 v[14:17], v[136:139], v[196:199], v[14:17]
	v_mfma_f32_16x16x32_bf16 v[10:13], v[148:151], v[196:199], v[10:13]
	v_mfma_f32_16x16x32_bf16 v[62:65], v[144:147], v[176:179], v[62:65]
	v_mfma_f32_16x16x32_bf16 v[58:61], v[152:155], v[176:179], v[58:61]
	v_mfma_f32_16x16x32_bf16 v[46:49], v[144:147], v[184:187], v[46:49]
	v_mfma_f32_16x16x32_bf16 v[42:45], v[152:155], v[184:187], v[42:45]
	v_mfma_f32_16x16x32_bf16 v[30:33], v[144:147], v[192:195], v[30:33]
	v_mfma_f32_16x16x32_bf16 v[26:29], v[152:155], v[192:195], v[26:29]
	v_mfma_f32_16x16x32_bf16 v[14:17], v[144:147], v[200:203], v[14:17]
	v_mfma_f32_16x16x32_bf16 v[10:13], v[152:155], v[200:203], v[10:13]
	v_mfma_f32_16x16x32_bf16 v[54:57], v[156:159], v[172:175], v[54:57]
	v_mfma_f32_16x16x32_bf16 v[50:53], v[164:167], v[172:175], v[50:53]
	v_mfma_f32_16x16x32_bf16 v[38:41], v[156:159], v[180:183], v[38:41]
	v_mfma_f32_16x16x32_bf16 v[34:37], v[164:167], v[180:183], v[34:37]
	v_mfma_f32_16x16x32_bf16 v[22:25], v[156:159], v[188:191], v[22:25]
	v_mfma_f32_16x16x32_bf16 v[18:21], v[164:167], v[188:191], v[18:21]
	v_mfma_f32_16x16x32_bf16 v[6:9], v[156:159], v[196:199], v[6:9]
	v_mfma_f32_16x16x32_bf16 v[2:5], v[164:167], v[196:199], v[2:5]
	v_mfma_f32_16x16x32_bf16 v[54:57], v[160:163], v[176:179], v[54:57]
	v_mfma_f32_16x16x32_bf16 v[50:53], v[168:171], v[176:179], v[50:53]
	v_mfma_f32_16x16x32_bf16 v[38:41], v[160:163], v[184:187], v[38:41]
	v_mfma_f32_16x16x32_bf16 v[34:37], v[168:171], v[184:187], v[34:37]
	v_mfma_f32_16x16x32_bf16 v[22:25], v[160:163], v[192:195], v[22:25]
	v_mfma_f32_16x16x32_bf16 v[18:21], v[168:171], v[192:195], v[18:21]
	v_mfma_f32_16x16x32_bf16 v[6:9], v[160:163], v[200:203], v[6:9]
	v_mfma_f32_16x16x32_bf16 v[2:5], v[168:171], v[200:203], v[2:5]
	s_barrier
	s_add_i32 s37, 0, 0x18000
	s_add_i32 s77, 0, 0x1c000
	v_add_u32_e32 v152, s37, v142
	v_add_u32_e32 v168, s77, v142
	ds_read_b128 v[136:139], v152
	ds_read_b128 v[144:147], v152 offset:1024
	ds_read_b128 v[148:151], v152 offset:2048
	ds_read_b128 v[152:155], v152 offset:3072
	ds_read_b128 v[156:159], v168
	ds_read_b128 v[160:163], v168 offset:1024
	ds_read_b128 v[164:167], v168 offset:2048
	ds_read_b128 v[168:171], v168 offset:3072
	s_add_u32 s20, s52, 0x40000
	s_addc_u32 s21, s53, 0
	s_mov_b32 m0, s62
	v_lshl_add_u64 v[214:215], s[20:21], 0, v[0:1]
	ds_read_b128 v[172:175], v143 offset:32768
	ds_read_b128 v[176:179], v143 offset:33792
	ds_read_b128 v[180:183], v143 offset:34816
	ds_read_b128 v[184:187], v143 offset:35840
	ds_read_b128 v[188:191], v143 offset:36864
	ds_read_b128 v[192:195], v143 offset:37888
	ds_read_b128 v[196:199], v143 offset:38912
	ds_read_b128 v[200:203], v143 offset:39936
	global_load_lds_dwordx4 v[214:215], off
	v_lshl_add_u64 v[214:215], s[20:21], 0, v[130:131]
	s_mov_b32 m0, s63
	s_nop 0
	global_load_lds_dwordx4 v[214:215], off
	s_waitcnt vmcnt(8)
	s_waitcnt lgkmcnt(0)
	s_barrier
	s_waitcnt lgkmcnt(0)
	v_mfma_f32_16x16x32_bf16 v[126:129], v[136:139], v[172:175], v[126:129]
	v_mfma_f32_16x16x32_bf16 v[122:125], v[148:151], v[172:175], v[122:125]
	v_mfma_f32_16x16x32_bf16 v[110:113], v[136:139], v[180:183], v[110:113]
	v_mfma_f32_16x16x32_bf16 v[106:109], v[148:151], v[180:183], v[106:109]
	v_mfma_f32_16x16x32_bf16 v[94:97], v[136:139], v[188:191], v[94:97]
	v_mfma_f32_16x16x32_bf16 v[90:93], v[148:151], v[188:191], v[90:93]
	v_mfma_f32_16x16x32_bf16 v[78:81], v[136:139], v[196:199], v[78:81]
	v_mfma_f32_16x16x32_bf16 v[74:77], v[148:151], v[196:199], v[74:77]
	v_mfma_f32_16x16x32_bf16 v[126:129], v[144:147], v[176:179], v[126:129]
	v_mfma_f32_16x16x32_bf16 v[122:125], v[152:155], v[176:179], v[122:125]
	v_mfma_f32_16x16x32_bf16 v[110:113], v[144:147], v[184:187], v[110:113]
	v_mfma_f32_16x16x32_bf16 v[106:109], v[152:155], v[184:187], v[106:109]
	v_mfma_f32_16x16x32_bf16 v[94:97], v[144:147], v[192:195], v[94:97]
	v_mfma_f32_16x16x32_bf16 v[90:93], v[152:155], v[192:195], v[90:93]
	v_mfma_f32_16x16x32_bf16 v[78:81], v[144:147], v[200:203], v[78:81]
	v_mfma_f32_16x16x32_bf16 v[74:77], v[152:155], v[200:203], v[74:77]
	v_mfma_f32_16x16x32_bf16 v[118:121], v[156:159], v[172:175], v[118:121]
	v_mfma_f32_16x16x32_bf16 v[114:117], v[164:167], v[172:175], v[114:117]
	v_mfma_f32_16x16x32_bf16 v[102:105], v[156:159], v[180:183], v[102:105]
	v_mfma_f32_16x16x32_bf16 v[98:101], v[164:167], v[180:183], v[98:101]
	v_mfma_f32_16x16x32_bf16 v[86:89], v[156:159], v[188:191], v[86:89]
	v_mfma_f32_16x16x32_bf16 v[82:85], v[164:167], v[188:191], v[82:85]
	v_mfma_f32_16x16x32_bf16 v[70:73], v[156:159], v[196:199], v[70:73]
	v_mfma_f32_16x16x32_bf16 v[66:69], v[164:167], v[196:199], v[66:69]
	v_mfma_f32_16x16x32_bf16 v[118:121], v[160:163], v[176:179], v[118:121]
	v_mfma_f32_16x16x32_bf16 v[114:117], v[168:171], v[176:179], v[114:117]
	v_mfma_f32_16x16x32_bf16 v[102:105], v[160:163], v[184:187], v[102:105]
	v_mfma_f32_16x16x32_bf16 v[98:101], v[168:171], v[184:187], v[98:101]
	v_mfma_f32_16x16x32_bf16 v[86:89], v[160:163], v[192:195], v[86:89]
	v_mfma_f32_16x16x32_bf16 v[82:85], v[168:171], v[192:195], v[82:85]
	v_mfma_f32_16x16x32_bf16 v[70:73], v[160:163], v[200:203], v[70:73]
	v_mfma_f32_16x16x32_bf16 v[66:69], v[168:171], v[200:203], v[66:69]
	s_barrier
	s_add_i32 s20, s37, s59
	v_lshl_add_u64 v[204:205], v[204:205], 0, s[24:25]
	s_mov_b32 m0, s20
	ds_read_b128 v[172:175], v143 offset:49152
	ds_read_b128 v[176:179], v143 offset:50176
	ds_read_b128 v[180:183], v143 offset:51200
	ds_read_b128 v[184:187], v143 offset:52224
	ds_read_b128 v[188:191], v143 offset:53248
	ds_read_b128 v[192:195], v143 offset:54272
	ds_read_b128 v[196:199], v143 offset:55296
	ds_read_b128 v[200:203], v143 offset:56320
	global_load_lds_dwordx4 v[204:205], off
	s_add_i32 m0, s20, 0x2000
	s_add_u32 s20, s50, 0x40080
	v_lshl_add_u64 v[204:205], v[206:207], 0, s[24:25]
	s_addc_u32 s21, s51, 0
	s_add_i32 s37, s77, s59
	global_load_lds_dwordx4 v[204:205], off
	v_lshl_add_u64 v[204:205], s[20:21], 0, v[0:1]
	s_mov_b32 m0, s37
	s_nop 0
	global_load_lds_dwordx4 v[204:205], off
	v_lshl_add_u64 v[204:205], s[20:21], 0, v[130:131]
	s_add_i32 m0, s37, 0x2000
	s_nop 0
	global_load_lds_dwordx4 v[204:205], off
	v_lshl_add_u64 v[204:205], v[208:209], 0, s[24:25]
	s_mov_b32 m0, s67
	s_nop 0
	global_load_lds_dwordx4 v[204:205], off
	v_lshl_add_u64 v[204:205], v[210:211], 0, s[24:25]
	s_mov_b32 m0, s68
	s_nop 0
	global_load_lds_dwordx4 v[204:205], off
	s_waitcnt vmcnt(8)
	s_waitcnt lgkmcnt(0)
	s_barrier
	s_waitcnt lgkmcnt(0)
	v_mfma_f32_16x16x32_bf16 v[62:65], v[136:139], v[172:175], v[62:65]
	v_mfma_f32_16x16x32_bf16 v[58:61], v[148:151], v[172:175], v[58:61]
	v_mfma_f32_16x16x32_bf16 v[46:49], v[136:139], v[180:183], v[46:49]
	v_mfma_f32_16x16x32_bf16 v[42:45], v[148:151], v[180:183], v[42:45]
	v_mfma_f32_16x16x32_bf16 v[30:33], v[136:139], v[188:191], v[30:33]
	v_mfma_f32_16x16x32_bf16 v[26:29], v[148:151], v[188:191], v[26:29]
	v_mfma_f32_16x16x32_bf16 v[14:17], v[136:139], v[196:199], v[14:17]
	v_mfma_f32_16x16x32_bf16 v[10:13], v[148:151], v[196:199], v[10:13]
	v_mfma_f32_16x16x32_bf16 v[62:65], v[144:147], v[176:179], v[62:65]
	v_mfma_f32_16x16x32_bf16 v[58:61], v[152:155], v[176:179], v[58:61]
	v_mfma_f32_16x16x32_bf16 v[46:49], v[144:147], v[184:187], v[46:49]
	v_mfma_f32_16x16x32_bf16 v[42:45], v[152:155], v[184:187], v[42:45]
	v_mfma_f32_16x16x32_bf16 v[30:33], v[144:147], v[192:195], v[30:33]
	v_mfma_f32_16x16x32_bf16 v[26:29], v[152:155], v[192:195], v[26:29]
	v_mfma_f32_16x16x32_bf16 v[14:17], v[144:147], v[200:203], v[14:17]
	v_mfma_f32_16x16x32_bf16 v[10:13], v[152:155], v[200:203], v[10:13]
	v_mfma_f32_16x16x32_bf16 v[54:57], v[156:159], v[172:175], v[54:57]
	v_mfma_f32_16x16x32_bf16 v[50:53], v[164:167], v[172:175], v[50:53]
	v_mfma_f32_16x16x32_bf16 v[38:41], v[156:159], v[180:183], v[38:41]
	v_mfma_f32_16x16x32_bf16 v[34:37], v[164:167], v[180:183], v[34:37]
	v_mfma_f32_16x16x32_bf16 v[22:25], v[156:159], v[188:191], v[22:25]
	v_mfma_f32_16x16x32_bf16 v[18:21], v[164:167], v[188:191], v[18:21]
	v_mfma_f32_16x16x32_bf16 v[6:9], v[156:159], v[196:199], v[6:9]
	v_mfma_f32_16x16x32_bf16 v[2:5], v[164:167], v[196:199], v[2:5]
	v_mfma_f32_16x16x32_bf16 v[54:57], v[160:163], v[176:179], v[54:57]
	v_mfma_f32_16x16x32_bf16 v[50:53], v[168:171], v[176:179], v[50:53]
	v_mfma_f32_16x16x32_bf16 v[38:41], v[160:163], v[184:187], v[38:41]
	v_mfma_f32_16x16x32_bf16 v[34:37], v[168:171], v[184:187], v[34:37]
	v_mfma_f32_16x16x32_bf16 v[22:25], v[160:163], v[192:195], v[22:25]
	v_mfma_f32_16x16x32_bf16 v[18:21], v[168:171], v[192:195], v[18:21]
	v_mfma_f32_16x16x32_bf16 v[6:9], v[160:163], v[200:203], v[6:9]
	v_mfma_f32_16x16x32_bf16 v[2:5], v[168:171], v[200:203], v[2:5]
	s_barrier
	s_add_i32 s85, s85, 2
	s_add_u32 s4, s4, 0x100
	s_addc_u32 s5, s5, 0
	s_add_u32 s73, s73, 0x100
	s_addc_u32 s81, s81, 0
	s_cmp_gt_u32 s85, 13
	s_cbranch_scc0 .LBB0_1880
	s_and_b64 vcc, exec, s[18:19]
	s_cbranch_vccz .LBB0_1883
	s_barrier

.LBB0_1972:
	s_add_u32 s37, s48, s17
	s_addc_u32 s45, s49, 0
	s_add_u32 s52, s37, 0x100
	s_addc_u32 s53, s45, 0
	s_and_b64 s[20:21], s[50:51], exec
	s_cselect_b32 s55, s19, s53
	s_cselect_b32 s54, s18, s52
	s_add_u32 s17, s46, s17
	s_addc_u32 s20, s47, 0
	s_add_u32 s17, s17, 0x100
	s_addc_u32 s52, s20, 0
	s_add_i32 s78, 0, 0x10000
	s_and_b64 s[20:21], s[50:51], exec
	s_cselect_b32 s57, s43, s52
	s_cselect_b32 s56, s42, s17
	s_add_i32 s20, 0, 0x14000
	s_add_u32 s60, s37, 0x80080
	s_addc_u32 s61, s45, 0
	s_add_i32 s77, s78, s66
	s_add_i32 m0, s67, 0xc000
	s_add_i32 s21, s67, 0xe000
	s_add_i32 s37, s77, 0x2000
	s_add_u32 s58, s56, 0x40000
	v_add_u32_e32 v152, s78, v141
	v_add_u32_e32 v168, s20, v141
	s_addc_u32 s59, s57, 0
	s_add_i32 s83, s20, s66
	ds_read_b128 v[136:139], v152
	ds_read_b128 v[144:147], v152 offset:1024
	ds_read_b128 v[148:151], v152 offset:2048
	ds_read_b128 v[152:155], v152 offset:3072
	ds_read_b128 v[156:159], v168
	ds_read_b128 v[160:163], v168 offset:1024
	ds_read_b128 v[164:167], v168 offset:2048
	ds_read_b128 v[168:171], v168 offset:3072
	s_add_i32 s82, s83, 0x2000
	s_add_i32 s92, 0, 0x18000
	s_add_i32 s88, 0, 0x1c000
	s_add_u32 s52, s54, 0x80000
	s_addc_u32 s53, s55, 0
	s_add_i32 s45, s92, s66
	s_add_i32 s17, s45, 0x2000
	s_add_u32 s50, s56, 0x40080
	s_addc_u32 s51, s57, 0
	s_add_i32 s20, s88, s66
	s_add_i32 s78, s20, 0x2000
	v_lshl_add_u64 v[204:205], s[60:61], 0, v[130:131]
	ds_read_b128 v[172:175], v143
	ds_read_b128 v[176:179], v143 offset:1024
	ds_read_b128 v[180:183], v143 offset:2048
	ds_read_b128 v[184:187], v143 offset:3072
	ds_read_b128 v[188:191], v143 offset:4096
	ds_read_b128 v[192:195], v143 offset:5120
	ds_read_b128 v[196:199], v143 offset:6144
	ds_read_b128 v[200:203], v143 offset:7168
	global_load_lds_dwordx4 v[204:205], off
	v_lshl_add_u64 v[204:205], s[60:61], 0, v[132:133]
	s_mov_b32 m0, s21
	s_nop 0
	global_load_lds_dwordx4 v[204:205], off
	s_waitcnt vmcnt(8)
	s_waitcnt lgkmcnt(0)
	s_barrier
	s_waitcnt lgkmcnt(0)
	v_mfma_f32_16x16x32_bf16 v[126:129], v[136:139], v[172:175], v[126:129]
	v_mfma_f32_16x16x32_bf16 v[122:125], v[148:151], v[172:175], v[122:125]
	v_mfma_f32_16x16x32_bf16 v[114:117], v[136:139], v[180:183], v[114:117]
	v_mfma_f32_16x16x32_bf16 v[106:109], v[148:151], v[180:183], v[106:109]
	v_mfma_f32_16x16x32_bf16 v[98:101], v[136:139], v[188:191], v[98:101]
	v_mfma_f32_16x16x32_bf16 v[90:93], v[148:151], v[188:191], v[90:93]
	v_mfma_f32_16x16x32_bf16 v[82:85], v[136:139], v[196:199], v[82:85]
	v_mfma_f32_16x16x32_bf16 v[74:77], v[148:151], v[196:199], v[74:77]
	v_mfma_f32_16x16x32_bf16 v[126:129], v[144:147], v[176:179], v[126:129]
	v_mfma_f32_16x16x32_bf16 v[122:125], v[152:155], v[176:179], v[122:125]
	v_mfma_f32_16x16x32_bf16 v[114:117], v[144:147], v[184:187], v[114:117]
	v_mfma_f32_16x16x32_bf16 v[106:109], v[152:155], v[184:187], v[106:109]
	v_mfma_f32_16x16x32_bf16 v[98:101], v[144:147], v[192:195], v[98:101]
	v_mfma_f32_16x16x32_bf16 v[90:93], v[152:155], v[192:195], v[90:93]
	v_mfma_f32_16x16x32_bf16 v[82:85], v[144:147], v[200:203], v[82:85]
	v_mfma_f32_16x16x32_bf16 v[74:77], v[152:155], v[200:203], v[74:77]
	v_mfma_f32_16x16x32_bf16 v[118:121], v[156:159], v[172:175], v[118:121]
	v_mfma_f32_16x16x32_bf16 v[110:113], v[164:167], v[172:175], v[110:113]
	v_mfma_f32_16x16x32_bf16 v[102:105], v[156:159], v[180:183], v[102:105]
	v_mfma_f32_16x16x32_bf16 v[94:97], v[164:167], v[180:183], v[94:97]
	v_mfma_f32_16x16x32_bf16 v[86:89], v[156:159], v[188:191], v[86:89]
	v_mfma_f32_16x16x32_bf16 v[78:81], v[164:167], v[188:191], v[78:81]
	v_mfma_f32_16x16x32_bf16 v[70:73], v[156:159], v[196:199], v[70:73]
	v_mfma_f32_16x16x32_bf16 v[66:69], v[164:167], v[196:199], v[66:69]
	v_mfma_f32_16x16x32_bf16 v[118:121], v[160:163], v[176:179], v[118:121]
	v_mfma_f32_16x16x32_bf16 v[110:113], v[168:171], v[176:179], v[110:113]
	v_mfma_f32_16x16x32_bf16 v[102:105], v[160:163], v[184:187], v[102:105]
	v_mfma_f32_16x16x32_bf16 v[94:97], v[168:171], v[184:187], v[94:97]
	v_mfma_f32_16x16x32_bf16 v[86:89], v[160:163], v[192:195], v[86:89]
	v_mfma_f32_16x16x32_bf16 v[78:81], v[168:171], v[192:195], v[78:81]
	v_mfma_f32_16x16x32_bf16 v[70:73], v[160:163], v[200:203], v[70:73]
	v_mfma_f32_16x16x32_bf16 v[66:69], v[168:171], v[200:203], v[66:69]
	s_barrier
	s_mov_b32 m0, s77
	v_lshl_add_u64 v[204:205], s[56:57], 0, v[0:1]
	ds_read_b128 v[172:175], v143 offset:16384
	ds_read_b128 v[176:179], v143 offset:17408
	ds_read_b128 v[180:183], v143 offset:18432
	ds_read_b128 v[184:187], v143 offset:19456
	ds_read_b128 v[188:191], v143 offset:20480
	ds_read_b128 v[192:195], v143 offset:21504
	ds_read_b128 v[196:199], v143 offset:22528
	ds_read_b128 v[200:203], v143 offset:23552
	global_load_lds_dwordx4 v[204:205], off
	v_lshl_add_u64 v[206:207], s[56:57], 0, v[134:135]
	s_mov_b32 m0, s37
	v_lshl_add_u64 v[208:209], s[58:59], 0, v[0:1]
	global_load_lds_dwordx4 v[206:207], off
	s_mov_b32 m0, s83
	v_lshl_add_u64 v[210:211], s[54:55], 0, v[132:133]
	global_load_lds_dwordx4 v[208:209], off
	v_lshl_add_u64 v[208:209], s[58:59], 0, v[134:135]
	s_mov_b32 m0, s82
	s_nop 0
	global_load_lds_dwordx4 v[208:209], off
	v_lshl_add_u64 v[208:209], s[54:55], 0, v[130:131]
	s_mov_b32 m0, s67
	s_nop 0
	global_load_lds_dwordx4 v[208:209], off
	s_mov_b32 m0, s68
	s_nop 0
	global_load_lds_dwordx4 v[210:211], off
	s_waitcnt vmcnt(8)
	s_waitcnt lgkmcnt(0)
	s_barrier
	s_waitcnt lgkmcnt(0)
	v_mfma_f32_16x16x32_bf16 v[62:65], v[136:139], v[172:175], v[62:65]
	v_mfma_f32_16x16x32_bf16 v[58:61], v[148:151], v[172:175], v[58:61]
	v_mfma_f32_16x16x32_bf16 v[50:53], v[136:139], v[180:183], v[50:53]
	v_mfma_f32_16x16x32_bf16 v[42:45], v[148:151], v[180:183], v[42:45]
	v_mfma_f32_16x16x32_bf16 v[34:37], v[136:139], v[188:191], v[34:37]
	v_mfma_f32_16x16x32_bf16 v[26:29], v[148:151], v[188:191], v[26:29]
	v_mfma_f32_16x16x32_bf16 v[18:21], v[136:139], v[196:199], v[18:21]
	v_mfma_f32_16x16x32_bf16 v[10:13], v[148:151], v[196:199], v[10:13]
	v_mfma_f32_16x16x32_bf16 v[62:65], v[144:147], v[176:179], v[62:65]
	v_mfma_f32_16x16x32_bf16 v[58:61], v[152:155], v[176:179], v[58:61]
	v_mfma_f32_16x16x32_bf16 v[50:53], v[144:147], v[184:187], v[50:53]
	v_mfma_f32_16x16x32_bf16 v[42:45], v[152:155], v[184:187], v[42:45]
	v_mfma_f32_16x16x32_bf16 v[34:37], v[144:147], v[192:195], v[34:37]
	v_mfma_f32_16x16x32_bf16 v[26:29], v[152:155], v[192:195], v[26:29]
	v_mfma_f32_16x16x32_bf16 v[18:21], v[144:147], v[200:203], v[18:21]
	v_mfma_f32_16x16x32_bf16 v[10:13], v[152:155], v[200:203], v[10:13]
	v_mfma_f32_16x16x32_bf16 v[54:57], v[156:159], v[172:175], v[54:57]
	v_mfma_f32_16x16x32_bf16 v[46:49], v[164:167], v[172:175], v[46:49]
	v_mfma_f32_16x16x32_bf16 v[38:41], v[156:159], v[180:183], v[38:41]
	v_mfma_f32_16x16x32_bf16 v[30:33], v[164:167], v[180:183], v[30:33]
	v_mfma_f32_16x16x32_bf16 v[22:25], v[156:159], v[188:191], v[22:25]
	v_mfma_f32_16x16x32_bf16 v[14:17], v[164:167], v[188:191], v[14:17]
	v_mfma_f32_16x16x32_bf16 v[6:9], v[156:159], v[196:199], v[6:9]
	v_mfma_f32_16x16x32_bf16 v[2:5], v[164:167], v[196:199], v[2:5]
	v_mfma_f32_16x16x32_bf16 v[54:57], v[160:163], v[176:179], v[54:57]
	v_mfma_f32_16x16x32_bf16 v[46:49], v[168:171], v[176:179], v[46:49]
	v_mfma_f32_16x16x32_bf16 v[38:41], v[160:163], v[184:187], v[38:41]
	v_mfma_f32_16x16x32_bf16 v[30:33], v[168:171], v[184:187], v[30:33]
	v_mfma_f32_16x16x32_bf16 v[22:25], v[160:163], v[192:195], v[22:25]
	v_mfma_f32_16x16x32_bf16 v[14:17], v[168:171], v[192:195], v[14:17]
	v_mfma_f32_16x16x32_bf16 v[6:9], v[160:163], v[200:203], v[6:9]
	v_mfma_f32_16x16x32_bf16 v[2:5], v[168:171], v[200:203], v[2:5]
	s_barrier
	v_add_u32_e32 v152, s92, v141
	v_add_u32_e32 v168, s88, v141
	ds_read_b128 v[136:139], v152
	ds_read_b128 v[144:147], v152 offset:1024
	ds_read_b128 v[148:151], v152 offset:2048
	ds_read_b128 v[152:155], v152 offset:3072
	ds_read_b128 v[156:159], v168
	ds_read_b128 v[160:163], v168 offset:1024
	ds_read_b128 v[164:167], v168 offset:2048
	ds_read_b128 v[168:171], v168 offset:3072
	s_mov_b32 m0, s69
	v_lshl_add_u64 v[214:215], s[52:53], 0, v[130:131]
	ds_read_b128 v[172:175], v143 offset:32768
	ds_read_b128 v[176:179], v143 offset:33792
	ds_read_b128 v[180:183], v143 offset:34816
	ds_read_b128 v[184:187], v143 offset:35840
	ds_read_b128 v[188:191], v143 offset:36864
	ds_read_b128 v[192:195], v143 offset:37888
	ds_read_b128 v[196:199], v143 offset:38912
	ds_read_b128 v[200:203], v143 offset:39936
	global_load_lds_dwordx4 v[214:215], off
	v_lshl_add_u64 v[214:215], s[52:53], 0, v[132:133]
	s_mov_b32 m0, s70
	s_nop 0
	global_load_lds_dwordx4 v[214:215], off
	s_waitcnt vmcnt(8)
	s_waitcnt lgkmcnt(0)
	s_barrier
	s_waitcnt lgkmcnt(0)
	v_mfma_f32_16x16x32_bf16 v[126:129], v[136:139], v[172:175], v[126:129]
	v_mfma_f32_16x16x32_bf16 v[122:125], v[148:151], v[172:175], v[122:125]
	v_mfma_f32_16x16x32_bf16 v[114:117], v[136:139], v[180:183], v[114:117]
	v_mfma_f32_16x16x32_bf16 v[106:109], v[148:151], v[180:183], v[106:109]
	v_mfma_f32_16x16x32_bf16 v[98:101], v[136:139], v[188:191], v[98:101]
	v_mfma_f32_16x16x32_bf16 v[90:93], v[148:151], v[188:191], v[90:93]
	v_mfma_f32_16x16x32_bf16 v[82:85], v[136:139], v[196:199], v[82:85]
	v_mfma_f32_16x16x32_bf16 v[74:77], v[148:151], v[196:199], v[74:77]
	v_mfma_f32_16x16x32_bf16 v[126:129], v[144:147], v[176:179], v[126:129]
	v_mfma_f32_16x16x32_bf16 v[122:125], v[152:155], v[176:179], v[122:125]
	v_mfma_f32_16x16x32_bf16 v[114:117], v[144:147], v[184:187], v[114:117]
	v_mfma_f32_16x16x32_bf16 v[106:109], v[152:155], v[184:187], v[106:109]
	v_mfma_f32_16x16x32_bf16 v[98:101], v[144:147], v[192:195], v[98:101]
	v_mfma_f32_16x16x32_bf16 v[90:93], v[152:155], v[192:195], v[90:93]
	v_mfma_f32_16x16x32_bf16 v[82:85], v[144:147], v[200:203], v[82:85]
	v_mfma_f32_16x16x32_bf16 v[74:77], v[152:155], v[200:203], v[74:77]
	v_mfma_f32_16x16x32_bf16 v[118:121], v[156:159], v[172:175], v[118:121]
	v_mfma_f32_16x16x32_bf16 v[110:113], v[164:167], v[172:175], v[110:113]
	v_mfma_f32_16x16x32_bf16 v[102:105], v[156:159], v[180:183], v[102:105]
	v_mfma_f32_16x16x32_bf16 v[94:97], v[164:167], v[180:183], v[94:97]
	v_mfma_f32_16x16x32_bf16 v[86:89], v[156:159], v[188:191], v[86:89]
	v_mfma_f32_16x16x32_bf16 v[78:81], v[164:167], v[188:191], v[78:81]
	v_mfma_f32_16x16x32_bf16 v[70:73], v[156:159], v[196:199], v[70:73]
	v_mfma_f32_16x16x32_bf16 v[66:69], v[164:167], v[196:199], v[66:69]
	v_mfma_f32_16x16x32_bf16 v[118:121], v[160:163], v[176:179], v[118:121]
	v_mfma_f32_16x16x32_bf16 v[110:113], v[168:171], v[176:179], v[110:113]
	v_mfma_f32_16x16x32_bf16 v[102:105], v[160:163], v[184:187], v[102:105]
	v_mfma_f32_16x16x32_bf16 v[94:97], v[168:171], v[184:187], v[94:97]
	v_mfma_f32_16x16x32_bf16 v[86:89], v[160:163], v[192:195], v[86:89]
	v_mfma_f32_16x16x32_bf16 v[78:81], v[168:171], v[192:195], v[78:81]
	v_mfma_f32_16x16x32_bf16 v[70:73], v[160:163], v[200:203], v[70:73]
	v_mfma_f32_16x16x32_bf16 v[66:69], v[168:171], v[200:203], v[66:69]
	s_barrier
	s_mov_b32 m0, s45
	v_lshl_add_u64 v[204:205], v[204:205], 0, s[24:25]
	ds_read_b128 v[172:175], v143 offset:49152
	ds_read_b128 v[176:179], v143 offset:50176
	ds_read_b128 v[180:183], v143 offset:51200
	ds_read_b128 v[184:187], v143 offset:52224
	ds_read_b128 v[188:191], v143 offset:53248
	ds_read_b128 v[192:195], v143 offset:54272
	ds_read_b128 v[196:199], v143 offset:55296
	ds_read_b128 v[200:203], v143 offset:56320
	global_load_lds_dwordx4 v[204:205], off
	v_lshl_add_u64 v[204:205], v[206:207], 0, s[24:25]
	s_mov_b32 m0, s17
	s_nop 0
	global_load_lds_dwordx4 v[204:205], off
	v_lshl_add_u64 v[204:205], s[50:51], 0, v[0:1]
	s_mov_b32 m0, s20
	s_nop 0
	global_load_lds_dwordx4 v[204:205], off
	v_lshl_add_u64 v[204:205], s[50:51], 0, v[134:135]
	s_mov_b32 m0, s78
	s_nop 0
	global_load_lds_dwordx4 v[204:205], off
	v_lshl_add_u64 v[204:205], v[208:209], 0, s[24:25]
	s_mov_b32 m0, s71
	s_nop 0
	global_load_lds_dwordx4 v[204:205], off
	v_lshl_add_u64 v[204:205], v[210:211], 0, s[24:25]
	s_mov_b32 m0, s72
	s_nop 0
	global_load_lds_dwordx4 v[204:205], off
	s_waitcnt vmcnt(8)
	s_waitcnt lgkmcnt(0)
	s_barrier
	s_waitcnt lgkmcnt(0)
	v_mfma_f32_16x16x32_bf16 v[62:65], v[136:139], v[172:175], v[62:65]
	v_mfma_f32_16x16x32_bf16 v[58:61], v[148:151], v[172:175], v[58:61]
	v_mfma_f32_16x16x32_bf16 v[50:53], v[136:139], v[180:183], v[50:53]
	v_mfma_f32_16x16x32_bf16 v[42:45], v[148:151], v[180:183], v[42:45]
	v_mfma_f32_16x16x32_bf16 v[34:37], v[136:139], v[188:191], v[34:37]
	v_mfma_f32_16x16x32_bf16 v[26:29], v[148:151], v[188:191], v[26:29]
	v_mfma_f32_16x16x32_bf16 v[18:21], v[136:139], v[196:199], v[18:21]
	v_mfma_f32_16x16x32_bf16 v[10:13], v[148:151], v[196:199], v[10:13]
	v_mfma_f32_16x16x32_bf16 v[62:65], v[144:147], v[176:179], v[62:65]
	v_mfma_f32_16x16x32_bf16 v[58:61], v[152:155], v[176:179], v[58:61]
	v_mfma_f32_16x16x32_bf16 v[50:53], v[144:147], v[184:187], v[50:53]
	v_mfma_f32_16x16x32_bf16 v[42:45], v[152:155], v[184:187], v[42:45]
	v_mfma_f32_16x16x32_bf16 v[34:37], v[144:147], v[192:195], v[34:37]
	v_mfma_f32_16x16x32_bf16 v[26:29], v[152:155], v[192:195], v[26:29]
	v_mfma_f32_16x16x32_bf16 v[18:21], v[144:147], v[200:203], v[18:21]
	v_mfma_f32_16x16x32_bf16 v[10:13], v[152:155], v[200:203], v[10:13]
	v_mfma_f32_16x16x32_bf16 v[54:57], v[156:159], v[172:175], v[54:57]
	v_mfma_f32_16x16x32_bf16 v[46:49], v[164:167], v[172:175], v[46:49]
	v_mfma_f32_16x16x32_bf16 v[38:41], v[156:159], v[180:183], v[38:41]
	v_mfma_f32_16x16x32_bf16 v[30:33], v[164:167], v[180:183], v[30:33]
	v_mfma_f32_16x16x32_bf16 v[22:25], v[156:159], v[188:191], v[22:25]
	v_mfma_f32_16x16x32_bf16 v[14:17], v[164:167], v[188:191], v[14:17]
	v_mfma_f32_16x16x32_bf16 v[6:9], v[156:159], v[196:199], v[6:9]
	v_mfma_f32_16x16x32_bf16 v[2:5], v[164:167], v[196:199], v[2:5]
	v_mfma_f32_16x16x32_bf16 v[54:57], v[160:163], v[176:179], v[54:57]
	v_mfma_f32_16x16x32_bf16 v[46:49], v[168:171], v[176:179], v[46:49]
	v_mfma_f32_16x16x32_bf16 v[38:41], v[160:163], v[184:187], v[38:41]
	v_mfma_f32_16x16x32_bf16 v[30:33], v[168:171], v[184:187], v[30:33]
	v_mfma_f32_16x16x32_bf16 v[22:25], v[160:163], v[192:195], v[22:25]
	v_mfma_f32_16x16x32_bf16 v[14:17], v[168:171], v[192:195], v[14:17]
	v_mfma_f32_16x16x32_bf16 v[6:9], v[160:163], v[200:203], v[6:9]
	v_mfma_f32_16x16x32_bf16 v[2:5], v[168:171], v[200:203], v[2:5]
	s_barrier
	s_movk_i32 s17, 0x100
	s_andn2_b64 vcc, exec, s[4:5]
	s_mov_b64 s[50:51], -1
	s_mov_b64 s[4:5], 0
	s_cbranch_vccz .LBB0_1972
	s_and_b64 vcc, exec, s[12:13]
	s_cbranch_vccz .LBB0_1975
	s_barrier

.LBB0_2034:
	s_add_u32 s37, s46, s13
	s_addc_u32 s43, s47, 0
	s_add_u32 s50, s37, 0x100
	s_addc_u32 s51, s43, 0
	s_and_b64 s[20:21], s[48:49], exec
	s_cselect_b32 s53, s17, s51
	s_cselect_b32 s52, s16, s50
	s_add_u32 s13, s44, s13
	s_addc_u32 s20, s45, 0
	s_add_u32 s13, s13, 0x100
	s_addc_u32 s50, s20, 0
	s_add_i32 s78, 0, 0x10000
	s_and_b64 s[20:21], s[48:49], exec
	s_cselect_b32 s55, s19, s50
	s_cselect_b32 s54, s18, s13
	s_add_i32 s20, 0, 0x14000
	s_add_u32 s58, s37, 0x40080
	s_addc_u32 s59, s43, 0
	s_add_i32 s77, s78, s64
	s_add_i32 m0, s65, 0xc000
	s_add_i32 s21, s65, 0xe000
	s_add_i32 s37, s77, 0x2000
	s_add_u32 s56, s54, 0x80000
	v_add_u32_e32 v152, s78, v141
	v_add_u32_e32 v168, s20, v141
	s_addc_u32 s57, s55, 0
	s_add_i32 s83, s20, s64
	ds_read_b128 v[136:139], v152
	ds_read_b128 v[144:147], v152 offset:1024
	ds_read_b128 v[148:151], v152 offset:2048
	ds_read_b128 v[152:155], v152 offset:3072
	ds_read_b128 v[156:159], v168
	ds_read_b128 v[160:163], v168 offset:1024
	ds_read_b128 v[164:167], v168 offset:2048
	ds_read_b128 v[168:171], v168 offset:3072
	s_add_i32 s82, s83, 0x2000
	s_add_i32 s87, 0, 0x18000
	s_add_i32 s86, 0, 0x1c000
	s_add_u32 s50, s52, 0x40000
	s_addc_u32 s51, s53, 0
	s_add_i32 s43, s87, s64
	s_add_i32 s13, s43, 0x2000
	s_add_u32 s48, s54, 0x80080
	s_addc_u32 s49, s55, 0
	s_add_i32 s20, s86, s64
	s_add_i32 s78, s20, 0x2000
	v_lshl_add_u64 v[204:205], s[58:59], 0, v[130:131]
	ds_read_b128 v[172:175], v143
	ds_read_b128 v[176:179], v143 offset:1024
	ds_read_b128 v[180:183], v143 offset:2048
	ds_read_b128 v[184:187], v143 offset:3072
	ds_read_b128 v[188:191], v143 offset:4096
	ds_read_b128 v[192:195], v143 offset:5120
	ds_read_b128 v[196:199], v143 offset:6144
	ds_read_b128 v[200:203], v143 offset:7168
	global_load_lds_dwordx4 v[204:205], off
	v_lshl_add_u64 v[204:205], s[58:59], 0, v[132:133]
	s_mov_b32 m0, s21
	s_nop 0
	global_load_lds_dwordx4 v[204:205], off
	s_waitcnt vmcnt(8)
	s_waitcnt lgkmcnt(0)
	s_barrier
	s_waitcnt lgkmcnt(0)
	v_mfma_f32_16x16x32_bf16 v[126:129], v[136:139], v[172:175], v[126:129]
	v_mfma_f32_16x16x32_bf16 v[122:125], v[148:151], v[172:175], v[122:125]
	v_mfma_f32_16x16x32_bf16 v[114:117], v[136:139], v[180:183], v[114:117]
	v_mfma_f32_16x16x32_bf16 v[106:109], v[148:151], v[180:183], v[106:109]
	v_mfma_f32_16x16x32_bf16 v[98:101], v[136:139], v[188:191], v[98:101]
	v_mfma_f32_16x16x32_bf16 v[90:93], v[148:151], v[188:191], v[90:93]
	v_mfma_f32_16x16x32_bf16 v[82:85], v[136:139], v[196:199], v[82:85]
	v_mfma_f32_16x16x32_bf16 v[74:77], v[148:151], v[196:199], v[74:77]
	v_mfma_f32_16x16x32_bf16 v[126:129], v[144:147], v[176:179], v[126:129]
	v_mfma_f32_16x16x32_bf16 v[122:125], v[152:155], v[176:179], v[122:125]
	v_mfma_f32_16x16x32_bf16 v[114:117], v[144:147], v[184:187], v[114:117]
	v_mfma_f32_16x16x32_bf16 v[106:109], v[152:155], v[184:187], v[106:109]
	v_mfma_f32_16x16x32_bf16 v[98:101], v[144:147], v[192:195], v[98:101]
	v_mfma_f32_16x16x32_bf16 v[90:93], v[152:155], v[192:195], v[90:93]
	v_mfma_f32_16x16x32_bf16 v[82:85], v[144:147], v[200:203], v[82:85]
	v_mfma_f32_16x16x32_bf16 v[74:77], v[152:155], v[200:203], v[74:77]
	v_mfma_f32_16x16x32_bf16 v[118:121], v[156:159], v[172:175], v[118:121]
	v_mfma_f32_16x16x32_bf16 v[110:113], v[164:167], v[172:175], v[110:113]
	v_mfma_f32_16x16x32_bf16 v[102:105], v[156:159], v[180:183], v[102:105]
	v_mfma_f32_16x16x32_bf16 v[94:97], v[164:167], v[180:183], v[94:97]
	v_mfma_f32_16x16x32_bf16 v[86:89], v[156:159], v[188:191], v[86:89]
	v_mfma_f32_16x16x32_bf16 v[78:81], v[164:167], v[188:191], v[78:81]
	v_mfma_f32_16x16x32_bf16 v[70:73], v[156:159], v[196:199], v[70:73]
	v_mfma_f32_16x16x32_bf16 v[66:69], v[164:167], v[196:199], v[66:69]
	v_mfma_f32_16x16x32_bf16 v[118:121], v[160:163], v[176:179], v[118:121]
	v_mfma_f32_16x16x32_bf16 v[110:113], v[168:171], v[176:179], v[110:113]
	v_mfma_f32_16x16x32_bf16 v[102:105], v[160:163], v[184:187], v[102:105]
	v_mfma_f32_16x16x32_bf16 v[94:97], v[168:171], v[184:187], v[94:97]
	v_mfma_f32_16x16x32_bf16 v[86:89], v[160:163], v[192:195], v[86:89]
	v_mfma_f32_16x16x32_bf16 v[78:81], v[168:171], v[192:195], v[78:81]
	v_mfma_f32_16x16x32_bf16 v[70:73], v[160:163], v[200:203], v[70:73]
	v_mfma_f32_16x16x32_bf16 v[66:69], v[168:171], v[200:203], v[66:69]
	s_barrier
	s_mov_b32 m0, s77
	v_lshl_add_u64 v[204:205], s[54:55], 0, v[0:1]
	ds_read_b128 v[172:175], v143 offset:16384
	ds_read_b128 v[176:179], v143 offset:17408
	ds_read_b128 v[180:183], v143 offset:18432
	ds_read_b128 v[184:187], v143 offset:19456
	ds_read_b128 v[188:191], v143 offset:20480
	ds_read_b128 v[192:195], v143 offset:21504
	ds_read_b128 v[196:199], v143 offset:22528
	ds_read_b128 v[200:203], v143 offset:23552
	global_load_lds_dwordx4 v[204:205], off
	v_lshl_add_u64 v[206:207], s[54:55], 0, v[134:135]
	s_mov_b32 m0, s37
	v_lshl_add_u64 v[208:209], s[56:57], 0, v[0:1]
	global_load_lds_dwordx4 v[206:207], off
	s_mov_b32 m0, s83
	v_lshl_add_u64 v[210:211], s[52:53], 0, v[132:133]
	global_load_lds_dwordx4 v[208:209], off
	v_lshl_add_u64 v[208:209], s[56:57], 0, v[134:135]
	s_mov_b32 m0, s82
	s_nop 0
	global_load_lds_dwordx4 v[208:209], off
	v_lshl_add_u64 v[208:209], s[52:53], 0, v[130:131]
	s_mov_b32 m0, s65
	s_nop 0
	global_load_lds_dwordx4 v[208:209], off
	s_mov_b32 m0, s66
	s_nop 0
	global_load_lds_dwordx4 v[210:211], off
	s_waitcnt vmcnt(8)
	s_waitcnt lgkmcnt(0)
	s_barrier
	s_waitcnt lgkmcnt(0)
	v_mfma_f32_16x16x32_bf16 v[62:65], v[136:139], v[172:175], v[62:65]
	v_mfma_f32_16x16x32_bf16 v[58:61], v[148:151], v[172:175], v[58:61]
	v_mfma_f32_16x16x32_bf16 v[50:53], v[136:139], v[180:183], v[50:53]
	v_mfma_f32_16x16x32_bf16 v[42:45], v[148:151], v[180:183], v[42:45]
	v_mfma_f32_16x16x32_bf16 v[34:37], v[136:139], v[188:191], v[34:37]
	v_mfma_f32_16x16x32_bf16 v[26:29], v[148:151], v[188:191], v[26:29]
	v_mfma_f32_16x16x32_bf16 v[18:21], v[136:139], v[196:199], v[18:21]
	v_mfma_f32_16x16x32_bf16 v[10:13], v[148:151], v[196:199], v[10:13]
	v_mfma_f32_16x16x32_bf16 v[62:65], v[144:147], v[176:179], v[62:65]
	v_mfma_f32_16x16x32_bf16 v[58:61], v[152:155], v[176:179], v[58:61]
	v_mfma_f32_16x16x32_bf16 v[50:53], v[144:147], v[184:187], v[50:53]
	v_mfma_f32_16x16x32_bf16 v[42:45], v[152:155], v[184:187], v[42:45]
	v_mfma_f32_16x16x32_bf16 v[34:37], v[144:147], v[192:195], v[34:37]
	v_mfma_f32_16x16x32_bf16 v[26:29], v[152:155], v[192:195], v[26:29]
	v_mfma_f32_16x16x32_bf16 v[18:21], v[144:147], v[200:203], v[18:21]
	v_mfma_f32_16x16x32_bf16 v[10:13], v[152:155], v[200:203], v[10:13]
	v_mfma_f32_16x16x32_bf16 v[54:57], v[156:159], v[172:175], v[54:57]
	v_mfma_f32_16x16x32_bf16 v[46:49], v[164:167], v[172:175], v[46:49]
	v_mfma_f32_16x16x32_bf16 v[38:41], v[156:159], v[180:183], v[38:41]
	v_mfma_f32_16x16x32_bf16 v[30:33], v[164:167], v[180:183], v[30:33]
	v_mfma_f32_16x16x32_bf16 v[22:25], v[156:159], v[188:191], v[22:25]
	v_mfma_f32_16x16x32_bf16 v[14:17], v[164:167], v[188:191], v[14:17]
	v_mfma_f32_16x16x32_bf16 v[6:9], v[156:159], v[196:199], v[6:9]
	v_mfma_f32_16x16x32_bf16 v[2:5], v[164:167], v[196:199], v[2:5]
	v_mfma_f32_16x16x32_bf16 v[54:57], v[160:163], v[176:179], v[54:57]
	v_mfma_f32_16x16x32_bf16 v[46:49], v[168:171], v[176:179], v[46:49]
	v_mfma_f32_16x16x32_bf16 v[38:41], v[160:163], v[184:187], v[38:41]
	v_mfma_f32_16x16x32_bf16 v[30:33], v[168:171], v[184:187], v[30:33]
	v_mfma_f32_16x16x32_bf16 v[22:25], v[160:163], v[192:195], v[22:25]
	v_mfma_f32_16x16x32_bf16 v[14:17], v[168:171], v[192:195], v[14:17]
	v_mfma_f32_16x16x32_bf16 v[6:9], v[160:163], v[200:203], v[6:9]
	v_mfma_f32_16x16x32_bf16 v[2:5], v[168:171], v[200:203], v[2:5]
	s_barrier
	v_add_u32_e32 v152, s87, v141
	v_add_u32_e32 v168, s86, v141
	ds_read_b128 v[136:139], v152
	ds_read_b128 v[144:147], v152 offset:1024
	ds_read_b128 v[148:151], v152 offset:2048
	ds_read_b128 v[152:155], v152 offset:3072
	ds_read_b128 v[156:159], v168
	ds_read_b128 v[160:163], v168 offset:1024
	ds_read_b128 v[164:167], v168 offset:2048
	ds_read_b128 v[168:171], v168 offset:3072
	s_mov_b32 m0, s67
	v_lshl_add_u64 v[214:215], s[50:51], 0, v[130:131]
	ds_read_b128 v[172:175], v143 offset:32768
	ds_read_b128 v[176:179], v143 offset:33792
	ds_read_b128 v[180:183], v143 offset:34816
	ds_read_b128 v[184:187], v143 offset:35840
	ds_read_b128 v[188:191], v143 offset:36864
	ds_read_b128 v[192:195], v143 offset:37888
	ds_read_b128 v[196:199], v143 offset:38912
	ds_read_b128 v[200:203], v143 offset:39936
	global_load_lds_dwordx4 v[214:215], off
	v_lshl_add_u64 v[214:215], s[50:51], 0, v[132:133]
	s_mov_b32 m0, s68
	s_nop 0
	global_load_lds_dwordx4 v[214:215], off
	s_waitcnt vmcnt(8)
	s_waitcnt lgkmcnt(0)
	s_barrier
	s_waitcnt lgkmcnt(0)
	v_mfma_f32_16x16x32_bf16 v[126:129], v[136:139], v[172:175], v[126:129]
	v_mfma_f32_16x16x32_bf16 v[122:125], v[148:151], v[172:175], v[122:125]
	v_mfma_f32_16x16x32_bf16 v[114:117], v[136:139], v[180:183], v[114:117]
	v_mfma_f32_16x16x32_bf16 v[106:109], v[148:151], v[180:183], v[106:109]
	v_mfma_f32_16x16x32_bf16 v[98:101], v[136:139], v[188:191], v[98:101]
	v_mfma_f32_16x16x32_bf16 v[90:93], v[148:151], v[188:191], v[90:93]
	v_mfma_f32_16x16x32_bf16 v[82:85], v[136:139], v[196:199], v[82:85]
	v_mfma_f32_16x16x32_bf16 v[74:77], v[148:151], v[196:199], v[74:77]
	v_mfma_f32_16x16x32_bf16 v[126:129], v[144:147], v[176:179], v[126:129]
	v_mfma_f32_16x16x32_bf16 v[122:125], v[152:155], v[176:179], v[122:125]
	v_mfma_f32_16x16x32_bf16 v[114:117], v[144:147], v[184:187], v[114:117]
	v_mfma_f32_16x16x32_bf16 v[106:109], v[152:155], v[184:187], v[106:109]
	v_mfma_f32_16x16x32_bf16 v[98:101], v[144:147], v[192:195], v[98:101]
	v_mfma_f32_16x16x32_bf16 v[90:93], v[152:155], v[192:195], v[90:93]
	v_mfma_f32_16x16x32_bf16 v[82:85], v[144:147], v[200:203], v[82:85]
	v_mfma_f32_16x16x32_bf16 v[74:77], v[152:155], v[200:203], v[74:77]
	v_mfma_f32_16x16x32_bf16 v[118:121], v[156:159], v[172:175], v[118:121]
	v_mfma_f32_16x16x32_bf16 v[110:113], v[164:167], v[172:175], v[110:113]
	v_mfma_f32_16x16x32_bf16 v[102:105], v[156:159], v[180:183], v[102:105]
	v_mfma_f32_16x16x32_bf16 v[94:97], v[164:167], v[180:183], v[94:97]
	v_mfma_f32_16x16x32_bf16 v[86:89], v[156:159], v[188:191], v[86:89]
	v_mfma_f32_16x16x32_bf16 v[78:81], v[164:167], v[188:191], v[78:81]
	v_mfma_f32_16x16x32_bf16 v[70:73], v[156:159], v[196:199], v[70:73]
	v_mfma_f32_16x16x32_bf16 v[66:69], v[164:167], v[196:199], v[66:69]
	v_mfma_f32_16x16x32_bf16 v[118:121], v[160:163], v[176:179], v[118:121]
	v_mfma_f32_16x16x32_bf16 v[110:113], v[168:171], v[176:179], v[110:113]
	v_mfma_f32_16x16x32_bf16 v[102:105], v[160:163], v[184:187], v[102:105]
	v_mfma_f32_16x16x32_bf16 v[94:97], v[168:171], v[184:187], v[94:97]
	v_mfma_f32_16x16x32_bf16 v[86:89], v[160:163], v[192:195], v[86:89]
	v_mfma_f32_16x16x32_bf16 v[78:81], v[168:171], v[192:195], v[78:81]
	v_mfma_f32_16x16x32_bf16 v[70:73], v[160:163], v[200:203], v[70:73]
	v_mfma_f32_16x16x32_bf16 v[66:69], v[168:171], v[200:203], v[66:69]
	s_barrier
	s_mov_b32 m0, s43
	v_lshl_add_u64 v[204:205], v[204:205], 0, s[24:25]
	ds_read_b128 v[172:175], v143 offset:49152
	ds_read_b128 v[176:179], v143 offset:50176
	ds_read_b128 v[180:183], v143 offset:51200
	ds_read_b128 v[184:187], v143 offset:52224
	ds_read_b128 v[188:191], v143 offset:53248
	ds_read_b128 v[192:195], v143 offset:54272
	ds_read_b128 v[196:199], v143 offset:55296
	ds_read_b128 v[200:203], v143 offset:56320
	global_load_lds_dwordx4 v[204:205], off
	v_lshl_add_u64 v[204:205], v[206:207], 0, s[24:25]
	s_mov_b32 m0, s13
	s_nop 0
	global_load_lds_dwordx4 v[204:205], off
	v_lshl_add_u64 v[204:205], s[48:49], 0, v[0:1]
	s_mov_b32 m0, s20
	s_nop 0
	global_load_lds_dwordx4 v[204:205], off
	v_lshl_add_u64 v[204:205], s[48:49], 0, v[134:135]
	s_mov_b32 m0, s78
	s_nop 0
	global_load_lds_dwordx4 v[204:205], off
	v_lshl_add_u64 v[204:205], v[208:209], 0, s[24:25]
	s_mov_b32 m0, s69
	s_nop 0
	global_load_lds_dwordx4 v[204:205], off
	v_lshl_add_u64 v[204:205], v[210:211], 0, s[24:25]
	s_mov_b32 m0, s70
	s_nop 0
	global_load_lds_dwordx4 v[204:205], off
	s_waitcnt vmcnt(8)
	s_waitcnt lgkmcnt(0)
	s_barrier
	s_waitcnt lgkmcnt(0)
	v_mfma_f32_16x16x32_bf16 v[62:65], v[136:139], v[172:175], v[62:65]
	v_mfma_f32_16x16x32_bf16 v[58:61], v[148:151], v[172:175], v[58:61]
	v_mfma_f32_16x16x32_bf16 v[50:53], v[136:139], v[180:183], v[50:53]
	v_mfma_f32_16x16x32_bf16 v[42:45], v[148:151], v[180:183], v[42:45]
	v_mfma_f32_16x16x32_bf16 v[34:37], v[136:139], v[188:191], v[34:37]
	v_mfma_f32_16x16x32_bf16 v[26:29], v[148:151], v[188:191], v[26:29]
	v_mfma_f32_16x16x32_bf16 v[18:21], v[136:139], v[196:199], v[18:21]
	v_mfma_f32_16x16x32_bf16 v[10:13], v[148:151], v[196:199], v[10:13]
	v_mfma_f32_16x16x32_bf16 v[62:65], v[144:147], v[176:179], v[62:65]
	v_mfma_f32_16x16x32_bf16 v[58:61], v[152:155], v[176:179], v[58:61]
	v_mfma_f32_16x16x32_bf16 v[50:53], v[144:147], v[184:187], v[50:53]
	v_mfma_f32_16x16x32_bf16 v[42:45], v[152:155], v[184:187], v[42:45]
	v_mfma_f32_16x16x32_bf16 v[34:37], v[144:147], v[192:195], v[34:37]
	v_mfma_f32_16x16x32_bf16 v[26:29], v[152:155], v[192:195], v[26:29]
	v_mfma_f32_16x16x32_bf16 v[18:21], v[144:147], v[200:203], v[18:21]
	v_mfma_f32_16x16x32_bf16 v[10:13], v[152:155], v[200:203], v[10:13]
	v_mfma_f32_16x16x32_bf16 v[54:57], v[156:159], v[172:175], v[54:57]
	v_mfma_f32_16x16x32_bf16 v[46:49], v[164:167], v[172:175], v[46:49]
	v_mfma_f32_16x16x32_bf16 v[38:41], v[156:159], v[180:183], v[38:41]
	v_mfma_f32_16x16x32_bf16 v[30:33], v[164:167], v[180:183], v[30:33]
	v_mfma_f32_16x16x32_bf16 v[22:25], v[156:159], v[188:191], v[22:25]
	v_mfma_f32_16x16x32_bf16 v[14:17], v[164:167], v[188:191], v[14:17]
	v_mfma_f32_16x16x32_bf16 v[6:9], v[156:159], v[196:199], v[6:9]
	v_mfma_f32_16x16x32_bf16 v[2:5], v[164:167], v[196:199], v[2:5]
	v_mfma_f32_16x16x32_bf16 v[54:57], v[160:163], v[176:179], v[54:57]
	v_mfma_f32_16x16x32_bf16 v[46:49], v[168:171], v[176:179], v[46:49]
	v_mfma_f32_16x16x32_bf16 v[38:41], v[160:163], v[184:187], v[38:41]
	v_mfma_f32_16x16x32_bf16 v[30:33], v[168:171], v[184:187], v[30:33]
	v_mfma_f32_16x16x32_bf16 v[22:25], v[160:163], v[192:195], v[22:25]
	v_mfma_f32_16x16x32_bf16 v[14:17], v[168:171], v[192:195], v[14:17]
	v_mfma_f32_16x16x32_bf16 v[6:9], v[160:163], v[200:203], v[6:9]
	v_mfma_f32_16x16x32_bf16 v[2:5], v[168:171], v[200:203], v[2:5]
	s_barrier
	s_movk_i32 s13, 0x100
	s_andn2_b64 vcc, exec, s[4:5]
	s_mov_b64 s[48:49], -1
	s_mov_b64 s[4:5], 0
	s_cbranch_vccz .LBB0_2034
	s_and_b64 vcc, exec, s[10:11]
	s_cbranch_vccz .LBB0_2037
	s_barrier

.LBB0_2148:
	s_add_u32 s6, s4, 0xfffc0080
	s_addc_u32 s7, s5, -1
	s_add_i32 s20, 0, 0x10000
	s_cmp_eq_u32 s72, 12
	s_cselect_b32 s51, s43, s7
	s_cselect_b32 s50, s42, s6
	s_cselect_b32 s7, s45, s47
	s_cselect_b32 s6, s44, s19
	s_add_i32 s37, 0, 0x14000
	v_add_u32_e32 v152, s20, v174
	v_add_u32_e32 v168, s37, v174
	ds_read_b128 v[140:143], v152
	ds_read_b128 v[144:147], v152 offset:1024
	ds_read_b128 v[148:151], v152 offset:2048
	ds_read_b128 v[152:155], v152 offset:3072
	ds_read_b128 v[156:159], v168
	ds_read_b128 v[160:163], v168 offset:1024
	ds_read_b128 v[164:167], v168 offset:2048
	ds_read_b128 v[168:171], v168 offset:3072
	v_lshl_add_u64 v[208:209], s[4:5], 0, v[136:137]
	s_add_i32 m0, s49, 0xc000
	ds_read_b128 v[176:179], v175
	ds_read_b128 v[180:183], v175 offset:1024
	ds_read_b128 v[184:187], v175 offset:2048
	ds_read_b128 v[188:191], v175 offset:3072
	ds_read_b128 v[192:195], v175 offset:4096
	ds_read_b128 v[196:199], v175 offset:5120
	ds_read_b128 v[200:203], v175 offset:6144
	ds_read_b128 v[204:207], v175 offset:7168
	global_load_lds_dwordx4 v[208:209], off
	v_lshl_add_u64 v[208:209], s[4:5], 0, v[138:139]
	s_add_i32 m0, s49, 0xe000
	s_nop 0
	global_load_lds_dwordx4 v[208:209], off
	s_waitcnt vmcnt(8)
	s_waitcnt lgkmcnt(0)
	s_barrier
	s_waitcnt lgkmcnt(0)
	v_mfma_f32_16x16x32_bf16 v[126:129], v[140:143], v[176:179], v[126:129]
	v_mfma_f32_16x16x32_bf16 v[122:125], v[148:151], v[176:179], v[122:125]
	v_mfma_f32_16x16x32_bf16 v[110:113], v[140:143], v[184:187], v[110:113]
	v_mfma_f32_16x16x32_bf16 v[106:109], v[148:151], v[184:187], v[106:109]
	v_mfma_f32_16x16x32_bf16 v[94:97], v[140:143], v[192:195], v[94:97]
	v_mfma_f32_16x16x32_bf16 v[90:93], v[148:151], v[192:195], v[90:93]
	v_mfma_f32_16x16x32_bf16 v[78:81], v[140:143], v[200:203], v[78:81]
	v_mfma_f32_16x16x32_bf16 v[74:77], v[148:151], v[200:203], v[74:77]
	v_mfma_f32_16x16x32_bf16 v[126:129], v[144:147], v[180:183], v[126:129]
	v_mfma_f32_16x16x32_bf16 v[122:125], v[152:155], v[180:183], v[122:125]
	v_mfma_f32_16x16x32_bf16 v[110:113], v[144:147], v[188:191], v[110:113]
	v_mfma_f32_16x16x32_bf16 v[106:109], v[152:155], v[188:191], v[106:109]
	v_mfma_f32_16x16x32_bf16 v[94:97], v[144:147], v[196:199], v[94:97]
	v_mfma_f32_16x16x32_bf16 v[90:93], v[152:155], v[196:199], v[90:93]
	v_mfma_f32_16x16x32_bf16 v[78:81], v[144:147], v[204:207], v[78:81]
	v_mfma_f32_16x16x32_bf16 v[74:77], v[152:155], v[204:207], v[74:77]
	v_mfma_f32_16x16x32_bf16 v[118:121], v[156:159], v[176:179], v[118:121]
	v_mfma_f32_16x16x32_bf16 v[114:117], v[164:167], v[176:179], v[114:117]
	v_mfma_f32_16x16x32_bf16 v[102:105], v[156:159], v[184:187], v[102:105]
	v_mfma_f32_16x16x32_bf16 v[98:101], v[164:167], v[184:187], v[98:101]
	v_mfma_f32_16x16x32_bf16 v[86:89], v[156:159], v[192:195], v[86:89]
	v_mfma_f32_16x16x32_bf16 v[82:85], v[164:167], v[192:195], v[82:85]
	v_mfma_f32_16x16x32_bf16 v[70:73], v[156:159], v[200:203], v[70:73]
	v_mfma_f32_16x16x32_bf16 v[66:69], v[164:167], v[200:203], v[66:69]
	v_mfma_f32_16x16x32_bf16 v[118:121], v[160:163], v[180:183], v[118:121]
	v_mfma_f32_16x16x32_bf16 v[114:117], v[168:171], v[180:183], v[114:117]
	v_mfma_f32_16x16x32_bf16 v[102:105], v[160:163], v[188:191], v[102:105]
	v_mfma_f32_16x16x32_bf16 v[98:101], v[168:171], v[188:191], v[98:101]
	v_mfma_f32_16x16x32_bf16 v[86:89], v[160:163], v[196:199], v[86:89]
	v_mfma_f32_16x16x32_bf16 v[82:85], v[168:171], v[196:199], v[82:85]
	v_mfma_f32_16x16x32_bf16 v[70:73], v[160:163], v[204:207], v[70:73]
	v_mfma_f32_16x16x32_bf16 v[66:69], v[168:171], v[204:207], v[66:69]
	s_barrier
	s_add_i32 s20, s20, s54
	v_lshl_add_u64 v[208:209], s[6:7], 0, v[0:1]
	s_mov_b32 m0, s20
	ds_read_b128 v[176:179], v175 offset:16384
	ds_read_b128 v[180:183], v175 offset:17408
	ds_read_b128 v[184:187], v175 offset:18432
	ds_read_b128 v[188:191], v175 offset:19456
	ds_read_b128 v[192:195], v175 offset:20480
	ds_read_b128 v[196:199], v175 offset:21504
	ds_read_b128 v[200:203], v175 offset:22528
	ds_read_b128 v[204:207], v175 offset:23552
	global_load_lds_dwordx4 v[208:209], off
	s_add_i32 m0, s20, 0x2000
	s_add_u32 s20, s6, 0x40000
	v_lshl_add_u64 v[210:211], s[6:7], 0, v[134:135]
	s_addc_u32 s21, s7, 0
	s_add_i32 s37, s37, s54
	global_load_lds_dwordx4 v[210:211], off
	v_lshl_add_u64 v[214:215], s[20:21], 0, v[0:1]
	s_mov_b32 m0, s37
	v_lshl_add_u64 v[216:217], s[50:51], 0, v[132:133]
	global_load_lds_dwordx4 v[214:215], off
	v_lshl_add_u64 v[214:215], s[20:21], 0, v[134:135]
	s_add_i32 m0, s37, 0x2000
	s_nop 0
	global_load_lds_dwordx4 v[214:215], off
	v_lshl_add_u64 v[214:215], s[50:51], 0, v[130:131]
	s_mov_b32 m0, s49
	s_nop 0
	global_load_lds_dwordx4 v[214:215], off
	s_mov_b32 m0, s55
	s_nop 0
	global_load_lds_dwordx4 v[216:217], off
	s_waitcnt vmcnt(8)
	s_waitcnt lgkmcnt(0)
	s_barrier
	s_waitcnt lgkmcnt(0)
	v_mfma_f32_16x16x32_bf16 v[62:65], v[140:143], v[176:179], v[62:65]
	v_mfma_f32_16x16x32_bf16 v[58:61], v[148:151], v[176:179], v[58:61]
	v_mfma_f32_16x16x32_bf16 v[46:49], v[140:143], v[184:187], v[46:49]
	v_mfma_f32_16x16x32_bf16 v[42:45], v[148:151], v[184:187], v[42:45]
	v_mfma_f32_16x16x32_bf16 v[30:33], v[140:143], v[192:195], v[30:33]
	v_mfma_f32_16x16x32_bf16 v[26:29], v[148:151], v[192:195], v[26:29]
	v_mfma_f32_16x16x32_bf16 v[14:17], v[140:143], v[200:203], v[14:17]
	v_mfma_f32_16x16x32_bf16 v[10:13], v[148:151], v[200:203], v[10:13]
	v_mfma_f32_16x16x32_bf16 v[62:65], v[144:147], v[180:183], v[62:65]
	v_mfma_f32_16x16x32_bf16 v[58:61], v[152:155], v[180:183], v[58:61]
	v_mfma_f32_16x16x32_bf16 v[46:49], v[144:147], v[188:191], v[46:49]
	v_mfma_f32_16x16x32_bf16 v[42:45], v[152:155], v[188:191], v[42:45]
	v_mfma_f32_16x16x32_bf16 v[30:33], v[144:147], v[196:199], v[30:33]
	v_mfma_f32_16x16x32_bf16 v[26:29], v[152:155], v[196:199], v[26:29]
	v_mfma_f32_16x16x32_bf16 v[14:17], v[144:147], v[204:207], v[14:17]
	v_mfma_f32_16x16x32_bf16 v[10:13], v[152:155], v[204:207], v[10:13]
	v_mfma_f32_16x16x32_bf16 v[54:57], v[156:159], v[176:179], v[54:57]
	v_mfma_f32_16x16x32_bf16 v[50:53], v[164:167], v[176:179], v[50:53]
	v_mfma_f32_16x16x32_bf16 v[38:41], v[156:159], v[184:187], v[38:41]
	v_mfma_f32_16x16x32_bf16 v[34:37], v[164:167], v[184:187], v[34:37]
	v_mfma_f32_16x16x32_bf16 v[22:25], v[156:159], v[192:195], v[22:25]
	v_mfma_f32_16x16x32_bf16 v[18:21], v[164:167], v[192:195], v[18:21]
	v_mfma_f32_16x16x32_bf16 v[6:9], v[156:159], v[200:203], v[6:9]
	v_mfma_f32_16x16x32_bf16 v[2:5], v[164:167], v[200:203], v[2:5]
	v_mfma_f32_16x16x32_bf16 v[54:57], v[160:163], v[180:183], v[54:57]
	v_mfma_f32_16x16x32_bf16 v[50:53], v[168:171], v[180:183], v[50:53]
	v_mfma_f32_16x16x32_bf16 v[38:41], v[160:163], v[188:191], v[38:41]
	v_mfma_f32_16x16x32_bf16 v[34:37], v[168:171], v[188:191], v[34:37]
	v_mfma_f32_16x16x32_bf16 v[22:25], v[160:163], v[196:199], v[22:25]
	v_mfma_f32_16x16x32_bf16 v[18:21], v[168:171], v[196:199], v[18:21]
	v_mfma_f32_16x16x32_bf16 v[6:9], v[160:163], v[204:207], v[6:9]
	v_mfma_f32_16x16x32_bf16 v[2:5], v[168:171], v[204:207], v[2:5]
	s_barrier
	s_add_i32 s37, 0, 0x18000
	s_add_i32 s73, 0, 0x1c000
	v_add_u32_e32 v152, s37, v174
	v_add_u32_e32 v168, s73, v174
	ds_read_b128 v[140:143], v152
	ds_read_b128 v[144:147], v152 offset:1024
	ds_read_b128 v[148:151], v152 offset:2048
	ds_read_b128 v[152:155], v152 offset:3072
	ds_read_b128 v[156:159], v168
	ds_read_b128 v[160:163], v168 offset:1024
	ds_read_b128 v[164:167], v168 offset:2048
	ds_read_b128 v[168:171], v168 offset:3072
	s_add_u32 s20, s50, 0x40000
	s_addc_u32 s21, s51, 0
	s_mov_b32 m0, s56
	v_lshl_add_u64 v[218:219], s[20:21], 0, v[130:131]
	ds_read_b128 v[176:179], v175 offset:32768
	ds_read_b128 v[180:183], v175 offset:33792
	ds_read_b128 v[184:187], v175 offset:34816
	ds_read_b128 v[188:191], v175 offset:35840
	ds_read_b128 v[192:195], v175 offset:36864
	ds_read_b128 v[196:199], v175 offset:37888
	ds_read_b128 v[200:203], v175 offset:38912
	ds_read_b128 v[204:207], v175 offset:39936
	global_load_lds_dwordx4 v[218:219], off
	v_lshl_add_u64 v[218:219], s[20:21], 0, v[132:133]
	s_mov_b32 m0, s57
	s_nop 0
	global_load_lds_dwordx4 v[218:219], off
	s_waitcnt vmcnt(8)
	s_waitcnt lgkmcnt(0)
	s_barrier
	s_waitcnt lgkmcnt(0)
	v_mfma_f32_16x16x32_bf16 v[126:129], v[140:143], v[176:179], v[126:129]
	v_mfma_f32_16x16x32_bf16 v[122:125], v[148:151], v[176:179], v[122:125]
	v_mfma_f32_16x16x32_bf16 v[110:113], v[140:143], v[184:187], v[110:113]
	v_mfma_f32_16x16x32_bf16 v[106:109], v[148:151], v[184:187], v[106:109]
	v_mfma_f32_16x16x32_bf16 v[94:97], v[140:143], v[192:195], v[94:97]
	v_mfma_f32_16x16x32_bf16 v[90:93], v[148:151], v[192:195], v[90:93]
	v_mfma_f32_16x16x32_bf16 v[78:81], v[140:143], v[200:203], v[78:81]
	v_mfma_f32_16x16x32_bf16 v[74:77], v[148:151], v[200:203], v[74:77]
	v_mfma_f32_16x16x32_bf16 v[126:129], v[144:147], v[180:183], v[126:129]
	v_mfma_f32_16x16x32_bf16 v[122:125], v[152:155], v[180:183], v[122:125]
	v_mfma_f32_16x16x32_bf16 v[110:113], v[144:147], v[188:191], v[110:113]
	v_mfma_f32_16x16x32_bf16 v[106:109], v[152:155], v[188:191], v[106:109]
	v_mfma_f32_16x16x32_bf16 v[94:97], v[144:147], v[196:199], v[94:97]
	v_mfma_f32_16x16x32_bf16 v[90:93], v[152:155], v[196:199], v[90:93]
	v_mfma_f32_16x16x32_bf16 v[78:81], v[144:147], v[204:207], v[78:81]
	v_mfma_f32_16x16x32_bf16 v[74:77], v[152:155], v[204:207], v[74:77]
	v_mfma_f32_16x16x32_bf16 v[118:121], v[156:159], v[176:179], v[118:121]
	v_mfma_f32_16x16x32_bf16 v[114:117], v[164:167], v[176:179], v[114:117]
	v_mfma_f32_16x16x32_bf16 v[102:105], v[156:159], v[184:187], v[102:105]
	v_mfma_f32_16x16x32_bf16 v[98:101], v[164:167], v[184:187], v[98:101]
	v_mfma_f32_16x16x32_bf16 v[86:89], v[156:159], v[192:195], v[86:89]
	v_mfma_f32_16x16x32_bf16 v[82:85], v[164:167], v[192:195], v[82:85]
	v_mfma_f32_16x16x32_bf16 v[70:73], v[156:159], v[200:203], v[70:73]
	v_mfma_f32_16x16x32_bf16 v[66:69], v[164:167], v[200:203], v[66:69]
	v_mfma_f32_16x16x32_bf16 v[118:121], v[160:163], v[180:183], v[118:121]
	v_mfma_f32_16x16x32_bf16 v[114:117], v[168:171], v[180:183], v[114:117]
	v_mfma_f32_16x16x32_bf16 v[102:105], v[160:163], v[188:191], v[102:105]
	v_mfma_f32_16x16x32_bf16 v[98:101], v[168:171], v[188:191], v[98:101]
	v_mfma_f32_16x16x32_bf16 v[86:89], v[160:163], v[196:199], v[86:89]
	v_mfma_f32_16x16x32_bf16 v[82:85], v[168:171], v[196:199], v[82:85]
	v_mfma_f32_16x16x32_bf16 v[70:73], v[160:163], v[204:207], v[70:73]
	v_mfma_f32_16x16x32_bf16 v[66:69], v[168:171], v[204:207], v[66:69]
	s_barrier
	s_add_i32 s20, s37, s54
	v_lshl_add_u64 v[208:209], v[208:209], 0, s[24:25]
	s_mov_b32 m0, s20
	ds_read_b128 v[176:179], v175 offset:49152
	ds_read_b128 v[180:183], v175 offset:50176
	ds_read_b128 v[184:187], v175 offset:51200
	ds_read_b128 v[188:191], v175 offset:52224
	ds_read_b128 v[192:195], v175 offset:53248
	ds_read_b128 v[196:199], v175 offset:54272
	ds_read_b128 v[200:203], v175 offset:55296
	ds_read_b128 v[204:207], v175 offset:56320
	global_load_lds_dwordx4 v[208:209], off
	s_add_i32 m0, s20, 0x2000
	s_add_u32 s6, s6, 0x40080
	v_lshl_add_u64 v[208:209], v[210:211], 0, s[24:25]
	s_addc_u32 s7, s7, 0
	s_add_i32 s20, s73, s54
	global_load_lds_dwordx4 v[208:209], off
	v_lshl_add_u64 v[208:209], s[6:7], 0, v[0:1]
	s_mov_b32 m0, s20
	s_nop 0
	global_load_lds_dwordx4 v[208:209], off
	v_lshl_add_u64 v[208:209], s[6:7], 0, v[134:135]
	s_add_i32 m0, s20, 0x2000
	s_nop 0
	global_load_lds_dwordx4 v[208:209], off
	v_lshl_add_u64 v[208:209], v[214:215], 0, s[24:25]
	s_mov_b32 m0, s62
	s_nop 0
	global_load_lds_dwordx4 v[208:209], off
	v_lshl_add_u64 v[208:209], v[216:217], 0, s[24:25]
	s_mov_b32 m0, s63
	s_nop 0
	global_load_lds_dwordx4 v[208:209], off
	s_waitcnt vmcnt(8)
	s_waitcnt lgkmcnt(0)
	s_barrier
	s_waitcnt lgkmcnt(0)
	v_mfma_f32_16x16x32_bf16 v[62:65], v[140:143], v[176:179], v[62:65]
	v_mfma_f32_16x16x32_bf16 v[58:61], v[148:151], v[176:179], v[58:61]
	v_mfma_f32_16x16x32_bf16 v[46:49], v[140:143], v[184:187], v[46:49]
	v_mfma_f32_16x16x32_bf16 v[42:45], v[148:151], v[184:187], v[42:45]
	v_mfma_f32_16x16x32_bf16 v[30:33], v[140:143], v[192:195], v[30:33]
	v_mfma_f32_16x16x32_bf16 v[26:29], v[148:151], v[192:195], v[26:29]
	v_mfma_f32_16x16x32_bf16 v[14:17], v[140:143], v[200:203], v[14:17]
	v_mfma_f32_16x16x32_bf16 v[10:13], v[148:151], v[200:203], v[10:13]
	v_mfma_f32_16x16x32_bf16 v[62:65], v[144:147], v[180:183], v[62:65]
	v_mfma_f32_16x16x32_bf16 v[58:61], v[152:155], v[180:183], v[58:61]
	v_mfma_f32_16x16x32_bf16 v[46:49], v[144:147], v[188:191], v[46:49]
	v_mfma_f32_16x16x32_bf16 v[42:45], v[152:155], v[188:191], v[42:45]
	v_mfma_f32_16x16x32_bf16 v[30:33], v[144:147], v[196:199], v[30:33]
	v_mfma_f32_16x16x32_bf16 v[26:29], v[152:155], v[196:199], v[26:29]
	v_mfma_f32_16x16x32_bf16 v[14:17], v[144:147], v[204:207], v[14:17]
	v_mfma_f32_16x16x32_bf16 v[10:13], v[152:155], v[204:207], v[10:13]
	v_mfma_f32_16x16x32_bf16 v[54:57], v[156:159], v[176:179], v[54:57]
	v_mfma_f32_16x16x32_bf16 v[50:53], v[164:167], v[176:179], v[50:53]
	v_mfma_f32_16x16x32_bf16 v[38:41], v[156:159], v[184:187], v[38:41]
	v_mfma_f32_16x16x32_bf16 v[34:37], v[164:167], v[184:187], v[34:37]
	v_mfma_f32_16x16x32_bf16 v[22:25], v[156:159], v[192:195], v[22:25]
	v_mfma_f32_16x16x32_bf16 v[18:21], v[164:167], v[192:195], v[18:21]
	v_mfma_f32_16x16x32_bf16 v[6:9], v[156:159], v[200:203], v[6:9]
	v_mfma_f32_16x16x32_bf16 v[2:5], v[164:167], v[200:203], v[2:5]
	v_mfma_f32_16x16x32_bf16 v[54:57], v[160:163], v[180:183], v[54:57]
	v_mfma_f32_16x16x32_bf16 v[50:53], v[168:171], v[180:183], v[50:53]
	v_mfma_f32_16x16x32_bf16 v[38:41], v[160:163], v[188:191], v[38:41]
	v_mfma_f32_16x16x32_bf16 v[34:37], v[168:171], v[188:191], v[34:37]
	v_mfma_f32_16x16x32_bf16 v[22:25], v[160:163], v[196:199], v[22:25]
	v_mfma_f32_16x16x32_bf16 v[18:21], v[168:171], v[196:199], v[18:21]
	v_mfma_f32_16x16x32_bf16 v[6:9], v[160:163], v[204:207], v[6:9]
	v_mfma_f32_16x16x32_bf16 v[2:5], v[168:171], v[204:207], v[2:5]
	s_barrier
	s_add_i32 s72, s72, 2
	s_add_u32 s4, s4, 0x100
	s_addc_u32 s5, s5, 0
	s_add_u32 s19, s19, 0x100
	s_addc_u32 s47, s47, 0
	s_cmp_gt_u32 s72, 13
	s_cbranch_scc0 .LBB0_2148
	s_and_b64 vcc, exec, s[16:17]
	s_cbranch_vccz .LBB0_2151
	s_barrier

.LBB0_2262:
	s_add_u32 s20, s44, 0xfffc0080
	s_addc_u32 s21, s45, -1
	s_add_i32 s37, 0, 0x10000
	s_cmp_eq_u32 s69, 12
	s_cselect_b32 s49, s5, s21
	s_cselect_b32 s48, s4, s20
	s_cselect_b32 s47, s19, s43
	s_cselect_b32 s46, s18, s17
	s_add_i32 s70, 0, 0x14000
	v_add_u32_e32 v152, s37, v142
	v_add_u32_e32 v168, s70, v142
	ds_read_b128 v[136:139], v152
	ds_read_b128 v[144:147], v152 offset:1024
	ds_read_b128 v[148:151], v152 offset:2048
	ds_read_b128 v[152:155], v152 offset:3072
	ds_read_b128 v[156:159], v168
	ds_read_b128 v[160:163], v168 offset:1024
	ds_read_b128 v[164:167], v168 offset:2048
	ds_read_b128 v[168:171], v168 offset:3072
	v_lshl_add_u64 v[204:205], s[44:45], 0, v[132:133]
	s_add_i32 m0, s56, 0xc000
	ds_read_b128 v[172:175], v143
	ds_read_b128 v[176:179], v143 offset:1024
	ds_read_b128 v[180:183], v143 offset:2048
	ds_read_b128 v[184:187], v143 offset:3072
	ds_read_b128 v[188:191], v143 offset:4096
	ds_read_b128 v[192:195], v143 offset:5120
	ds_read_b128 v[196:199], v143 offset:6144
	ds_read_b128 v[200:203], v143 offset:7168
	global_load_lds_dwordx4 v[204:205], off
	v_lshl_add_u64 v[204:205], s[44:45], 0, v[134:135]
	s_add_i32 m0, s56, 0xe000
	s_nop 0
	global_load_lds_dwordx4 v[204:205], off
	s_waitcnt vmcnt(8)
	s_waitcnt lgkmcnt(0)
	s_barrier
	s_waitcnt lgkmcnt(0)
	v_mfma_f32_16x16x32_bf16 v[126:129], v[136:139], v[172:175], v[126:129]
	v_mfma_f32_16x16x32_bf16 v[122:125], v[148:151], v[172:175], v[122:125]
	v_mfma_f32_16x16x32_bf16 v[110:113], v[136:139], v[180:183], v[110:113]
	v_mfma_f32_16x16x32_bf16 v[106:109], v[148:151], v[180:183], v[106:109]
	v_mfma_f32_16x16x32_bf16 v[94:97], v[136:139], v[188:191], v[94:97]
	v_mfma_f32_16x16x32_bf16 v[90:93], v[148:151], v[188:191], v[90:93]
	v_mfma_f32_16x16x32_bf16 v[78:81], v[136:139], v[196:199], v[78:81]
	v_mfma_f32_16x16x32_bf16 v[74:77], v[148:151], v[196:199], v[74:77]
	v_mfma_f32_16x16x32_bf16 v[126:129], v[144:147], v[176:179], v[126:129]
	v_mfma_f32_16x16x32_bf16 v[122:125], v[152:155], v[176:179], v[122:125]
	v_mfma_f32_16x16x32_bf16 v[110:113], v[144:147], v[184:187], v[110:113]
	v_mfma_f32_16x16x32_bf16 v[106:109], v[152:155], v[184:187], v[106:109]
	v_mfma_f32_16x16x32_bf16 v[94:97], v[144:147], v[192:195], v[94:97]
	v_mfma_f32_16x16x32_bf16 v[90:93], v[152:155], v[192:195], v[90:93]
	v_mfma_f32_16x16x32_bf16 v[78:81], v[144:147], v[200:203], v[78:81]
	v_mfma_f32_16x16x32_bf16 v[74:77], v[152:155], v[200:203], v[74:77]
	v_mfma_f32_16x16x32_bf16 v[118:121], v[156:159], v[172:175], v[118:121]
	v_mfma_f32_16x16x32_bf16 v[114:117], v[164:167], v[172:175], v[114:117]
	v_mfma_f32_16x16x32_bf16 v[102:105], v[156:159], v[180:183], v[102:105]
	v_mfma_f32_16x16x32_bf16 v[98:101], v[164:167], v[180:183], v[98:101]
	v_mfma_f32_16x16x32_bf16 v[86:89], v[156:159], v[188:191], v[86:89]
	v_mfma_f32_16x16x32_bf16 v[82:85], v[164:167], v[188:191], v[82:85]
	v_mfma_f32_16x16x32_bf16 v[70:73], v[156:159], v[196:199], v[70:73]
	v_mfma_f32_16x16x32_bf16 v[66:69], v[164:167], v[196:199], v[66:69]
	v_mfma_f32_16x16x32_bf16 v[118:121], v[160:163], v[176:179], v[118:121]
	v_mfma_f32_16x16x32_bf16 v[114:117], v[168:171], v[176:179], v[114:117]
	v_mfma_f32_16x16x32_bf16 v[102:105], v[160:163], v[184:187], v[102:105]
	v_mfma_f32_16x16x32_bf16 v[98:101], v[168:171], v[184:187], v[98:101]
	v_mfma_f32_16x16x32_bf16 v[86:89], v[160:163], v[192:195], v[86:89]
	v_mfma_f32_16x16x32_bf16 v[82:85], v[168:171], v[192:195], v[82:85]
	v_mfma_f32_16x16x32_bf16 v[70:73], v[160:163], v[200:203], v[70:73]
	v_mfma_f32_16x16x32_bf16 v[66:69], v[168:171], v[200:203], v[66:69]
	s_barrier
	s_add_i32 s20, s37, s55
	v_lshl_add_u64 v[204:205], s[46:47], 0, v[0:1]
	s_mov_b32 m0, s20
	ds_read_b128 v[172:175], v143 offset:16384
	ds_read_b128 v[176:179], v143 offset:17408
	ds_read_b128 v[180:183], v143 offset:18432
	ds_read_b128 v[184:187], v143 offset:19456
	ds_read_b128 v[188:191], v143 offset:20480
	ds_read_b128 v[192:195], v143 offset:21504
	ds_read_b128 v[196:199], v143 offset:22528
	ds_read_b128 v[200:203], v143 offset:23552
	global_load_lds_dwordx4 v[204:205], off
	s_add_i32 m0, s20, 0x2000
	s_add_u32 s20, s46, 0x40000
	v_lshl_add_u64 v[206:207], s[46:47], 0, v[130:131]
	s_addc_u32 s21, s47, 0
	s_add_i32 s37, s70, s55
	global_load_lds_dwordx4 v[206:207], off
	v_lshl_add_u64 v[208:209], s[20:21], 0, v[0:1]
	s_mov_b32 m0, s37
	v_lshl_add_u64 v[210:211], s[48:49], 0, v[130:131]
	global_load_lds_dwordx4 v[208:209], off
	v_lshl_add_u64 v[208:209], s[20:21], 0, v[130:131]
	s_add_i32 m0, s37, 0x2000
	s_nop 0
	global_load_lds_dwordx4 v[208:209], off
	v_lshl_add_u64 v[208:209], s[48:49], 0, v[0:1]
	s_mov_b32 m0, s56
	s_nop 0
	global_load_lds_dwordx4 v[208:209], off
	s_mov_b32 m0, s57
	s_nop 0
	global_load_lds_dwordx4 v[210:211], off
	s_waitcnt vmcnt(8)
	s_waitcnt lgkmcnt(0)
	s_barrier
	s_waitcnt lgkmcnt(0)
	v_mfma_f32_16x16x32_bf16 v[62:65], v[136:139], v[172:175], v[62:65]
	v_mfma_f32_16x16x32_bf16 v[58:61], v[148:151], v[172:175], v[58:61]
	v_mfma_f32_16x16x32_bf16 v[46:49], v[136:139], v[180:183], v[46:49]
	v_mfma_f32_16x16x32_bf16 v[42:45], v[148:151], v[180:183], v[42:45]
	v_mfma_f32_16x16x32_bf16 v[30:33], v[136:139], v[188:191], v[30:33]
	v_mfma_f32_16x16x32_bf16 v[26:29], v[148:151], v[188:191], v[26:29]
	v_mfma_f32_16x16x32_bf16 v[14:17], v[136:139], v[196:199], v[14:17]
	v_mfma_f32_16x16x32_bf16 v[10:13], v[148:151], v[196:199], v[10:13]
	v_mfma_f32_16x16x32_bf16 v[62:65], v[144:147], v[176:179], v[62:65]
	v_mfma_f32_16x16x32_bf16 v[58:61], v[152:155], v[176:179], v[58:61]
	v_mfma_f32_16x16x32_bf16 v[46:49], v[144:147], v[184:187], v[46:49]
	v_mfma_f32_16x16x32_bf16 v[42:45], v[152:155], v[184:187], v[42:45]
	v_mfma_f32_16x16x32_bf16 v[30:33], v[144:147], v[192:195], v[30:33]
	v_mfma_f32_16x16x32_bf16 v[26:29], v[152:155], v[192:195], v[26:29]
	v_mfma_f32_16x16x32_bf16 v[14:17], v[144:147], v[200:203], v[14:17]
	v_mfma_f32_16x16x32_bf16 v[10:13], v[152:155], v[200:203], v[10:13]
	v_mfma_f32_16x16x32_bf16 v[54:57], v[156:159], v[172:175], v[54:57]
	v_mfma_f32_16x16x32_bf16 v[50:53], v[164:167], v[172:175], v[50:53]
	v_mfma_f32_16x16x32_bf16 v[38:41], v[156:159], v[180:183], v[38:41]
	v_mfma_f32_16x16x32_bf16 v[34:37], v[164:167], v[180:183], v[34:37]
	v_mfma_f32_16x16x32_bf16 v[22:25], v[156:159], v[188:191], v[22:25]
	v_mfma_f32_16x16x32_bf16 v[18:21], v[164:167], v[188:191], v[18:21]
	v_mfma_f32_16x16x32_bf16 v[6:9], v[156:159], v[196:199], v[6:9]
	v_mfma_f32_16x16x32_bf16 v[2:5], v[164:167], v[196:199], v[2:5]
	v_mfma_f32_16x16x32_bf16 v[54:57], v[160:163], v[176:179], v[54:57]
	v_mfma_f32_16x16x32_bf16 v[50:53], v[168:171], v[176:179], v[50:53]
	v_mfma_f32_16x16x32_bf16 v[38:41], v[160:163], v[184:187], v[38:41]
	v_mfma_f32_16x16x32_bf16 v[34:37], v[168:171], v[184:187], v[34:37]
	v_mfma_f32_16x16x32_bf16 v[22:25], v[160:163], v[192:195], v[22:25]
	v_mfma_f32_16x16x32_bf16 v[18:21], v[168:171], v[192:195], v[18:21]
	v_mfma_f32_16x16x32_bf16 v[6:9], v[160:163], v[200:203], v[6:9]
	v_mfma_f32_16x16x32_bf16 v[2:5], v[168:171], v[200:203], v[2:5]
	s_barrier
	s_add_i32 s37, 0, 0x18000
	s_add_i32 s70, 0, 0x1c000
	v_add_u32_e32 v152, s37, v142
	v_add_u32_e32 v168, s70, v142
	ds_read_b128 v[136:139], v152
	ds_read_b128 v[144:147], v152 offset:1024
	ds_read_b128 v[148:151], v152 offset:2048
	ds_read_b128 v[152:155], v152 offset:3072
	ds_read_b128 v[156:159], v168
	ds_read_b128 v[160:163], v168 offset:1024
	ds_read_b128 v[164:167], v168 offset:2048
	ds_read_b128 v[168:171], v168 offset:3072
	s_add_u32 s20, s48, 0x40000
	s_addc_u32 s21, s49, 0
	s_mov_b32 m0, s58
	v_lshl_add_u64 v[214:215], s[20:21], 0, v[0:1]
	ds_read_b128 v[172:175], v143 offset:32768
	ds_read_b128 v[176:179], v143 offset:33792
	ds_read_b128 v[180:183], v143 offset:34816
	ds_read_b128 v[184:187], v143 offset:35840
	ds_read_b128 v[188:191], v143 offset:36864
	ds_read_b128 v[192:195], v143 offset:37888
	ds_read_b128 v[196:199], v143 offset:38912
	ds_read_b128 v[200:203], v143 offset:39936
	global_load_lds_dwordx4 v[214:215], off
	v_lshl_add_u64 v[214:215], s[20:21], 0, v[130:131]
	s_mov_b32 m0, s59
	s_nop 0
	global_load_lds_dwordx4 v[214:215], off
	s_waitcnt vmcnt(8)
	s_waitcnt lgkmcnt(0)
	s_barrier
	s_waitcnt lgkmcnt(0)
	v_mfma_f32_16x16x32_bf16 v[126:129], v[136:139], v[172:175], v[126:129]
	v_mfma_f32_16x16x32_bf16 v[122:125], v[148:151], v[172:175], v[122:125]
	v_mfma_f32_16x16x32_bf16 v[110:113], v[136:139], v[180:183], v[110:113]
	v_mfma_f32_16x16x32_bf16 v[106:109], v[148:151], v[180:183], v[106:109]
	v_mfma_f32_16x16x32_bf16 v[94:97], v[136:139], v[188:191], v[94:97]
	v_mfma_f32_16x16x32_bf16 v[90:93], v[148:151], v[188:191], v[90:93]
	v_mfma_f32_16x16x32_bf16 v[78:81], v[136:139], v[196:199], v[78:81]
	v_mfma_f32_16x16x32_bf16 v[74:77], v[148:151], v[196:199], v[74:77]
	v_mfma_f32_16x16x32_bf16 v[126:129], v[144:147], v[176:179], v[126:129]
	v_mfma_f32_16x16x32_bf16 v[122:125], v[152:155], v[176:179], v[122:125]
	v_mfma_f32_16x16x32_bf16 v[110:113], v[144:147], v[184:187], v[110:113]
	v_mfma_f32_16x16x32_bf16 v[106:109], v[152:155], v[184:187], v[106:109]
	v_mfma_f32_16x16x32_bf16 v[94:97], v[144:147], v[192:195], v[94:97]
	v_mfma_f32_16x16x32_bf16 v[90:93], v[152:155], v[192:195], v[90:93]
	v_mfma_f32_16x16x32_bf16 v[78:81], v[144:147], v[200:203], v[78:81]
	v_mfma_f32_16x16x32_bf16 v[74:77], v[152:155], v[200:203], v[74:77]
	v_mfma_f32_16x16x32_bf16 v[118:121], v[156:159], v[172:175], v[118:121]
	v_mfma_f32_16x16x32_bf16 v[114:117], v[164:167], v[172:175], v[114:117]
	v_mfma_f32_16x16x32_bf16 v[102:105], v[156:159], v[180:183], v[102:105]
	v_mfma_f32_16x16x32_bf16 v[98:101], v[164:167], v[180:183], v[98:101]
	v_mfma_f32_16x16x32_bf16 v[86:89], v[156:159], v[188:191], v[86:89]
	v_mfma_f32_16x16x32_bf16 v[82:85], v[164:167], v[188:191], v[82:85]
	v_mfma_f32_16x16x32_bf16 v[70:73], v[156:159], v[196:199], v[70:73]
	v_mfma_f32_16x16x32_bf16 v[66:69], v[164:167], v[196:199], v[66:69]
	v_mfma_f32_16x16x32_bf16 v[118:121], v[160:163], v[176:179], v[118:121]
	v_mfma_f32_16x16x32_bf16 v[114:117], v[168:171], v[176:179], v[114:117]
	v_mfma_f32_16x16x32_bf16 v[102:105], v[160:163], v[184:187], v[102:105]
	v_mfma_f32_16x16x32_bf16 v[98:101], v[168:171], v[184:187], v[98:101]
	v_mfma_f32_16x16x32_bf16 v[86:89], v[160:163], v[192:195], v[86:89]
	v_mfma_f32_16x16x32_bf16 v[82:85], v[168:171], v[192:195], v[82:85]
	v_mfma_f32_16x16x32_bf16 v[70:73], v[160:163], v[200:203], v[70:73]
	v_mfma_f32_16x16x32_bf16 v[66:69], v[168:171], v[200:203], v[66:69]
	s_barrier
	s_add_i32 s20, s37, s55
	v_lshl_add_u64 v[204:205], v[204:205], 0, s[24:25]
	s_mov_b32 m0, s20
	ds_read_b128 v[172:175], v143 offset:49152
	ds_read_b128 v[176:179], v143 offset:50176
	ds_read_b128 v[180:183], v143 offset:51200
	ds_read_b128 v[184:187], v143 offset:52224
	ds_read_b128 v[188:191], v143 offset:53248
	ds_read_b128 v[192:195], v143 offset:54272
	ds_read_b128 v[196:199], v143 offset:55296
	ds_read_b128 v[200:203], v143 offset:56320
	global_load_lds_dwordx4 v[204:205], off
	s_add_i32 m0, s20, 0x2000
	s_add_u32 s20, s46, 0x40080
	v_lshl_add_u64 v[204:205], v[206:207], 0, s[24:25]
	s_addc_u32 s21, s47, 0
	s_add_i32 s37, s70, s55
	global_load_lds_dwordx4 v[204:205], off
	v_lshl_add_u64 v[204:205], s[20:21], 0, v[0:1]
	s_mov_b32 m0, s37
	s_nop 0
	global_load_lds_dwordx4 v[204:205], off
	v_lshl_add_u64 v[204:205], s[20:21], 0, v[130:131]
	s_add_i32 m0, s37, 0x2000
	s_nop 0
	global_load_lds_dwordx4 v[204:205], off
	v_lshl_add_u64 v[204:205], v[208:209], 0, s[24:25]
	s_mov_b32 m0, s63
	s_nop 0
	global_load_lds_dwordx4 v[204:205], off
	v_lshl_add_u64 v[204:205], v[210:211], 0, s[24:25]
	s_mov_b32 m0, s64
	s_nop 0
	global_load_lds_dwordx4 v[204:205], off
	s_waitcnt vmcnt(8)
	s_waitcnt lgkmcnt(0)
	s_barrier
	s_waitcnt lgkmcnt(0)
	v_mfma_f32_16x16x32_bf16 v[62:65], v[136:139], v[172:175], v[62:65]
	v_mfma_f32_16x16x32_bf16 v[58:61], v[148:151], v[172:175], v[58:61]
	v_mfma_f32_16x16x32_bf16 v[46:49], v[136:139], v[180:183], v[46:49]
	v_mfma_f32_16x16x32_bf16 v[42:45], v[148:151], v[180:183], v[42:45]
	v_mfma_f32_16x16x32_bf16 v[30:33], v[136:139], v[188:191], v[30:33]
	v_mfma_f32_16x16x32_bf16 v[26:29], v[148:151], v[188:191], v[26:29]
	v_mfma_f32_16x16x32_bf16 v[14:17], v[136:139], v[196:199], v[14:17]
	v_mfma_f32_16x16x32_bf16 v[10:13], v[148:151], v[196:199], v[10:13]
	v_mfma_f32_16x16x32_bf16 v[62:65], v[144:147], v[176:179], v[62:65]
	v_mfma_f32_16x16x32_bf16 v[58:61], v[152:155], v[176:179], v[58:61]
	v_mfma_f32_16x16x32_bf16 v[46:49], v[144:147], v[184:187], v[46:49]
	v_mfma_f32_16x16x32_bf16 v[42:45], v[152:155], v[184:187], v[42:45]
	v_mfma_f32_16x16x32_bf16 v[30:33], v[144:147], v[192:195], v[30:33]
	v_mfma_f32_16x16x32_bf16 v[26:29], v[152:155], v[192:195], v[26:29]
	v_mfma_f32_16x16x32_bf16 v[14:17], v[144:147], v[200:203], v[14:17]
	v_mfma_f32_16x16x32_bf16 v[10:13], v[152:155], v[200:203], v[10:13]
	v_mfma_f32_16x16x32_bf16 v[54:57], v[156:159], v[172:175], v[54:57]
	v_mfma_f32_16x16x32_bf16 v[50:53], v[164:167], v[172:175], v[50:53]
	v_mfma_f32_16x16x32_bf16 v[38:41], v[156:159], v[180:183], v[38:41]
	v_mfma_f32_16x16x32_bf16 v[34:37], v[164:167], v[180:183], v[34:37]
	v_mfma_f32_16x16x32_bf16 v[22:25], v[156:159], v[188:191], v[22:25]
	v_mfma_f32_16x16x32_bf16 v[18:21], v[164:167], v[188:191], v[18:21]
	v_mfma_f32_16x16x32_bf16 v[6:9], v[156:159], v[196:199], v[6:9]
	v_mfma_f32_16x16x32_bf16 v[2:5], v[164:167], v[196:199], v[2:5]
	v_mfma_f32_16x16x32_bf16 v[54:57], v[160:163], v[176:179], v[54:57]
	v_mfma_f32_16x16x32_bf16 v[50:53], v[168:171], v[176:179], v[50:53]
	v_mfma_f32_16x16x32_bf16 v[38:41], v[160:163], v[184:187], v[38:41]
	v_mfma_f32_16x16x32_bf16 v[34:37], v[168:171], v[184:187], v[34:37]
	v_mfma_f32_16x16x32_bf16 v[22:25], v[160:163], v[192:195], v[22:25]
	v_mfma_f32_16x16x32_bf16 v[18:21], v[168:171], v[192:195], v[18:21]
	v_mfma_f32_16x16x32_bf16 v[6:9], v[160:163], v[200:203], v[6:9]
	v_mfma_f32_16x16x32_bf16 v[2:5], v[168:171], v[200:203], v[2:5]
	s_barrier
	s_add_i32 s69, s69, 2
	s_add_u32 s44, s44, 0x100
	s_addc_u32 s45, s45, 0
	s_add_u32 s17, s17, 0x100
	s_addc_u32 s43, s43, 0
	s_cmp_gt_u32 s69, 13
	s_cbranch_scc0 .LBB0_2262
	s_and_b64 vcc, exec, s[12:13]
	s_cbranch_vccz .LBB0_2265
	s_barrier

.LBB0_2428:
	s_add_u32 s8, s4, 0xfffc0080
	s_addc_u32 s9, s5, -1
	s_add_i32 s20, 0, 0x10000
	s_cmp_eq_u32 s70, 12
	s_cselect_b32 s53, s49, s9
	s_cselect_b32 s52, s48, s8
	v_add_u32_e32 v144, s20, v147
	s_cselect_b32 s9, s7, s69
	s_cselect_b32 s8, s47, s68
	s_add_i32 s37, 0, 0x14000
	ds_read_b128 v[140:143], v144
	ds_read_b128 v[150:153], v144 offset:1024
	ds_read_b128 v[154:157], v144 offset:2048
	ds_read_b128 v[158:161], v144 offset:3072
	v_add_u32_e32 v144, s37, v147
	ds_read_b128 v[162:165], v144
	ds_read_b128 v[166:169], v144 offset:1024
	ds_read_b128 v[170:173], v144 offset:2048
	ds_read_b128 v[174:177], v144 offset:3072
	v_lshl_add_u64 v[144:145], s[4:5], 0, v[136:137]
	s_add_i32 m0, s57, 0xc000
	ds_read_b128 v[178:181], v149
	ds_read_b128 v[182:185], v149 offset:1024
	ds_read_b128 v[186:189], v149 offset:2048
	ds_read_b128 v[190:193], v149 offset:3072
	ds_read_b128 v[194:197], v149 offset:4096
	ds_read_b128 v[198:201], v149 offset:5120
	ds_read_b128 v[202:205], v149 offset:6144
	ds_read_b128 v[206:209], v149 offset:7168
	global_load_lds_dwordx4 v[144:145], off
	v_lshl_add_u64 v[144:145], s[4:5], 0, v[138:139]
	s_add_i32 m0, s57, 0xe000
	s_nop 0
	global_load_lds_dwordx4 v[144:145], off
	s_waitcnt vmcnt(8)
	s_waitcnt lgkmcnt(0)
	s_barrier
	s_waitcnt lgkmcnt(0)
	v_mfma_f32_16x16x32_bf16 v[126:129], v[140:143], v[178:181], v[126:129]
	v_mfma_f32_16x16x32_bf16 v[122:125], v[154:157], v[178:181], v[122:125]
	v_mfma_f32_16x16x32_bf16 v[110:113], v[140:143], v[186:189], v[110:113]
	v_mfma_f32_16x16x32_bf16 v[106:109], v[154:157], v[186:189], v[106:109]
	v_mfma_f32_16x16x32_bf16 v[94:97], v[140:143], v[194:197], v[94:97]
	v_mfma_f32_16x16x32_bf16 v[90:93], v[154:157], v[194:197], v[90:93]
	v_mfma_f32_16x16x32_bf16 v[78:81], v[140:143], v[202:205], v[78:81]
	v_mfma_f32_16x16x32_bf16 v[74:77], v[154:157], v[202:205], v[74:77]
	v_mfma_f32_16x16x32_bf16 v[126:129], v[150:153], v[182:185], v[126:129]
	v_mfma_f32_16x16x32_bf16 v[122:125], v[158:161], v[182:185], v[122:125]
	v_mfma_f32_16x16x32_bf16 v[110:113], v[150:153], v[190:193], v[110:113]
	v_mfma_f32_16x16x32_bf16 v[106:109], v[158:161], v[190:193], v[106:109]
	v_mfma_f32_16x16x32_bf16 v[94:97], v[150:153], v[198:201], v[94:97]
	v_mfma_f32_16x16x32_bf16 v[90:93], v[158:161], v[198:201], v[90:93]
	v_mfma_f32_16x16x32_bf16 v[78:81], v[150:153], v[206:209], v[78:81]
	v_mfma_f32_16x16x32_bf16 v[74:77], v[158:161], v[206:209], v[74:77]
	v_mfma_f32_16x16x32_bf16 v[118:121], v[162:165], v[178:181], v[118:121]
	v_mfma_f32_16x16x32_bf16 v[114:117], v[170:173], v[178:181], v[114:117]
	v_mfma_f32_16x16x32_bf16 v[102:105], v[162:165], v[186:189], v[102:105]
	v_mfma_f32_16x16x32_bf16 v[98:101], v[170:173], v[186:189], v[98:101]
	v_mfma_f32_16x16x32_bf16 v[86:89], v[162:165], v[194:197], v[86:89]
	v_mfma_f32_16x16x32_bf16 v[82:85], v[170:173], v[194:197], v[82:85]
	v_mfma_f32_16x16x32_bf16 v[70:73], v[162:165], v[202:205], v[70:73]
	v_mfma_f32_16x16x32_bf16 v[66:69], v[170:173], v[202:205], v[66:69]
	v_mfma_f32_16x16x32_bf16 v[118:121], v[166:169], v[182:185], v[118:121]
	v_mfma_f32_16x16x32_bf16 v[114:117], v[174:177], v[182:185], v[114:117]
	v_mfma_f32_16x16x32_bf16 v[102:105], v[166:169], v[190:193], v[102:105]
	v_mfma_f32_16x16x32_bf16 v[98:101], v[174:177], v[190:193], v[98:101]
	v_mfma_f32_16x16x32_bf16 v[86:89], v[166:169], v[198:201], v[86:89]
	v_mfma_f32_16x16x32_bf16 v[82:85], v[174:177], v[198:201], v[82:85]
	v_mfma_f32_16x16x32_bf16 v[70:73], v[166:169], v[206:209], v[70:73]
	v_mfma_f32_16x16x32_bf16 v[66:69], v[174:177], v[206:209], v[66:69]
	s_barrier
	s_add_i32 s20, s20, s56
	v_lshl_add_u64 v[144:145], s[8:9], 0, v[0:1]
	s_mov_b32 m0, s20
	ds_read_b128 v[178:181], v149 offset:16384
	ds_read_b128 v[182:185], v149 offset:17408
	ds_read_b128 v[186:189], v149 offset:18432
	ds_read_b128 v[190:193], v149 offset:19456
	ds_read_b128 v[194:197], v149 offset:20480
	ds_read_b128 v[198:201], v149 offset:21504
	ds_read_b128 v[202:205], v149 offset:22528
	ds_read_b128 v[206:209], v149 offset:23552
	global_load_lds_dwordx4 v[144:145], off
	s_add_i32 m0, s20, 0x2000
	s_add_u32 s20, s8, 0x40000
	v_lshl_add_u64 v[210:211], s[8:9], 0, v[134:135]
	s_addc_u32 s21, s9, 0
	s_add_i32 s37, s37, s56
	global_load_lds_dwordx4 v[210:211], off
	v_lshl_add_u64 v[214:215], s[20:21], 0, v[0:1]
	s_mov_b32 m0, s37
	v_lshl_add_u64 v[216:217], s[52:53], 0, v[132:133]
	global_load_lds_dwordx4 v[214:215], off
	v_lshl_add_u64 v[214:215], s[20:21], 0, v[134:135]
	s_add_i32 m0, s37, 0x2000
	s_nop 0
	global_load_lds_dwordx4 v[214:215], off
	v_lshl_add_u64 v[214:215], s[52:53], 0, v[130:131]
	s_mov_b32 m0, s57
	s_nop 0
	global_load_lds_dwordx4 v[214:215], off
	s_mov_b32 m0, s58
	s_nop 0
	global_load_lds_dwordx4 v[216:217], off
	s_waitcnt vmcnt(8)
	s_waitcnt lgkmcnt(0)
	s_barrier
	s_waitcnt lgkmcnt(0)
	v_mfma_f32_16x16x32_bf16 v[62:65], v[140:143], v[178:181], v[62:65]
	v_mfma_f32_16x16x32_bf16 v[58:61], v[154:157], v[178:181], v[58:61]
	v_mfma_f32_16x16x32_bf16 v[46:49], v[140:143], v[186:189], v[46:49]
	v_mfma_f32_16x16x32_bf16 v[42:45], v[154:157], v[186:189], v[42:45]
	v_mfma_f32_16x16x32_bf16 v[30:33], v[140:143], v[194:197], v[30:33]
	v_mfma_f32_16x16x32_bf16 v[26:29], v[154:157], v[194:197], v[26:29]
	v_mfma_f32_16x16x32_bf16 v[14:17], v[140:143], v[202:205], v[14:17]
	v_mfma_f32_16x16x32_bf16 v[10:13], v[154:157], v[202:205], v[10:13]
	v_mfma_f32_16x16x32_bf16 v[62:65], v[150:153], v[182:185], v[62:65]
	v_mfma_f32_16x16x32_bf16 v[58:61], v[158:161], v[182:185], v[58:61]
	v_mfma_f32_16x16x32_bf16 v[46:49], v[150:153], v[190:193], v[46:49]
	v_mfma_f32_16x16x32_bf16 v[42:45], v[158:161], v[190:193], v[42:45]
	v_mfma_f32_16x16x32_bf16 v[30:33], v[150:153], v[198:201], v[30:33]
	v_mfma_f32_16x16x32_bf16 v[26:29], v[158:161], v[198:201], v[26:29]
	v_mfma_f32_16x16x32_bf16 v[14:17], v[150:153], v[206:209], v[14:17]
	v_mfma_f32_16x16x32_bf16 v[10:13], v[158:161], v[206:209], v[10:13]
	v_mfma_f32_16x16x32_bf16 v[54:57], v[162:165], v[178:181], v[54:57]
	v_mfma_f32_16x16x32_bf16 v[50:53], v[170:173], v[178:181], v[50:53]
	v_mfma_f32_16x16x32_bf16 v[38:41], v[162:165], v[186:189], v[38:41]
	v_mfma_f32_16x16x32_bf16 v[34:37], v[170:173], v[186:189], v[34:37]
	v_mfma_f32_16x16x32_bf16 v[22:25], v[162:165], v[194:197], v[22:25]
	v_mfma_f32_16x16x32_bf16 v[18:21], v[170:173], v[194:197], v[18:21]
	v_mfma_f32_16x16x32_bf16 v[6:9], v[162:165], v[202:205], v[6:9]
	v_mfma_f32_16x16x32_bf16 v[2:5], v[170:173], v[202:205], v[2:5]
	v_mfma_f32_16x16x32_bf16 v[54:57], v[166:169], v[182:185], v[54:57]
	v_mfma_f32_16x16x32_bf16 v[50:53], v[174:177], v[182:185], v[50:53]
	v_mfma_f32_16x16x32_bf16 v[38:41], v[166:169], v[190:193], v[38:41]
	v_mfma_f32_16x16x32_bf16 v[34:37], v[174:177], v[190:193], v[34:37]
	v_mfma_f32_16x16x32_bf16 v[22:25], v[166:169], v[198:201], v[22:25]
	v_mfma_f32_16x16x32_bf16 v[18:21], v[174:177], v[198:201], v[18:21]
	v_mfma_f32_16x16x32_bf16 v[6:9], v[166:169], v[206:209], v[6:9]
	v_mfma_f32_16x16x32_bf16 v[2:5], v[174:177], v[206:209], v[2:5]
	s_barrier
	s_add_i32 s37, 0, 0x18000
	s_add_i32 s71, 0, 0x1c000
	v_add_u32_e32 v158, s37, v147
	v_add_u32_e32 v174, s71, v147
	ds_read_b128 v[140:143], v158
	ds_read_b128 v[150:153], v158 offset:1024
	ds_read_b128 v[154:157], v158 offset:2048
	ds_read_b128 v[158:161], v158 offset:3072
	ds_read_b128 v[162:165], v174
	ds_read_b128 v[166:169], v174 offset:1024
	ds_read_b128 v[170:173], v174 offset:2048
	ds_read_b128 v[174:177], v174 offset:3072
	s_add_u32 s20, s52, 0x40000
	s_addc_u32 s21, s53, 0
	s_mov_b32 m0, s59
	v_lshl_add_u64 v[218:219], s[20:21], 0, v[130:131]
	ds_read_b128 v[178:181], v149 offset:32768
	ds_read_b128 v[182:185], v149 offset:33792
	ds_read_b128 v[186:189], v149 offset:34816
	ds_read_b128 v[190:193], v149 offset:35840
	ds_read_b128 v[194:197], v149 offset:36864
	ds_read_b128 v[198:201], v149 offset:37888
	ds_read_b128 v[202:205], v149 offset:38912
	ds_read_b128 v[206:209], v149 offset:39936
	global_load_lds_dwordx4 v[218:219], off
	v_lshl_add_u64 v[218:219], s[20:21], 0, v[132:133]
	s_mov_b32 m0, s60
	s_nop 0
	global_load_lds_dwordx4 v[218:219], off
	s_waitcnt vmcnt(8)
	s_waitcnt lgkmcnt(0)
	s_barrier
	s_waitcnt lgkmcnt(0)
	v_mfma_f32_16x16x32_bf16 v[126:129], v[140:143], v[178:181], v[126:129]
	v_mfma_f32_16x16x32_bf16 v[122:125], v[154:157], v[178:181], v[122:125]
	v_mfma_f32_16x16x32_bf16 v[110:113], v[140:143], v[186:189], v[110:113]
	v_mfma_f32_16x16x32_bf16 v[106:109], v[154:157], v[186:189], v[106:109]
	v_mfma_f32_16x16x32_bf16 v[94:97], v[140:143], v[194:197], v[94:97]
	v_mfma_f32_16x16x32_bf16 v[90:93], v[154:157], v[194:197], v[90:93]
	v_mfma_f32_16x16x32_bf16 v[78:81], v[140:143], v[202:205], v[78:81]
	v_mfma_f32_16x16x32_bf16 v[74:77], v[154:157], v[202:205], v[74:77]
	v_mfma_f32_16x16x32_bf16 v[126:129], v[150:153], v[182:185], v[126:129]
	v_mfma_f32_16x16x32_bf16 v[122:125], v[158:161], v[182:185], v[122:125]
	v_mfma_f32_16x16x32_bf16 v[110:113], v[150:153], v[190:193], v[110:113]
	v_mfma_f32_16x16x32_bf16 v[106:109], v[158:161], v[190:193], v[106:109]
	v_mfma_f32_16x16x32_bf16 v[94:97], v[150:153], v[198:201], v[94:97]
	v_mfma_f32_16x16x32_bf16 v[90:93], v[158:161], v[198:201], v[90:93]
	v_mfma_f32_16x16x32_bf16 v[78:81], v[150:153], v[206:209], v[78:81]
	v_mfma_f32_16x16x32_bf16 v[74:77], v[158:161], v[206:209], v[74:77]
	v_mfma_f32_16x16x32_bf16 v[118:121], v[162:165], v[178:181], v[118:121]
	v_mfma_f32_16x16x32_bf16 v[114:117], v[170:173], v[178:181], v[114:117]
	v_mfma_f32_16x16x32_bf16 v[102:105], v[162:165], v[186:189], v[102:105]
	v_mfma_f32_16x16x32_bf16 v[98:101], v[170:173], v[186:189], v[98:101]
	v_mfma_f32_16x16x32_bf16 v[86:89], v[162:165], v[194:197], v[86:89]
	v_mfma_f32_16x16x32_bf16 v[82:85], v[170:173], v[194:197], v[82:85]
	v_mfma_f32_16x16x32_bf16 v[70:73], v[162:165], v[202:205], v[70:73]
	v_mfma_f32_16x16x32_bf16 v[66:69], v[170:173], v[202:205], v[66:69]
	v_mfma_f32_16x16x32_bf16 v[118:121], v[166:169], v[182:185], v[118:121]
	v_mfma_f32_16x16x32_bf16 v[114:117], v[174:177], v[182:185], v[114:117]
	v_mfma_f32_16x16x32_bf16 v[102:105], v[166:169], v[190:193], v[102:105]
	v_mfma_f32_16x16x32_bf16 v[98:101], v[174:177], v[190:193], v[98:101]
	v_mfma_f32_16x16x32_bf16 v[86:89], v[166:169], v[198:201], v[86:89]
	v_mfma_f32_16x16x32_bf16 v[82:85], v[174:177], v[198:201], v[82:85]
	v_mfma_f32_16x16x32_bf16 v[70:73], v[166:169], v[206:209], v[70:73]
	v_mfma_f32_16x16x32_bf16 v[66:69], v[174:177], v[206:209], v[66:69]
	s_barrier
	s_add_i32 s20, s37, s56
	v_lshl_add_u64 v[144:145], v[144:145], 0, s[24:25]
	s_mov_b32 m0, s20
	ds_read_b128 v[178:181], v149 offset:49152
	ds_read_b128 v[182:185], v149 offset:50176
	ds_read_b128 v[186:189], v149 offset:51200
	ds_read_b128 v[190:193], v149 offset:52224
	ds_read_b128 v[194:197], v149 offset:53248
	ds_read_b128 v[198:201], v149 offset:54272
	ds_read_b128 v[202:205], v149 offset:55296
	ds_read_b128 v[206:209], v149 offset:56320
	global_load_lds_dwordx4 v[144:145], off
	s_add_i32 m0, s20, 0x2000
	s_add_u32 s8, s8, 0x40080
	v_lshl_add_u64 v[144:145], v[210:211], 0, s[24:25]
	s_addc_u32 s9, s9, 0
	s_add_i32 s20, s71, s56
	global_load_lds_dwordx4 v[144:145], off
	v_lshl_add_u64 v[144:145], s[8:9], 0, v[0:1]
	s_mov_b32 m0, s20
	s_nop 0
	global_load_lds_dwordx4 v[144:145], off
	v_lshl_add_u64 v[144:145], s[8:9], 0, v[134:135]
	s_add_i32 m0, s20, 0x2000
	s_nop 0
	global_load_lds_dwordx4 v[144:145], off
	v_lshl_add_u64 v[144:145], v[214:215], 0, s[24:25]
	s_mov_b32 m0, s61
	s_nop 0
	global_load_lds_dwordx4 v[144:145], off
	v_lshl_add_u64 v[144:145], v[216:217], 0, s[24:25]
	s_mov_b32 m0, s62
	s_nop 0
	global_load_lds_dwordx4 v[144:145], off
	s_waitcnt vmcnt(8)
	s_waitcnt lgkmcnt(0)
	s_barrier
	s_waitcnt lgkmcnt(0)
	v_mfma_f32_16x16x32_bf16 v[62:65], v[140:143], v[178:181], v[62:65]
	v_mfma_f32_16x16x32_bf16 v[58:61], v[154:157], v[178:181], v[58:61]
	v_mfma_f32_16x16x32_bf16 v[46:49], v[140:143], v[186:189], v[46:49]
	v_mfma_f32_16x16x32_bf16 v[42:45], v[154:157], v[186:189], v[42:45]
	v_mfma_f32_16x16x32_bf16 v[30:33], v[140:143], v[194:197], v[30:33]
	v_mfma_f32_16x16x32_bf16 v[26:29], v[154:157], v[194:197], v[26:29]
	v_mfma_f32_16x16x32_bf16 v[14:17], v[140:143], v[202:205], v[14:17]
	v_mfma_f32_16x16x32_bf16 v[10:13], v[154:157], v[202:205], v[10:13]
	v_mfma_f32_16x16x32_bf16 v[62:65], v[150:153], v[182:185], v[62:65]
	v_mfma_f32_16x16x32_bf16 v[58:61], v[158:161], v[182:185], v[58:61]
	v_mfma_f32_16x16x32_bf16 v[46:49], v[150:153], v[190:193], v[46:49]
	v_mfma_f32_16x16x32_bf16 v[42:45], v[158:161], v[190:193], v[42:45]
	v_mfma_f32_16x16x32_bf16 v[30:33], v[150:153], v[198:201], v[30:33]
	v_mfma_f32_16x16x32_bf16 v[26:29], v[158:161], v[198:201], v[26:29]
	v_mfma_f32_16x16x32_bf16 v[14:17], v[150:153], v[206:209], v[14:17]
	v_mfma_f32_16x16x32_bf16 v[10:13], v[158:161], v[206:209], v[10:13]
	v_mfma_f32_16x16x32_bf16 v[54:57], v[162:165], v[178:181], v[54:57]
	v_mfma_f32_16x16x32_bf16 v[50:53], v[170:173], v[178:181], v[50:53]
	v_mfma_f32_16x16x32_bf16 v[38:41], v[162:165], v[186:189], v[38:41]
	v_mfma_f32_16x16x32_bf16 v[34:37], v[170:173], v[186:189], v[34:37]
	v_mfma_f32_16x16x32_bf16 v[22:25], v[162:165], v[194:197], v[22:25]
	v_mfma_f32_16x16x32_bf16 v[18:21], v[170:173], v[194:197], v[18:21]
	v_mfma_f32_16x16x32_bf16 v[6:9], v[162:165], v[202:205], v[6:9]
	v_mfma_f32_16x16x32_bf16 v[2:5], v[170:173], v[202:205], v[2:5]
	v_mfma_f32_16x16x32_bf16 v[54:57], v[166:169], v[182:185], v[54:57]
	v_mfma_f32_16x16x32_bf16 v[50:53], v[174:177], v[182:185], v[50:53]
	v_mfma_f32_16x16x32_bf16 v[38:41], v[166:169], v[190:193], v[38:41]
	v_mfma_f32_16x16x32_bf16 v[34:37], v[174:177], v[190:193], v[34:37]
	v_mfma_f32_16x16x32_bf16 v[22:25], v[166:169], v[198:201], v[22:25]
	v_mfma_f32_16x16x32_bf16 v[18:21], v[174:177], v[198:201], v[18:21]
	v_mfma_f32_16x16x32_bf16 v[6:9], v[166:169], v[206:209], v[6:9]
	v_mfma_f32_16x16x32_bf16 v[2:5], v[174:177], v[206:209], v[2:5]
	s_barrier
	s_add_i32 s70, s70, 2
	s_add_u32 s4, s4, 0x100
	s_addc_u32 s5, s5, 0
	s_add_u32 s68, s68, 0x100
	s_addc_u32 s69, s69, 0
	s_cmp_gt_u32 s70, 13
	s_cbranch_scc0 .LBB0_2428
	s_and_b64 vcc, exec, s[44:45]
	s_cbranch_vccz .LBB0_2431
	s_barrier

.LBB0_2540:
	s_add_u32 s20, s4, 0xfff00080
	s_addc_u32 s21, s5, -1
	s_add_i32 s37, 0, 0x10000
	s_cmp_eq_u32 s73, 60
	s_cselect_b32 s51, s43, s21
	s_cselect_b32 s50, s42, s20
	s_cselect_b32 s49, s41, s72
	s_cselect_b32 s48, s47, s71
	s_add_i32 s77, 0, 0x14000
	v_add_u32_e32 v152, s37, v142
	v_add_u32_e32 v168, s77, v142
	ds_read_b128 v[136:139], v152
	ds_read_b128 v[144:147], v152 offset:1024
	ds_read_b128 v[148:151], v152 offset:2048
	ds_read_b128 v[152:155], v152 offset:3072
	ds_read_b128 v[156:159], v168
	ds_read_b128 v[160:163], v168 offset:1024
	ds_read_b128 v[164:167], v168 offset:2048
	ds_read_b128 v[168:171], v168 offset:3072
	v_lshl_add_u64 v[204:205], s[4:5], 0, v[132:133]
	s_add_i32 m0, s58, 0xc000
	ds_read_b128 v[172:175], v143
	ds_read_b128 v[176:179], v143 offset:1024
	ds_read_b128 v[180:183], v143 offset:2048
	ds_read_b128 v[184:187], v143 offset:3072
	ds_read_b128 v[188:191], v143 offset:4096
	ds_read_b128 v[192:195], v143 offset:5120
	ds_read_b128 v[196:199], v143 offset:6144
	ds_read_b128 v[200:203], v143 offset:7168
	global_load_lds_dwordx4 v[204:205], off
	v_lshl_add_u64 v[204:205], s[4:5], 0, v[134:135]
	s_add_i32 m0, s58, 0xe000
	s_nop 0
	global_load_lds_dwordx4 v[204:205], off
	s_waitcnt vmcnt(8)
	s_waitcnt lgkmcnt(0)
	s_barrier
	s_waitcnt lgkmcnt(0)
	v_mfma_f32_16x16x32_bf16 v[126:129], v[136:139], v[172:175], v[126:129]
	v_mfma_f32_16x16x32_bf16 v[122:125], v[148:151], v[172:175], v[122:125]
	v_mfma_f32_16x16x32_bf16 v[110:113], v[136:139], v[180:183], v[110:113]
	v_mfma_f32_16x16x32_bf16 v[106:109], v[148:151], v[180:183], v[106:109]
	v_mfma_f32_16x16x32_bf16 v[94:97], v[136:139], v[188:191], v[94:97]
	v_mfma_f32_16x16x32_bf16 v[90:93], v[148:151], v[188:191], v[90:93]
	v_mfma_f32_16x16x32_bf16 v[78:81], v[136:139], v[196:199], v[78:81]
	v_mfma_f32_16x16x32_bf16 v[74:77], v[148:151], v[196:199], v[74:77]
	v_mfma_f32_16x16x32_bf16 v[126:129], v[144:147], v[176:179], v[126:129]
	v_mfma_f32_16x16x32_bf16 v[122:125], v[152:155], v[176:179], v[122:125]
	v_mfma_f32_16x16x32_bf16 v[110:113], v[144:147], v[184:187], v[110:113]
	v_mfma_f32_16x16x32_bf16 v[106:109], v[152:155], v[184:187], v[106:109]
	v_mfma_f32_16x16x32_bf16 v[94:97], v[144:147], v[192:195], v[94:97]
	v_mfma_f32_16x16x32_bf16 v[90:93], v[152:155], v[192:195], v[90:93]
	v_mfma_f32_16x16x32_bf16 v[78:81], v[144:147], v[200:203], v[78:81]
	v_mfma_f32_16x16x32_bf16 v[74:77], v[152:155], v[200:203], v[74:77]
	v_mfma_f32_16x16x32_bf16 v[118:121], v[156:159], v[172:175], v[118:121]
	v_mfma_f32_16x16x32_bf16 v[114:117], v[164:167], v[172:175], v[114:117]
	v_mfma_f32_16x16x32_bf16 v[102:105], v[156:159], v[180:183], v[102:105]
	v_mfma_f32_16x16x32_bf16 v[98:101], v[164:167], v[180:183], v[98:101]
	v_mfma_f32_16x16x32_bf16 v[86:89], v[156:159], v[188:191], v[86:89]
	v_mfma_f32_16x16x32_bf16 v[82:85], v[164:167], v[188:191], v[82:85]
	v_mfma_f32_16x16x32_bf16 v[70:73], v[156:159], v[196:199], v[70:73]
	v_mfma_f32_16x16x32_bf16 v[66:69], v[164:167], v[196:199], v[66:69]
	v_mfma_f32_16x16x32_bf16 v[118:121], v[160:163], v[176:179], v[118:121]
	v_mfma_f32_16x16x32_bf16 v[114:117], v[168:171], v[176:179], v[114:117]
	v_mfma_f32_16x16x32_bf16 v[102:105], v[160:163], v[184:187], v[102:105]
	v_mfma_f32_16x16x32_bf16 v[98:101], v[168:171], v[184:187], v[98:101]
	v_mfma_f32_16x16x32_bf16 v[86:89], v[160:163], v[192:195], v[86:89]
	v_mfma_f32_16x16x32_bf16 v[82:85], v[168:171], v[192:195], v[82:85]
	v_mfma_f32_16x16x32_bf16 v[70:73], v[160:163], v[200:203], v[70:73]
	v_mfma_f32_16x16x32_bf16 v[66:69], v[168:171], v[200:203], v[66:69]
	s_barrier
	s_add_i32 s20, s37, s57
	v_lshl_add_u64 v[204:205], s[48:49], 0, v[0:1]
	s_mov_b32 m0, s20
	ds_read_b128 v[172:175], v143 offset:16384
	ds_read_b128 v[176:179], v143 offset:17408
	ds_read_b128 v[180:183], v143 offset:18432
	ds_read_b128 v[184:187], v143 offset:19456
	ds_read_b128 v[188:191], v143 offset:20480
	ds_read_b128 v[192:195], v143 offset:21504
	ds_read_b128 v[196:199], v143 offset:22528
	ds_read_b128 v[200:203], v143 offset:23552
	global_load_lds_dwordx4 v[204:205], off
	s_add_i32 m0, s20, 0x2000
	s_add_u32 s20, s48, 0x100000
	v_lshl_add_u64 v[206:207], s[48:49], 0, v[130:131]
	s_addc_u32 s21, s49, 0
	s_add_i32 s37, s77, s57
	global_load_lds_dwordx4 v[206:207], off
	v_lshl_add_u64 v[208:209], s[20:21], 0, v[0:1]
	s_mov_b32 m0, s37
	v_lshl_add_u64 v[210:211], s[50:51], 0, v[130:131]
	global_load_lds_dwordx4 v[208:209], off
	v_lshl_add_u64 v[208:209], s[20:21], 0, v[130:131]
	s_add_i32 m0, s37, 0x2000
	s_nop 0
	global_load_lds_dwordx4 v[208:209], off
	v_lshl_add_u64 v[208:209], s[50:51], 0, v[0:1]
	s_mov_b32 m0, s58
	s_nop 0
	global_load_lds_dwordx4 v[208:209], off
	s_mov_b32 m0, s59
	s_nop 0
	global_load_lds_dwordx4 v[210:211], off
	s_waitcnt vmcnt(8)
	s_waitcnt lgkmcnt(0)
	s_barrier
	s_waitcnt lgkmcnt(0)
	v_mfma_f32_16x16x32_bf16 v[62:65], v[136:139], v[172:175], v[62:65]
	v_mfma_f32_16x16x32_bf16 v[58:61], v[148:151], v[172:175], v[58:61]
	v_mfma_f32_16x16x32_bf16 v[46:49], v[136:139], v[180:183], v[46:49]
	v_mfma_f32_16x16x32_bf16 v[42:45], v[148:151], v[180:183], v[42:45]
	v_mfma_f32_16x16x32_bf16 v[30:33], v[136:139], v[188:191], v[30:33]
	v_mfma_f32_16x16x32_bf16 v[26:29], v[148:151], v[188:191], v[26:29]
	v_mfma_f32_16x16x32_bf16 v[14:17], v[136:139], v[196:199], v[14:17]
	v_mfma_f32_16x16x32_bf16 v[10:13], v[148:151], v[196:199], v[10:13]
	v_mfma_f32_16x16x32_bf16 v[62:65], v[144:147], v[176:179], v[62:65]
	v_mfma_f32_16x16x32_bf16 v[58:61], v[152:155], v[176:179], v[58:61]
	v_mfma_f32_16x16x32_bf16 v[46:49], v[144:147], v[184:187], v[46:49]
	v_mfma_f32_16x16x32_bf16 v[42:45], v[152:155], v[184:187], v[42:45]
	v_mfma_f32_16x16x32_bf16 v[30:33], v[144:147], v[192:195], v[30:33]
	v_mfma_f32_16x16x32_bf16 v[26:29], v[152:155], v[192:195], v[26:29]
	v_mfma_f32_16x16x32_bf16 v[14:17], v[144:147], v[200:203], v[14:17]
	v_mfma_f32_16x16x32_bf16 v[10:13], v[152:155], v[200:203], v[10:13]
	v_mfma_f32_16x16x32_bf16 v[54:57], v[156:159], v[172:175], v[54:57]
	v_mfma_f32_16x16x32_bf16 v[50:53], v[164:167], v[172:175], v[50:53]
	v_mfma_f32_16x16x32_bf16 v[38:41], v[156:159], v[180:183], v[38:41]
	v_mfma_f32_16x16x32_bf16 v[34:37], v[164:167], v[180:183], v[34:37]
	v_mfma_f32_16x16x32_bf16 v[22:25], v[156:159], v[188:191], v[22:25]
	v_mfma_f32_16x16x32_bf16 v[18:21], v[164:167], v[188:191], v[18:21]
	v_mfma_f32_16x16x32_bf16 v[6:9], v[156:159], v[196:199], v[6:9]
	v_mfma_f32_16x16x32_bf16 v[2:5], v[164:167], v[196:199], v[2:5]
	v_mfma_f32_16x16x32_bf16 v[54:57], v[160:163], v[176:179], v[54:57]
	v_mfma_f32_16x16x32_bf16 v[50:53], v[168:171], v[176:179], v[50:53]
	v_mfma_f32_16x16x32_bf16 v[38:41], v[160:163], v[184:187], v[38:41]
	v_mfma_f32_16x16x32_bf16 v[34:37], v[168:171], v[184:187], v[34:37]
	v_mfma_f32_16x16x32_bf16 v[22:25], v[160:163], v[192:195], v[22:25]
	v_mfma_f32_16x16x32_bf16 v[18:21], v[168:171], v[192:195], v[18:21]
	v_mfma_f32_16x16x32_bf16 v[6:9], v[160:163], v[200:203], v[6:9]
	v_mfma_f32_16x16x32_bf16 v[2:5], v[168:171], v[200:203], v[2:5]
	s_barrier
	s_add_i32 s37, 0, 0x18000
	s_add_i32 s77, 0, 0x1c000
	v_add_u32_e32 v152, s37, v142
	v_add_u32_e32 v168, s77, v142
	ds_read_b128 v[136:139], v152
	ds_read_b128 v[144:147], v152 offset:1024
	ds_read_b128 v[148:151], v152 offset:2048
	ds_read_b128 v[152:155], v152 offset:3072
	ds_read_b128 v[156:159], v168
	ds_read_b128 v[160:163], v168 offset:1024
	ds_read_b128 v[164:167], v168 offset:2048
	ds_read_b128 v[168:171], v168 offset:3072
	s_add_u32 s20, s50, 0x100000
	s_addc_u32 s21, s51, 0
	s_mov_b32 m0, s60
	v_lshl_add_u64 v[214:215], s[20:21], 0, v[0:1]
	ds_read_b128 v[172:175], v143 offset:32768
	ds_read_b128 v[176:179], v143 offset:33792
	ds_read_b128 v[180:183], v143 offset:34816
	ds_read_b128 v[184:187], v143 offset:35840
	ds_read_b128 v[188:191], v143 offset:36864
	ds_read_b128 v[192:195], v143 offset:37888
	ds_read_b128 v[196:199], v143 offset:38912
	ds_read_b128 v[200:203], v143 offset:39936
	global_load_lds_dwordx4 v[214:215], off
	v_lshl_add_u64 v[214:215], s[20:21], 0, v[130:131]
	s_mov_b32 m0, s61
	s_nop 0
	global_load_lds_dwordx4 v[214:215], off
	s_waitcnt vmcnt(8)
	s_waitcnt lgkmcnt(0)
	s_barrier
	s_waitcnt lgkmcnt(0)
	v_mfma_f32_16x16x32_bf16 v[126:129], v[136:139], v[172:175], v[126:129]
	v_mfma_f32_16x16x32_bf16 v[122:125], v[148:151], v[172:175], v[122:125]
	v_mfma_f32_16x16x32_bf16 v[110:113], v[136:139], v[180:183], v[110:113]
	v_mfma_f32_16x16x32_bf16 v[106:109], v[148:151], v[180:183], v[106:109]
	v_mfma_f32_16x16x32_bf16 v[94:97], v[136:139], v[188:191], v[94:97]
	v_mfma_f32_16x16x32_bf16 v[90:93], v[148:151], v[188:191], v[90:93]
	v_mfma_f32_16x16x32_bf16 v[78:81], v[136:139], v[196:199], v[78:81]
	v_mfma_f32_16x16x32_bf16 v[74:77], v[148:151], v[196:199], v[74:77]
	v_mfma_f32_16x16x32_bf16 v[126:129], v[144:147], v[176:179], v[126:129]
	v_mfma_f32_16x16x32_bf16 v[122:125], v[152:155], v[176:179], v[122:125]
	v_mfma_f32_16x16x32_bf16 v[110:113], v[144:147], v[184:187], v[110:113]
	v_mfma_f32_16x16x32_bf16 v[106:109], v[152:155], v[184:187], v[106:109]
	v_mfma_f32_16x16x32_bf16 v[94:97], v[144:147], v[192:195], v[94:97]
	v_mfma_f32_16x16x32_bf16 v[90:93], v[152:155], v[192:195], v[90:93]
	v_mfma_f32_16x16x32_bf16 v[78:81], v[144:147], v[200:203], v[78:81]
	v_mfma_f32_16x16x32_bf16 v[74:77], v[152:155], v[200:203], v[74:77]
	v_mfma_f32_16x16x32_bf16 v[118:121], v[156:159], v[172:175], v[118:121]
	v_mfma_f32_16x16x32_bf16 v[114:117], v[164:167], v[172:175], v[114:117]
	v_mfma_f32_16x16x32_bf16 v[102:105], v[156:159], v[180:183], v[102:105]
	v_mfma_f32_16x16x32_bf16 v[98:101], v[164:167], v[180:183], v[98:101]
	v_mfma_f32_16x16x32_bf16 v[86:89], v[156:159], v[188:191], v[86:89]
	v_mfma_f32_16x16x32_bf16 v[82:85], v[164:167], v[188:191], v[82:85]
	v_mfma_f32_16x16x32_bf16 v[70:73], v[156:159], v[196:199], v[70:73]
	v_mfma_f32_16x16x32_bf16 v[66:69], v[164:167], v[196:199], v[66:69]
	v_mfma_f32_16x16x32_bf16 v[118:121], v[160:163], v[176:179], v[118:121]
	v_mfma_f32_16x16x32_bf16 v[114:117], v[168:171], v[176:179], v[114:117]
	v_mfma_f32_16x16x32_bf16 v[102:105], v[160:163], v[184:187], v[102:105]
	v_mfma_f32_16x16x32_bf16 v[98:101], v[168:171], v[184:187], v[98:101]
	v_mfma_f32_16x16x32_bf16 v[86:89], v[160:163], v[192:195], v[86:89]
	v_mfma_f32_16x16x32_bf16 v[82:85], v[168:171], v[192:195], v[82:85]
	v_mfma_f32_16x16x32_bf16 v[70:73], v[160:163], v[200:203], v[70:73]
	v_mfma_f32_16x16x32_bf16 v[66:69], v[168:171], v[200:203], v[66:69]
	s_barrier
	s_add_i32 s20, s37, s57
	v_lshl_add_u64 v[204:205], v[204:205], 0, s[24:25]
	s_mov_b32 m0, s20
	ds_read_b128 v[172:175], v143 offset:49152
	ds_read_b128 v[176:179], v143 offset:50176
	ds_read_b128 v[180:183], v143 offset:51200
	ds_read_b128 v[184:187], v143 offset:52224
	ds_read_b128 v[188:191], v143 offset:53248
	ds_read_b128 v[192:195], v143 offset:54272
	ds_read_b128 v[196:199], v143 offset:55296
	ds_read_b128 v[200:203], v143 offset:56320
	global_load_lds_dwordx4 v[204:205], off
	s_add_i32 m0, s20, 0x2000
	s_add_u32 s20, s48, 0x100080
	v_lshl_add_u64 v[204:205], v[206:207], 0, s[24:25]
	s_addc_u32 s21, s49, 0
	s_add_i32 s37, s77, s57
	global_load_lds_dwordx4 v[204:205], off
	v_lshl_add_u64 v[204:205], s[20:21], 0, v[0:1]
	s_mov_b32 m0, s37
	s_nop 0
	global_load_lds_dwordx4 v[204:205], off
	v_lshl_add_u64 v[204:205], s[20:21], 0, v[130:131]
	s_add_i32 m0, s37, 0x2000
	s_nop 0
	global_load_lds_dwordx4 v[204:205], off
	v_lshl_add_u64 v[204:205], v[208:209], 0, s[24:25]
	s_mov_b32 m0, s65
	s_nop 0
	global_load_lds_dwordx4 v[204:205], off
	v_lshl_add_u64 v[204:205], v[210:211], 0, s[24:25]
	s_mov_b32 m0, s66
	s_nop 0
	global_load_lds_dwordx4 v[204:205], off
	s_waitcnt vmcnt(8)
	s_waitcnt lgkmcnt(0)
	s_barrier
	s_waitcnt lgkmcnt(0)
	v_mfma_f32_16x16x32_bf16 v[62:65], v[136:139], v[172:175], v[62:65]
	v_mfma_f32_16x16x32_bf16 v[58:61], v[148:151], v[172:175], v[58:61]
	v_mfma_f32_16x16x32_bf16 v[46:49], v[136:139], v[180:183], v[46:49]
	v_mfma_f32_16x16x32_bf16 v[42:45], v[148:151], v[180:183], v[42:45]
	v_mfma_f32_16x16x32_bf16 v[30:33], v[136:139], v[188:191], v[30:33]
	v_mfma_f32_16x16x32_bf16 v[26:29], v[148:151], v[188:191], v[26:29]
	v_mfma_f32_16x16x32_bf16 v[14:17], v[136:139], v[196:199], v[14:17]
	v_mfma_f32_16x16x32_bf16 v[10:13], v[148:151], v[196:199], v[10:13]
	v_mfma_f32_16x16x32_bf16 v[62:65], v[144:147], v[176:179], v[62:65]
	v_mfma_f32_16x16x32_bf16 v[58:61], v[152:155], v[176:179], v[58:61]
	v_mfma_f32_16x16x32_bf16 v[46:49], v[144:147], v[184:187], v[46:49]
	v_mfma_f32_16x16x32_bf16 v[42:45], v[152:155], v[184:187], v[42:45]
	v_mfma_f32_16x16x32_bf16 v[30:33], v[144:147], v[192:195], v[30:33]
	v_mfma_f32_16x16x32_bf16 v[26:29], v[152:155], v[192:195], v[26:29]
	v_mfma_f32_16x16x32_bf16 v[14:17], v[144:147], v[200:203], v[14:17]
	v_mfma_f32_16x16x32_bf16 v[10:13], v[152:155], v[200:203], v[10:13]
	v_mfma_f32_16x16x32_bf16 v[54:57], v[156:159], v[172:175], v[54:57]
	v_mfma_f32_16x16x32_bf16 v[50:53], v[164:167], v[172:175], v[50:53]
	v_mfma_f32_16x16x32_bf16 v[38:41], v[156:159], v[180:183], v[38:41]
	v_mfma_f32_16x16x32_bf16 v[34:37], v[164:167], v[180:183], v[34:37]
	v_mfma_f32_16x16x32_bf16 v[22:25], v[156:159], v[188:191], v[22:25]
	v_mfma_f32_16x16x32_bf16 v[18:21], v[164:167], v[188:191], v[18:21]
	v_mfma_f32_16x16x32_bf16 v[6:9], v[156:159], v[196:199], v[6:9]
	v_mfma_f32_16x16x32_bf16 v[2:5], v[164:167], v[196:199], v[2:5]
	v_mfma_f32_16x16x32_bf16 v[54:57], v[160:163], v[176:179], v[54:57]
	v_mfma_f32_16x16x32_bf16 v[50:53], v[168:171], v[176:179], v[50:53]
	v_mfma_f32_16x16x32_bf16 v[38:41], v[160:163], v[184:187], v[38:41]
	v_mfma_f32_16x16x32_bf16 v[34:37], v[168:171], v[184:187], v[34:37]
	v_mfma_f32_16x16x32_bf16 v[22:25], v[160:163], v[192:195], v[22:25]
	v_mfma_f32_16x16x32_bf16 v[18:21], v[168:171], v[192:195], v[18:21]
	v_mfma_f32_16x16x32_bf16 v[6:9], v[160:163], v[200:203], v[6:9]
	v_mfma_f32_16x16x32_bf16 v[2:5], v[168:171], v[200:203], v[2:5]
	s_barrier
	s_add_i32 s73, s73, 2
	s_add_u32 s4, s4, 0x100
	s_addc_u32 s5, s5, 0
	s_add_u32 s71, s71, 0x100
	s_addc_u32 s72, s72, 0
	s_cmp_gt_u32 s73, 61
	s_cbranch_scc0 .LBB0_2540
	s_and_b64 vcc, exec, s[18:19]
	s_cbranch_vccz .LBB0_2543
	s_barrier
